# GEMM epilogues: prefetch per-row scale / residual-base loads up front and drop the per-row vmcnt(0) ladder (P1, P8, P2); attention LDS read pipelining
# baseline (speedup 1.0000x reference)
;     __device__ __forceinline__ void operator()(const f32x4 (&acc)[2][2][4][2], const Unit& u, int wr, int wc, int fr, int fq) const {
;         const int row0 = u.pm * BM + wr * 64 + fr; const int col0 = u.pn * HALF + wc * 32 + 8 * fq;
;         f32x4 sg[2], su[2];
; #pragma unroll
;         for (int n = 0; n < 2; ++n) { sg[n] = cmg ? *(const f32x4*)(cmg + col0 + 4 * n) * cscale : (f32x4){1.f, 1.f, 1.f, 1.f}; su[n] = cmu ? *(const f32x4*)(cmu + col0 + 4 * n) * cscale : (f32x4){1.f, 1.f, 1.f, 1.f}; }
; #pragma unroll
;         for (int ai = 0; ai < 2; ++ai) { unsigned pw[4][2];
; #pragma unroll
;             for (int m = 0; m < 4; ++m) { const int row = row0 + ai * HALF + m * 16; bf16_t* rowp = O + (size_t)row * ldc + col0;
;                 const float rs = rsc ? rsc[row] : 1.f;
;                 f32x4 r[2];
; #pragma unroll
;                 for (int n = 0; n < 2; ++n) { const f32x4 g = acc[ai][0][m][n] * sg[n] * rs, up = acc[ai][1][m][n] * su[n] * rs;
; #pragma unroll
;                     for (int e = 0; e < 4; ++e) { const float sgm = __builtin_amdgcn_rcpf(1.0f + __builtin_amdgcn_exp2f(-1.4426950408889634f * g[e])); r[n][e] = g[e] * sgm * up[e]; } }
;     ...
;                         for (int n = 0; n < 2; ++n) { const i32x4 iv = __builtin_bit_cast(i32x4, acc[a][b][m][n]); acc[a][b][m][n] = (f32x4){(float)iv[0], (float)iv[1], (float)iv[2], (float)iv[3]}; } }
.LBB0_278:
	v_mbcnt_lo_u32_b32 v146, -1, 0
	v_mbcnt_hi_u32_b32 v146, -1, v146
	s_lshl_b32 s59, s90, 7
	v_lshrrev_b32_e32 v136, 1, v146
	v_and_or_b32 v136, v136, 24, s59
	v_or_b32_e32 v144, s85, v136
	v_ashrrev_i32_e32 v145, 31, v144
	v_lshlrev_b64 v[136:137], 2, v[144:145]
	s_lshl_b32 s59, s68, 8
	v_lshl_add_u64 v[138:139], s[22:23], 0, v[136:137]
	v_lshl_add_u64 v[136:137], s[36:37], 0, v[136:137]
	s_add_i32 s59, s59, s84
	global_load_dwordx4 v[140:143], v[138:139], off
	global_load_dwordx4 v[152:155], v[136:137], off
	global_load_dwordx4 v[156:159], v[138:139], off offset:16
	global_load_dwordx4 v[160:163], v[136:137], off offset:16
	v_and_or_b32 v136, v146, 15, s59
	v_ashrrev_i32_e32 v137, 31, v136
	v_lshl_add_u64 v[146:147], v[136:137], 2, s[20:21]
	global_load_dword v164, v[146:147], off
	global_load_dword v240, v[146:147], off offset:64
	global_load_dword v241, v[146:147], off offset:128
	global_load_dword v242, v[146:147], off offset:192
	global_load_dword v243, v[146:147], off offset:512
	global_load_dword v244, v[146:147], off offset:576
	global_load_dword v245, v[146:147], off offset:640
	global_load_dword v246, v[146:147], off offset:704
	v_cvt_f32_i32_e32 v167, v124
	v_cvt_f32_i32_e32 v166, v120
	v_cvt_f32_i32_e32 v171, v126
	v_cvt_f32_i32_e32 v170, v122
	v_cvt_f32_i32_e32 v169, v125
	v_cvt_f32_i32_e32 v168, v121
	v_mov_b64_e32 v[138:139], s[14:15]
	v_cvt_f32_i32_e32 v175, v116
	v_cvt_f32_i32_e32 v177, v117
	v_cvt_f32_i32_e32 v176, v113
	v_cvt_f32_i32_e32 v173, v127
	v_cvt_f32_i32_e32 v172, v123
	v_cvt_f32_i32_e32 v174, v112
	v_mad_i64_i32 v[112:113], s[70:71], v136, s89, v[138:139]
	v_lshlrev_b64 v[120:121], 1, v[144:145]
	v_lshl_add_u64 v[180:181], v[112:113], 0, v[120:121]
	v_cvt_f32_i32_e32 v179, v118
	v_cvt_f32_i32_e32 v178, v114
	v_cvt_f32_i32_e32 v119, v119
	v_cvt_f32_i32_e32 v109, v109
	v_cvt_f32_i32_e32 v111, v111
	v_cvt_f32_i32_e32 v101, v101
	v_cvt_f32_i32_e32 v103, v103
	v_cvt_f32_i32_e32 v93, v93
	v_cvt_f32_i32_e32 v95, v95
	v_cvt_f32_i32_e32 v85, v85
	v_cvt_f32_i32_e32 v87, v87
	v_cvt_f32_i32_e32 v77, v77
	v_cvt_f32_i32_e32 v79, v79
	v_cvt_f32_i32_e32 v69, v69
	v_cvt_f32_i32_e32 v71, v71
	v_cvt_f32_i32_e32 v61, v61
	v_cvt_f32_i32_e32 v53, v53
	v_cvt_f32_i32_e32 v63, v63
	v_cvt_f32_i32_e32 v55, v55
	v_cvt_f32_i32_e32 v45, v45
	v_cvt_f32_i32_e32 v37, v37
	v_cvt_f32_i32_e32 v47, v47
	v_cvt_f32_i32_e32 v39, v39
	v_cvt_f32_i32_e32 v29, v29
	v_cvt_f32_i32_e32 v31, v31
	v_cvt_f32_i32_e32 v21, v21
	v_cvt_f32_i32_e32 v23, v23
	v_cvt_f32_i32_e32 v13, v13
	v_cvt_f32_i32_e32 v15, v15
	v_cvt_f32_i32_e32 v5, v5
	v_cvt_f32_i32_e32 v7, v7
	s_andn2_b64 vcc, exec, s[66:67]
	s_waitcnt vmcnt(0)
	v_pk_mul_f32 v[112:113], v[158:159], s[56:57] op_sel_hi:[1,0]
	v_pk_mul_f32 v[116:117], v[142:143], s[56:57] op_sel_hi:[1,0]
	v_pk_mul_f32 v[124:125], v[140:141], s[56:57] op_sel_hi:[1,0]
	v_pk_mul_f32 v[142:143], v[154:155], s[56:57] op_sel_hi:[1,0]
	v_pk_mul_f32 v[140:141], v[152:153], s[56:57] op_sel_hi:[1,0]
	v_mov_b32_e32 v127, v124
	v_mov_b32_e32 v126, v140
	v_mov_b32_e32 v124, v141
	v_mov_b32_e32 v140, v142
	v_mov_b32_e32 v141, v116
	v_pk_mul_f32 v[122:123], v[156:157], s[56:57] op_sel_hi:[1,0]
	v_pk_mul_f32 v[144:145], v[160:161], s[56:57] op_sel_hi:[1,0]
	v_pk_mul_f32 v[154:155], v[126:127], v[166:167]
	v_pk_mul_f32 v[158:159], v[140:141], v[170:171]
	v_mov_b32_e32 v116, v143
	v_mov_b32_e32 v143, v122
	v_mov_b32_e32 v122, v145
	v_pk_mul_f32 v[156:157], v[124:125], v[168:169]
	v_pk_mul_f32 v[154:155], v[154:155], v[164:165] op_sel_hi:[1,0]
	v_pk_mul_f32 v[158:159], v[158:159], v[164:165] op_sel_hi:[1,0]
	v_mov_b32_e32 v142, v144
	v_mov_b32_e32 v145, v112
	v_pk_mul_f32 v[166:167], v[122:123], v[176:177]
	v_pk_mul_f32 v[156:157], v[156:157], v[164:165] op_sel_hi:[1,0]
	v_mul_f32_e32 v112, 0xbfb8aa3b, v155
	v_mul_f32_e32 v118, 0xbfb8aa3b, v159
	v_pk_mul_f32 v[152:153], v[162:163], s[56:57] op_sel_hi:[1,0]
	v_pk_mul_f32 v[160:161], v[116:117], v[172:173]
	v_pk_mul_f32 v[162:163], v[142:143], v[174:175]
	v_pk_mul_f32 v[166:167], v[164:165], v[166:167] op_sel_hi:[0,1]
	v_mul_f32_e32 v114, 0xbfb8aa3b, v157
	v_exp_f32_e32 v112, v112
	v_exp_f32_e32 v118, v118
	v_pk_mul_f32 v[160:161], v[160:161], v[164:165] op_sel_hi:[1,0]
	v_pk_mul_f32 v[162:163], v[164:165], v[162:163] op_sel_hi:[0,1]
	v_mul_f32_e32 v165, 0xbfb8aa3b, v167
	v_exp_f32_e32 v114, v114
	v_mov_b32_e32 v144, v152
	v_mul_f32_e32 v152, 0xbfb8aa3b, v163
	v_exp_f32_e32 v165, v165
	v_exp_f32_e32 v152, v152
	v_add_f32_e32 v112, 1.0, v112
	v_add_f32_e32 v118, 1.0, v118
	v_add_f32_e32 v114, 1.0, v114
	v_rcp_f32_e32 v112, v112
	v_rcp_f32_e32 v118, v118
	v_add_f32_e32 v165, 1.0, v165
	v_rcp_f32_e32 v114, v114
	v_add_f32_e32 v152, 1.0, v152
	v_rcp_f32_e32 v165, v165
	v_rcp_f32_e32 v152, v152
	v_mul_f32_e32 v112, v155, v112
	v_mul_f32_e32 v118, v159, v118
	v_mul_f32_e32 v114, v157, v114
	v_mul_f32_e32 v157, v154, v112
	v_mul_f32_e32 v158, v158, v118
	v_pk_mul_f32 v[154:155], v[144:145], v[178:179]
	v_cvt_f32_i32_e32 v118, v115
	v_pk_mul_f32 v[154:155], v[164:165], v[154:155] op_sel_hi:[0,1]
	v_mul_f32_e32 v152, v163, v152
	v_mul_f32_e32 v112, 0xbfb8aa3b, v155
	v_mul_f32_e32 v159, v162, v152
	v_exp_f32_e32 v152, v112
	v_mov_b32_e32 v112, v153
	v_mul_f32_e32 v156, v156, v114
	v_pk_mul_f32 v[114:115], v[112:113], v[118:119]
	v_mul_f32_e32 v137, 0xbfb8aa3b, v161
	v_pk_mul_f32 v[114:115], v[164:165], v[114:115] op_sel_hi:[0,1]
	v_mul_f32_e32 v118, 0xbfb8aa3b, v115
	v_exp_f32_e32 v118, v118
	v_exp_f32_e32 v137, v137
	v_add_f32_e32 v152, 1.0, v152
	v_rcp_f32_e32 v152, v152
	v_add_f32_e32 v118, 1.0, v118
	v_add_f32_e32 v137, 1.0, v137
	v_rcp_f32_e32 v118, v118
	v_rcp_f32_e32 v137, v137
; __device__ __forceinline__ unsigned cvt_pk_bf16(float lo, float hi) { unsigned r; asm volatile("v_cvt_pk_bf16_f32 %0, %1, %2" : "=v"(r) : "v"(lo), "v"(hi)); return r; }
;     __device__ __forceinline__ void operator()(const f32x4 (&acc)[2][2][4][2], const Unit& u, int wr, int wc, int fr, int fq) const {
;     ...
;             for (int m = 0; m < 4; ++m) { const int row = row0 + ai * HALF + m * 16; bf16_t* rowp = O + (size_t)row * ldc + col0;
;                 const float rs = rsc ? rsc[row] : 1.f;
;                 f32x4 r[2];
; #pragma unroll
;                 for (int n = 0; n < 2; ++n) { const f32x4 g = acc[ai][0][m][n] * sg[n] * rs, up = acc[ai][1][m][n] * su[n] * rs;
; #pragma unroll
;                     for (int e = 0; e < 4; ++e) { const float sgm = __builtin_amdgcn_rcpf(1.0f + __builtin_amdgcn_exp2f(-1.4426950408889634f * g[e])); r[n][e] = g[e] * sgm * up[e]; } }
;                 if constexpr (OUT8) { typedef unsigned u32x2v __attribute__((ext_vector_type(2))); _Pragma("unroll") for (int e = 0; e < 4; ++e) { r[0][e] = __builtin_amdgcn_fmed3f(r[0][e] * ACT8SCALE, -448.f, 448.f); r[1][e] = __builtin_amdgcn_fmed3f(r[1][e] * ACT8SCALE, -448.f, 448.f); }
;                     int w0 = __builtin_amdgcn_cvt_pk_fp8_f32(r[0][0], r[0][1], 0, false); w0 = __builtin_amdgcn_cvt_pk_fp8_f32(r[0][2], r[0][3], w0, true);
;                     int w1 = __builtin_amdgcn_cvt_pk_fp8_f32(r[1][0], r[1][1], 0, false); w1 = __builtin_amdgcn_cvt_pk_fp8_f32(r[1][2], r[1][3], w1, true);
;                     pw[m][0] = (unsigned)w0; pw[m][1] = (unsigned)w1; (void)rowp; }
;                 else { u32x4 w; w.x = cvt_pk_bf16(r[0][0], r[0][1]); w.y = cvt_pk_bf16(r[0][2], r[0][3]); w.z = cvt_pk_bf16(r[1][0], r[1][1]); w.w = cvt_pk_bf16(r[1][2], r[1][3]);
;                     *(u32x4*)rowp = w; } }
	v_mul_f32_e32 v152, v155, v152
	v_mul_f32_e32 v119, v167, v165
	v_mul_f32_e32 v115, v115, v118
	v_mul_f32_e32 v137, v161, v137
	v_mul_f32_e32 v155, v154, v152
	v_mul_f32_e32 v114, v114, v115
	v_mul_f32_e32 v137, v160, v137
	v_mul_f32_e32 v119, v166, v119
	v_cvt_pk_bf16_f32 v152, v157, v156
	v_cvt_pk_bf16_f32 v153, v158, v137
	v_cvt_pk_bf16_f32 v154, v159, v119
	v_cvt_pk_bf16_f32 v155, v155, v114
	v_or_b32_e32 v114, 16, v136
	v_ashrrev_i32_e32 v115, 31, v114
	global_store_dwordx4 v[180:181], v[152:155], off
	v_lshl_add_u64 v[118:119], v[114:115], 2, s[20:21]
	s_nop 1
	v_mov_b32_e32 v118, v240
	v_cvt_f32_i32_e32 v153, v108
	v_cvt_f32_i32_e32 v108, v105
	v_cvt_f32_i32_e32 v152, v104
	v_cvt_f32_i32_e32 v105, v110
	v_cvt_f32_i32_e32 v104, v106
	v_cvt_f32_i32_e32 v110, v107
	v_cvt_f32_i32_e32 v107, v100
	v_cvt_f32_i32_e32 v106, v96
	v_cvt_f32_i32_e32 v100, v97
	v_pk_mul_f32 v[108:109], v[124:125], v[108:109]
	v_cvt_f32_i32_e32 v97, v102
	v_pk_mul_f32 v[152:153], v[126:127], v[152:153]
	v_pk_mul_f32 v[104:105], v[140:141], v[104:105]
	v_pk_mul_f32 v[110:111], v[116:117], v[110:111]
	v_pk_mul_f32 v[106:107], v[142:143], v[106:107]
	v_pk_mul_f32 v[100:101], v[122:123], v[100:101]
	v_cvt_f32_i32_e32 v96, v98
	v_mad_i64_i32 v[114:115], s[70:71], v114, s89, v[138:139]
	v_lshl_add_u64 v[114:115], v[114:115], 0, v[120:121]
	v_pk_mul_f32 v[96:97], v[144:145], v[96:97]
	v_pk_mul_f32 v[108:109], v[108:109], v[118:119] op_sel_hi:[1,0]
	s_nop 0
	v_mul_f32_e32 v102, 0xbfb8aa3b, v109
	v_exp_f32_e32 v102, v102
	v_pk_mul_f32 v[152:153], v[152:153], v[118:119] op_sel_hi:[1,0]
	v_pk_mul_f32 v[104:105], v[104:105], v[118:119] op_sel_hi:[1,0]
	v_pk_mul_f32 v[110:111], v[110:111], v[118:119] op_sel_hi:[1,0]
	v_pk_mul_f32 v[106:107], v[106:107], v[118:119] op_sel_hi:[1,0]
	v_pk_mul_f32 v[100:101], v[100:101], v[118:119] op_sel_hi:[1,0]
	v_mul_f32_e32 v98, 0xbfb8aa3b, v153
	v_mul_f32_e32 v119, 0xbfb8aa3b, v105
	v_mul_f32_e32 v137, 0xbfb8aa3b, v111
	v_mul_f32_e32 v154, 0xbfb8aa3b, v107
	v_exp_f32_e32 v98, v98
	v_exp_f32_e32 v119, v119
	v_exp_f32_e32 v137, v137
	v_exp_f32_e32 v154, v154
	v_add_f32_e32 v102, 1.0, v102
	v_rcp_f32_e32 v102, v102
	v_add_f32_e32 v98, 1.0, v98
	v_add_f32_e32 v119, 1.0, v119
	v_add_f32_e32 v137, 1.0, v137
	v_add_f32_e32 v154, 1.0, v154
	v_rcp_f32_e32 v98, v98
	v_rcp_f32_e32 v119, v119
	v_rcp_f32_e32 v137, v137
	v_rcp_f32_e32 v154, v154
	v_mul_f32_e32 v102, v109, v102
	v_mul_f32_e32 v108, v108, v102
	v_cvt_f32_i32_e32 v102, v99
	v_mul_f32_e32 v98, v153, v98
	v_pk_mul_f32 v[96:97], v[96:97], v[118:119] op_sel_hi:[1,0]
	v_mul_f32_e32 v109, v111, v137
	v_mul_f32_e32 v107, v107, v154
	v_mul_f32_e32 v111, v152, v98
	v_mul_f32_e32 v98, 0xbfb8aa3b, v97
	v_mul_f32_e32 v106, v106, v107
	v_exp_f32_e32 v107, v98
	v_pk_mul_f32 v[98:99], v[112:113], v[102:103]
	v_mul_f32_e32 v155, 0xbfb8aa3b, v101
	v_pk_mul_f32 v[98:99], v[98:99], v[118:119] op_sel_hi:[1,0]
	v_exp_f32_e32 v155, v155
	v_mul_f32_e32 v102, 0xbfb8aa3b, v99
	v_exp_f32_e32 v102, v102
	v_add_f32_e32 v103, 1.0, v107
	v_add_f32_e32 v155, 1.0, v155
	v_rcp_f32_e32 v155, v155
	v_rcp_f32_e32 v103, v103
	v_add_f32_e32 v102, 1.0, v102
	v_rcp_f32_e32 v102, v102
	v_mul_f32_e32 v101, v101, v155
	v_mul_f32_e32 v97, v97, v103
	v_mul_f32_e32 v100, v100, v101
	v_mul_f32_e32 v101, v96, v97
	v_mul_f32_e32 v96, v99, v102
	v_mul_f32_e32 v105, v105, v119
	v_mul_f32_e32 v99, v98, v96
	v_cvt_pk_bf16_f32 v96, v111, v108
	v_mul_f32_e32 v104, v104, v105
	v_mul_f32_e32 v105, v110, v109
	v_cvt_pk_bf16_f32 v97, v104, v105
	v_cvt_pk_bf16_f32 v98, v106, v100
	v_cvt_pk_bf16_f32 v99, v101, v99
	global_store_dwordx4 v[114:115], v[96:99], off
	v_cvt_f32_i32_e32 v101, v92
	v_cvt_f32_i32_e32 v100, v88
	v_or_b32_e32 v96, 32, v136
	v_ashrrev_i32_e32 v97, 31, v96
	v_lshl_add_u64 v[98:99], v[96:97], 2, s[20:21]
	s_nop 1
	v_mov_b32_e32 v98, v241
	v_cvt_f32_i32_e32 v92, v89
	v_cvt_f32_i32_e32 v89, v94
	v_cvt_f32_i32_e32 v88, v90
	v_cvt_f32_i32_e32 v94, v91
	v_cvt_f32_i32_e32 v91, v84
	v_cvt_f32_i32_e32 v90, v80
	v_cvt_f32_i32_e32 v84, v81
	v_cvt_f32_i32_e32 v81, v86
	v_cvt_f32_i32_e32 v80, v82
	v_cvt_f32_i32_e32 v86, v83
	v_mad_i64_i32 v[82:83], s[70:71], v96, s89, v[138:139]
	v_lshl_add_u64 v[96:97], v[82:83], 0, v[120:121]
	v_pk_mul_f32 v[82:83], v[126:127], v[100:101]
	v_pk_mul_f32 v[92:93], v[124:125], v[92:93]
	v_pk_mul_f32 v[88:89], v[140:141], v[88:89]
	v_pk_mul_f32 v[94:95], v[116:117], v[94:95]
	v_pk_mul_f32 v[90:91], v[142:143], v[90:91]
	v_pk_mul_f32 v[84:85], v[122:123], v[84:85]
	v_pk_mul_f32 v[80:81], v[144:145], v[80:81]
	v_pk_mul_f32 v[82:83], v[82:83], v[98:99] op_sel_hi:[1,0]
	v_pk_mul_f32 v[92:93], v[92:93], v[98:99] op_sel_hi:[1,0]
	v_pk_mul_f32 v[88:89], v[88:89], v[98:99] op_sel_hi:[1,0]
	v_pk_mul_f32 v[94:95], v[94:95], v[98:99] op_sel_hi:[1,0]
	v_pk_mul_f32 v[90:91], v[90:91], v[98:99] op_sel_hi:[1,0]
	v_pk_mul_f32 v[84:85], v[84:85], v[98:99] op_sel_hi:[1,0]
	v_pk_mul_f32 v[80:81], v[80:81], v[98:99] op_sel_hi:[1,0]
	v_mul_f32_e32 v99, 0xbfb8aa3b, v83
	v_exp_f32_e32 v99, v99
	v_mul_f32_e32 v103, 0xbfb8aa3b, v91
	v_exp_f32_e32 v103, v103
	v_mul_f32_e32 v104, 0xbfb8aa3b, v85
	v_add_f32_e32 v99, 1.0, v99
	v_rcp_f32_e32 v99, v99
	v_add_f32_e32 v103, 1.0, v103
	v_rcp_f32_e32 v103, v103
	v_mul_f32_e32 v105, 0xbfb8aa3b, v81
	v_mul_f32_e32 v83, v83, v99
	v_mul_f32_e32 v99, v82, v83
	v_pk_mul_f32 v[82:83], v[112:113], v[86:87]
	v_mul_f32_e32 v91, v91, v103
	v_pk_mul_f32 v[82:83], v[82:83], v[98:99] op_sel_hi:[1,0]
	v_mul_f32_e32 v100, 0xbfb8aa3b, v93
	v_exp_f32_e32 v104, v104
	v_mul_f32_e32 v90, v90, v91
	v_exp_f32_e32 v91, v105
	v_mul_f32_e32 v86, 0xbfb8aa3b, v83
	v_mul_f32_e32 v101, 0xbfb8aa3b, v89
; __device__ __forceinline__ unsigned cvt_pk_bf16(float lo, float hi) { unsigned r; asm volatile("v_cvt_pk_bf16_f32 %0, %1, %2" : "=v"(r) : "v"(lo), "v"(hi)); return r; }
;     __device__ __forceinline__ void operator()(const f32x4 (&acc)[2][2][4][2], const Unit& u, int wr, int wc, int fr, int fq) const {
;     ...
;             for (int m = 0; m < 4; ++m) { const int row = row0 + ai * HALF + m * 16; bf16_t* rowp = O + (size_t)row * ldc + col0;
;                 const float rs = rsc ? rsc[row] : 1.f;
;                 f32x4 r[2];
; #pragma unroll
;                 for (int n = 0; n < 2; ++n) { const f32x4 g = acc[ai][0][m][n] * sg[n] * rs, up = acc[ai][1][m][n] * su[n] * rs;
; #pragma unroll
;                     for (int e = 0; e < 4; ++e) { const float sgm = __builtin_amdgcn_rcpf(1.0f + __builtin_amdgcn_exp2f(-1.4426950408889634f * g[e])); r[n][e] = g[e] * sgm * up[e]; } }
;                 if constexpr (OUT8) { typedef unsigned u32x2v __attribute__((ext_vector_type(2))); _Pragma("unroll") for (int e = 0; e < 4; ++e) { r[0][e] = __builtin_amdgcn_fmed3f(r[0][e] * ACT8SCALE, -448.f, 448.f); r[1][e] = __builtin_amdgcn_fmed3f(r[1][e] * ACT8SCALE, -448.f, 448.f); }
;                     int w0 = __builtin_amdgcn_cvt_pk_fp8_f32(r[0][0], r[0][1], 0, false); w0 = __builtin_amdgcn_cvt_pk_fp8_f32(r[0][2], r[0][3], w0, true);
;                     int w1 = __builtin_amdgcn_cvt_pk_fp8_f32(r[1][0], r[1][1], 0, false); w1 = __builtin_amdgcn_cvt_pk_fp8_f32(r[1][2], r[1][3], w1, true);
;                     pw[m][0] = (unsigned)w0; pw[m][1] = (unsigned)w1; (void)rowp; }
;                 else { u32x4 w; w.x = cvt_pk_bf16(r[0][0], r[0][1]); w.y = cvt_pk_bf16(r[0][2], r[0][3]); w.z = cvt_pk_bf16(r[1][0], r[1][1]); w.w = cvt_pk_bf16(r[1][2], r[1][3]);
;                     *(u32x4*)rowp = w; } }
	v_mul_f32_e32 v102, 0xbfb8aa3b, v95
	v_exp_f32_e32 v100, v100
	v_exp_f32_e32 v86, v86
	v_exp_f32_e32 v101, v101
	v_exp_f32_e32 v102, v102
	v_add_f32_e32 v104, 1.0, v104
	v_add_f32_e32 v87, 1.0, v91
	v_add_f32_e32 v100, 1.0, v100
	v_rcp_f32_e32 v104, v104
	v_rcp_f32_e32 v87, v87
	v_add_f32_e32 v86, 1.0, v86
	v_add_f32_e32 v101, 1.0, v101
	v_add_f32_e32 v102, 1.0, v102
	v_rcp_f32_e32 v100, v100
	v_rcp_f32_e32 v86, v86
	v_rcp_f32_e32 v101, v101
	v_rcp_f32_e32 v102, v102
	v_mul_f32_e32 v85, v85, v104
	v_mul_f32_e32 v81, v81, v87
	v_mul_f32_e32 v93, v93, v100
	v_mul_f32_e32 v84, v84, v85
	v_mul_f32_e32 v85, v80, v81
	v_mul_f32_e32 v80, v83, v86
	v_mul_f32_e32 v89, v89, v101
	v_mul_f32_e32 v95, v95, v102
	v_mul_f32_e32 v92, v92, v93
	v_mul_f32_e32 v83, v82, v80
	v_cvt_pk_bf16_f32 v80, v99, v92
	v_mul_f32_e32 v88, v88, v89
	v_mul_f32_e32 v89, v94, v95
	v_cvt_pk_bf16_f32 v81, v88, v89
	v_cvt_pk_bf16_f32 v82, v90, v84
	v_cvt_pk_bf16_f32 v83, v85, v83
	global_store_dwordx4 v[96:97], v[80:83], off
	v_cvt_f32_i32_e32 v85, v76
	v_cvt_f32_i32_e32 v84, v72
	v_or_b32_e32 v80, 48, v136
	v_ashrrev_i32_e32 v81, 31, v80
	v_lshl_add_u64 v[82:83], v[80:81], 2, s[20:21]
	s_nop 1
	v_mov_b32_e32 v82, v242
	v_cvt_f32_i32_e32 v76, v73
	v_cvt_f32_i32_e32 v73, v78
	v_cvt_f32_i32_e32 v72, v74
	v_cvt_f32_i32_e32 v78, v75
	v_cvt_f32_i32_e32 v75, v68
	v_cvt_f32_i32_e32 v74, v64
	v_cvt_f32_i32_e32 v68, v65
	v_cvt_f32_i32_e32 v65, v70
	v_cvt_f32_i32_e32 v64, v66
	v_pk_mul_f32 v[74:75], v[142:143], v[74:75]
	v_cvt_f32_i32_e32 v70, v67
	v_mad_i64_i32 v[66:67], s[70:71], v80, s89, v[138:139]
	v_lshl_add_u64 v[80:81], v[66:67], 0, v[120:121]
	v_pk_mul_f32 v[66:67], v[126:127], v[84:85]
	v_pk_mul_f32 v[76:77], v[124:125], v[76:77]
	v_pk_mul_f32 v[72:73], v[140:141], v[72:73]
	v_pk_mul_f32 v[78:79], v[116:117], v[78:79]
	v_pk_mul_f32 v[68:69], v[122:123], v[68:69]
	v_pk_mul_f32 v[64:65], v[144:145], v[64:65]
	v_pk_mul_f32 v[70:71], v[112:113], v[70:71]
	v_pk_mul_f32 v[74:75], v[74:75], v[82:83] op_sel_hi:[1,0]
	s_nop 0
	v_mul_f32_e32 v86, 0xbfb8aa3b, v75
	v_exp_f32_e32 v86, v86
	v_pk_mul_f32 v[66:67], v[66:67], v[82:83] op_sel_hi:[1,0]
	v_pk_mul_f32 v[76:77], v[76:77], v[82:83] op_sel_hi:[1,0]
	v_pk_mul_f32 v[72:73], v[72:73], v[82:83] op_sel_hi:[1,0]
	v_pk_mul_f32 v[78:79], v[78:79], v[82:83] op_sel_hi:[1,0]
	v_pk_mul_f32 v[68:69], v[68:69], v[82:83] op_sel_hi:[1,0]
	v_pk_mul_f32 v[64:65], v[64:65], v[82:83] op_sel_hi:[1,0]
	v_pk_mul_f32 v[70:71], v[70:71], v[82:83] op_sel_hi:[1,0]
	v_mul_f32_e32 v82, 0xbfb8aa3b, v67
	v_mul_f32_e32 v83, 0xbfb8aa3b, v77
	v_exp_f32_e32 v82, v82
	v_exp_f32_e32 v83, v83
	v_add_f32_e32 v86, 1.0, v86
	v_rcp_f32_e32 v86, v86
	v_add_f32_e32 v82, 1.0, v82
	v_add_f32_e32 v83, 1.0, v83
	v_mul_f32_e32 v87, 0xbfb8aa3b, v69
	v_mul_f32_e32 v88, 0xbfb8aa3b, v65
	v_rcp_f32_e32 v82, v82
	v_rcp_f32_e32 v83, v83
	v_mul_f32_e32 v75, v75, v86
	v_mul_f32_e32 v84, 0xbfb8aa3b, v73
	v_mul_f32_e32 v85, 0xbfb8aa3b, v79
	v_exp_f32_e32 v87, v87
	v_exp_f32_e32 v88, v88
	v_mul_f32_e32 v74, v74, v75
	v_mul_f32_e32 v75, 0xbfb8aa3b, v71
	v_exp_f32_e32 v84, v84
	v_exp_f32_e32 v85, v85
	v_exp_f32_e32 v75, v75
	v_mul_f32_e32 v67, v67, v82
	v_mul_f32_e32 v77, v77, v83
	v_add_f32_e32 v87, 1.0, v87
	v_mul_f32_e32 v66, v66, v67
	v_mul_f32_e32 v67, v76, v77
	v_add_f32_e32 v76, 1.0, v88
	v_add_f32_e32 v84, 1.0, v84
	v_add_f32_e32 v85, 1.0, v85
	v_rcp_f32_e32 v87, v87
	v_rcp_f32_e32 v76, v76
	v_add_f32_e32 v75, 1.0, v75
	v_rcp_f32_e32 v84, v84
	v_rcp_f32_e32 v85, v85
	v_rcp_f32_e32 v75, v75
	v_mul_f32_e32 v69, v69, v87
	v_mul_f32_e32 v65, v65, v76
	v_mul_f32_e32 v73, v73, v84
	v_mul_f32_e32 v79, v79, v85
	v_mul_f32_e32 v68, v68, v69
	v_mul_f32_e32 v69, v64, v65
	v_mul_f32_e32 v64, v71, v75
	v_mul_f32_e32 v72, v72, v73
	v_mul_f32_e32 v73, v78, v79
	v_mul_f32_e32 v70, v70, v64
	v_cvt_pk_bf16_f32 v64, v66, v67
	v_cvt_pk_bf16_f32 v65, v72, v73
	v_cvt_pk_bf16_f32 v66, v74, v68
	v_cvt_pk_bf16_f32 v67, v69, v70
	global_store_dwordx4 v[80:81], v[64:67], off
	s_nop 1
	v_mov_b32_e32 v64, v243
	s_nop 0
	v_cvt_f32_i32_e32 v67, v60
	v_cvt_f32_i32_e32 v66, v56
	v_cvt_f32_i32_e32 v60, v57
	v_cvt_f32_i32_e32 v57, v62
	v_cvt_f32_i32_e32 v56, v58
	v_cvt_f32_i32_e32 v62, v59
	v_cvt_f32_i32_e32 v59, v52
	v_cvt_f32_i32_e32 v58, v48
	v_cvt_f32_i32_e32 v52, v49
	v_cvt_f32_i32_e32 v49, v54
	v_cvt_f32_i32_e32 v48, v50
	v_pk_mul_f32 v[58:59], v[142:143], v[58:59]
	v_cvt_f32_i32_e32 v54, v51
	v_add_u32_e32 v50, 0x80, v136
	v_mad_i64_i32 v[50:51], s[70:71], v50, s89, v[138:139]
	v_lshl_add_u64 v[68:69], v[50:51], 0, v[120:121]
	v_pk_mul_f32 v[50:51], v[126:127], v[66:67]
	v_pk_mul_f32 v[60:61], v[124:125], v[60:61]
	v_pk_mul_f32 v[52:53], v[122:123], v[52:53]
	v_pk_mul_f32 v[48:49], v[144:145], v[48:49]
	v_pk_mul_f32 v[56:57], v[140:141], v[56:57]
	v_pk_mul_f32 v[62:63], v[116:117], v[62:63]
	v_pk_mul_f32 v[54:55], v[112:113], v[54:55]
	v_pk_mul_f32 v[58:59], v[58:59], v[64:65] op_sel_hi:[1,0]
	s_nop 0
	v_mul_f32_e32 v70, 0xbfb8aa3b, v59
	v_exp_f32_e32 v70, v70
	v_pk_mul_f32 v[50:51], v[50:51], v[64:65] op_sel_hi:[1,0]
	v_pk_mul_f32 v[60:61], v[60:61], v[64:65] op_sel_hi:[1,0]
	v_pk_mul_f32 v[52:53], v[52:53], v[64:65] op_sel_hi:[1,0]
	v_pk_mul_f32 v[48:49], v[48:49], v[64:65] op_sel_hi:[1,0]
	v_pk_mul_f32 v[56:57], v[56:57], v[64:65] op_sel_hi:[1,0]
	v_pk_mul_f32 v[62:63], v[62:63], v[64:65] op_sel_hi:[1,0]
	v_pk_mul_f32 v[54:55], v[54:55], v[64:65] op_sel_hi:[1,0]
	v_mul_f32_e32 v64, 0xbfb8aa3b, v51
	v_mul_f32_e32 v65, 0xbfb8aa3b, v61
	v_mul_f32_e32 v71, 0xbfb8aa3b, v53
	v_mul_f32_e32 v72, 0xbfb8aa3b, v49
	v_add_f32_e32 v70, 1.0, v70
	v_mul_f32_e32 v66, 0xbfb8aa3b, v57
	v_mul_f32_e32 v67, 0xbfb8aa3b, v63
; __device__ __forceinline__ unsigned cvt_pk_bf16(float lo, float hi) { unsigned r; asm volatile("v_cvt_pk_bf16_f32 %0, %1, %2" : "=v"(r) : "v"(lo), "v"(hi)); return r; }
;     __device__ __forceinline__ void operator()(const f32x4 (&acc)[2][2][4][2], const Unit& u, int wr, int wc, int fr, int fq) const {
;     ...
;             for (int m = 0; m < 4; ++m) { const int row = row0 + ai * HALF + m * 16; bf16_t* rowp = O + (size_t)row * ldc + col0;
;                 const float rs = rsc ? rsc[row] : 1.f;
;                 f32x4 r[2];
; #pragma unroll
;                 for (int n = 0; n < 2; ++n) { const f32x4 g = acc[ai][0][m][n] * sg[n] * rs, up = acc[ai][1][m][n] * su[n] * rs;
; #pragma unroll
;                     for (int e = 0; e < 4; ++e) { const float sgm = __builtin_amdgcn_rcpf(1.0f + __builtin_amdgcn_exp2f(-1.4426950408889634f * g[e])); r[n][e] = g[e] * sgm * up[e]; } }
;                 if constexpr (OUT8) { typedef unsigned u32x2v __attribute__((ext_vector_type(2))); _Pragma("unroll") for (int e = 0; e < 4; ++e) { r[0][e] = __builtin_amdgcn_fmed3f(r[0][e] * ACT8SCALE, -448.f, 448.f); r[1][e] = __builtin_amdgcn_fmed3f(r[1][e] * ACT8SCALE, -448.f, 448.f); }
;                     int w0 = __builtin_amdgcn_cvt_pk_fp8_f32(r[0][0], r[0][1], 0, false); w0 = __builtin_amdgcn_cvt_pk_fp8_f32(r[0][2], r[0][3], w0, true);
;                     int w1 = __builtin_amdgcn_cvt_pk_fp8_f32(r[1][0], r[1][1], 0, false); w1 = __builtin_amdgcn_cvt_pk_fp8_f32(r[1][2], r[1][3], w1, true);
;                     pw[m][0] = (unsigned)w0; pw[m][1] = (unsigned)w1; (void)rowp; }
;                 else { u32x4 w; w.x = cvt_pk_bf16(r[0][0], r[0][1]); w.y = cvt_pk_bf16(r[0][2], r[0][3]); w.z = cvt_pk_bf16(r[1][0], r[1][1]); w.w = cvt_pk_bf16(r[1][2], r[1][3]);
;                     *(u32x4*)rowp = w; } }
	v_mul_f32_e32 v73, 0xbfb8aa3b, v55
	v_exp_f32_e32 v64, v64
	v_exp_f32_e32 v65, v65
	v_exp_f32_e32 v71, v71
	v_exp_f32_e32 v72, v72
	v_rcp_f32_e32 v70, v70
	v_exp_f32_e32 v66, v66
	v_exp_f32_e32 v67, v67
	v_exp_f32_e32 v73, v73
	v_add_f32_e32 v64, 1.0, v64
	v_add_f32_e32 v65, 1.0, v65
	v_add_f32_e32 v71, 1.0, v71
	v_add_f32_e32 v72, 1.0, v72
	v_mul_f32_e32 v59, v59, v70
	v_add_f32_e32 v66, 1.0, v66
	v_add_f32_e32 v67, 1.0, v67
	v_rcp_f32_e32 v64, v64
	v_rcp_f32_e32 v65, v65
	v_rcp_f32_e32 v71, v71
	v_rcp_f32_e32 v72, v72
	v_mul_f32_e32 v58, v58, v59
	v_add_f32_e32 v59, 1.0, v73
	v_rcp_f32_e32 v66, v66
	v_rcp_f32_e32 v67, v67
	v_rcp_f32_e32 v59, v59
	v_mul_f32_e32 v51, v51, v64
	v_mul_f32_e32 v61, v61, v65
	v_mul_f32_e32 v53, v53, v71
	v_mul_f32_e32 v49, v49, v72
	v_mul_f32_e32 v57, v57, v66
	v_mul_f32_e32 v63, v63, v67
	v_mul_f32_e32 v50, v50, v51
	v_mul_f32_e32 v51, v60, v61
	v_mul_f32_e32 v52, v52, v53
	v_mul_f32_e32 v53, v48, v49
	v_mul_f32_e32 v48, v55, v59
	v_mul_f32_e32 v56, v56, v57
	v_mul_f32_e32 v57, v62, v63
	v_mul_f32_e32 v54, v54, v48
	v_cvt_pk_bf16_f32 v48, v50, v51
	v_cvt_pk_bf16_f32 v49, v56, v57
	v_cvt_pk_bf16_f32 v50, v58, v52
	v_cvt_pk_bf16_f32 v51, v53, v54
	global_store_dwordx4 v[68:69], v[48:51], off
	s_nop 1
	v_mov_b32_e32 v48, v244
	s_nop 0
	v_cvt_f32_i32_e32 v51, v44
	v_cvt_f32_i32_e32 v50, v40
	v_cvt_f32_i32_e32 v44, v41
	v_cvt_f32_i32_e32 v41, v46
	v_cvt_f32_i32_e32 v40, v42
	v_cvt_f32_i32_e32 v46, v43
	v_cvt_f32_i32_e32 v43, v36
	v_cvt_f32_i32_e32 v42, v32
	v_cvt_f32_i32_e32 v36, v33
	v_cvt_f32_i32_e32 v33, v38
	v_cvt_f32_i32_e32 v32, v34
	v_cvt_f32_i32_e32 v38, v35
	v_add_u32_e32 v34, 0x90, v136
	v_mad_i64_i32 v[34:35], s[70:71], v34, s89, v[138:139]
	v_lshl_add_u64 v[52:53], v[34:35], 0, v[120:121]
	v_pk_mul_f32 v[34:35], v[126:127], v[50:51]
	v_pk_mul_f32 v[44:45], v[124:125], v[44:45]
	v_pk_mul_f32 v[36:37], v[122:123], v[36:37]
	v_pk_mul_f32 v[32:33], v[144:145], v[32:33]
	v_pk_mul_f32 v[40:41], v[140:141], v[40:41]
	v_pk_mul_f32 v[46:47], v[116:117], v[46:47]
	v_pk_mul_f32 v[42:43], v[142:143], v[42:43]
	v_pk_mul_f32 v[38:39], v[112:113], v[38:39]
	v_pk_mul_f32 v[34:35], v[34:35], v[48:49] op_sel_hi:[1,0]
	v_pk_mul_f32 v[44:45], v[44:45], v[48:49] op_sel_hi:[1,0]
	v_pk_mul_f32 v[36:37], v[36:37], v[48:49] op_sel_hi:[1,0]
	v_pk_mul_f32 v[32:33], v[32:33], v[48:49] op_sel_hi:[1,0]
	v_pk_mul_f32 v[40:41], v[40:41], v[48:49] op_sel_hi:[1,0]
	v_pk_mul_f32 v[46:47], v[46:47], v[48:49] op_sel_hi:[1,0]
	v_pk_mul_f32 v[42:43], v[42:43], v[48:49] op_sel_hi:[1,0]
	v_pk_mul_f32 v[38:39], v[38:39], v[48:49] op_sel_hi:[1,0]
	v_mul_f32_e32 v48, 0xbfb8aa3b, v35
	v_mul_f32_e32 v49, 0xbfb8aa3b, v45
	v_mul_f32_e32 v55, 0xbfb8aa3b, v37
	v_mul_f32_e32 v56, 0xbfb8aa3b, v33
	v_mul_f32_e32 v50, 0xbfb8aa3b, v41
	v_mul_f32_e32 v51, 0xbfb8aa3b, v47
	v_mul_f32_e32 v54, 0xbfb8aa3b, v43
	v_mul_f32_e32 v57, 0xbfb8aa3b, v39
	v_exp_f32_e32 v48, v48
	v_exp_f32_e32 v49, v49
	v_exp_f32_e32 v55, v55
	v_exp_f32_e32 v56, v56
	v_exp_f32_e32 v50, v50
	v_exp_f32_e32 v51, v51
	v_exp_f32_e32 v54, v54
	v_exp_f32_e32 v57, v57
	v_add_f32_e32 v48, 1.0, v48
	v_add_f32_e32 v49, 1.0, v49
	v_add_f32_e32 v55, 1.0, v55
	v_add_f32_e32 v56, 1.0, v56
	v_add_f32_e32 v50, 1.0, v50
	v_add_f32_e32 v51, 1.0, v51
	v_add_f32_e32 v54, 1.0, v54
	v_add_f32_e32 v57, 1.0, v57
	v_rcp_f32_e32 v48, v48
	v_rcp_f32_e32 v49, v49
	v_rcp_f32_e32 v55, v55
	v_rcp_f32_e32 v56, v56
	v_rcp_f32_e32 v50, v50
	v_rcp_f32_e32 v51, v51
	v_rcp_f32_e32 v54, v54
	v_rcp_f32_e32 v57, v57
	v_mul_f32_e32 v35, v35, v48
	v_mul_f32_e32 v45, v45, v49
	v_mul_f32_e32 v37, v37, v55
	v_mul_f32_e32 v33, v33, v56
	v_mul_f32_e32 v41, v41, v50
	v_mul_f32_e32 v47, v47, v51
	v_mul_f32_e32 v43, v43, v54
	v_mul_f32_e32 v34, v34, v35
	v_mul_f32_e32 v35, v44, v45
	v_mul_f32_e32 v36, v36, v37
	v_mul_f32_e32 v37, v32, v33
	v_mul_f32_e32 v32, v39, v57
	v_mul_f32_e32 v40, v40, v41
	v_mul_f32_e32 v41, v46, v47
	v_mul_f32_e32 v42, v42, v43
	v_mul_f32_e32 v38, v38, v32
	v_cvt_pk_bf16_f32 v32, v34, v35
	v_cvt_pk_bf16_f32 v33, v40, v41
	v_cvt_pk_bf16_f32 v34, v42, v36
	v_cvt_pk_bf16_f32 v35, v37, v38
	global_store_dwordx4 v[52:53], v[32:35], off
	s_nop 1
	v_mov_b32_e32 v32, v245
	s_nop 0
	v_cvt_f32_i32_e32 v35, v28
	v_cvt_f32_i32_e32 v34, v24
	v_cvt_f32_i32_e32 v28, v25
	v_cvt_f32_i32_e32 v25, v30
	v_cvt_f32_i32_e32 v24, v26
	v_cvt_f32_i32_e32 v30, v27
	v_cvt_f32_i32_e32 v27, v20
	v_cvt_f32_i32_e32 v26, v16
	v_cvt_f32_i32_e32 v20, v17
	v_cvt_f32_i32_e32 v17, v22
	v_cvt_f32_i32_e32 v16, v18
	v_cvt_f32_i32_e32 v22, v19
	v_add_u32_e32 v18, 0xa0, v136
	v_mad_i64_i32 v[18:19], s[70:71], v18, s89, v[138:139]
	v_lshl_add_u64 v[36:37], v[18:19], 0, v[120:121]
	v_pk_mul_f32 v[18:19], v[126:127], v[34:35]
	v_pk_mul_f32 v[28:29], v[124:125], v[28:29]
	v_pk_mul_f32 v[24:25], v[140:141], v[24:25]
	v_pk_mul_f32 v[30:31], v[116:117], v[30:31]
	v_pk_mul_f32 v[26:27], v[142:143], v[26:27]
	v_pk_mul_f32 v[20:21], v[122:123], v[20:21]
	v_pk_mul_f32 v[16:17], v[144:145], v[16:17]
; __device__ __forceinline__ int tid_of(int wv) { int l; asm volatile("v_mbcnt_lo_u32_b32 %0, -1, 0\n\tv_mbcnt_hi_u32_b32 %0, -1, %0" : "=v"(l)); return wv * 64 + l; }
;     __device__ __forceinline__ void operator()(const f32x4 (&acc)[2][2][4][2], const Unit& u, int wr, int wc, int fr, int fq) const {
;     ...
;             for (int m = 0; m < 4; ++m) { const int row = row0 + ai * HALF + m * 16; bf16_t* rowp = O + (size_t)row * ldc + col0;
;                 const float rs = rsc ? rsc[row] : 1.f;
;                 f32x4 r[2];
; #pragma unroll
;                 for (int n = 0; n < 2; ++n) { const f32x4 g = acc[ai][0][m][n] * sg[n] * rs, up = acc[ai][1][m][n] * su[n] * rs;
; #pragma unroll
;                     for (int e = 0; e < 4; ++e) { const float sgm = __builtin_amdgcn_rcpf(1.0f + __builtin_amdgcn_exp2f(-1.4426950408889634f * g[e])); r[n][e] = g[e] * sgm * up[e]; } }
;                 if constexpr (OUT8) { typedef unsigned u32x2v __attribute__((ext_vector_type(2))); _Pragma("unroll") for (int e = 0; e < 4; ++e) { r[0][e] = __builtin_amdgcn_fmed3f(r[0][e] * ACT8SCALE, -448.f, 448.f); r[1][e] = __builtin_amdgcn_fmed3f(r[1][e] * ACT8SCALE, -448.f, 448.f); }
;                     int w0 = __builtin_amdgcn_cvt_pk_fp8_f32(r[0][0], r[0][1], 0, false); w0 = __builtin_amdgcn_cvt_pk_fp8_f32(r[0][2], r[0][3], w0, true);
;                     int w1 = __builtin_amdgcn_cvt_pk_fp8_f32(r[1][0], r[1][1], 0, false); w1 = __builtin_amdgcn_cvt_pk_fp8_f32(r[1][2], r[1][3], w1, true);
;                     pw[m][0] = (unsigned)w0; pw[m][1] = (unsigned)w1; (void)rowp; }
;                 else { u32x4 w; w.x = cvt_pk_bf16(r[0][0], r[0][1]); w.y = cvt_pk_bf16(r[0][2], r[0][3]); w.z = cvt_pk_bf16(r[1][0], r[1][1]); w.w = cvt_pk_bf16(r[1][2], r[1][3]);
;                     *(u32x4*)rowp = w; } }
;     ...
;         if constexpr (!Epi::AFTER_DRAIN) { const int t2 = tid_of(wv), l2 = t2 & 63; E(acc, cur, wid >> 2, wid & 3, l2 & 15, l2 >> 4); S.done(cur); }
;         if (!has_next) break;
; #pragma unroll
;         for (int a = 0; a < 2; ++a)
; #pragma unroll
;             for (int b = 0; b < 2; ++b)
; #pragma unroll
;                 for (int m = 0; m < 4; ++m)
; #pragma unroll
;                     for (int n = 0; n < 2; ++n) acc[a][b][m][n] = (f32x4){0.f, 0.f, 0.f, 0.f};
;         cur = nxt; cA = nA; cB = nB; ++ui;
;         if constexpr (ALIGN_EPI) { if (wr == 1) PG8_BAR; }
	v_pk_mul_f32 v[22:23], v[112:113], v[22:23]
	v_pk_mul_f32 v[18:19], v[18:19], v[32:33] op_sel_hi:[1,0]
	v_pk_mul_f32 v[28:29], v[28:29], v[32:33] op_sel_hi:[1,0]
	v_pk_mul_f32 v[24:25], v[24:25], v[32:33] op_sel_hi:[1,0]
	v_pk_mul_f32 v[30:31], v[30:31], v[32:33] op_sel_hi:[1,0]
	v_pk_mul_f32 v[26:27], v[26:27], v[32:33] op_sel_hi:[1,0]
	v_pk_mul_f32 v[20:21], v[20:21], v[32:33] op_sel_hi:[1,0]
	v_pk_mul_f32 v[16:17], v[16:17], v[32:33] op_sel_hi:[1,0]
	v_pk_mul_f32 v[22:23], v[22:23], v[32:33] op_sel_hi:[1,0]
	v_mul_f32_e32 v32, 0xbfb8aa3b, v19
	v_mul_f32_e32 v33, 0xbfb8aa3b, v29
	v_mul_f32_e32 v34, 0xbfb8aa3b, v25
	v_mul_f32_e32 v35, 0xbfb8aa3b, v31
	v_mul_f32_e32 v38, 0xbfb8aa3b, v27
	v_mul_f32_e32 v39, 0xbfb8aa3b, v21
	v_mul_f32_e32 v40, 0xbfb8aa3b, v17
	v_mul_f32_e32 v41, 0xbfb8aa3b, v23
	v_exp_f32_e32 v32, v32
	v_exp_f32_e32 v33, v33
	v_exp_f32_e32 v34, v34
	v_exp_f32_e32 v35, v35
	v_exp_f32_e32 v38, v38
	v_exp_f32_e32 v39, v39
	v_exp_f32_e32 v40, v40
	v_exp_f32_e32 v41, v41
	v_add_f32_e32 v32, 1.0, v32
	v_add_f32_e32 v33, 1.0, v33
	v_add_f32_e32 v34, 1.0, v34
	v_add_f32_e32 v35, 1.0, v35
	v_add_f32_e32 v38, 1.0, v38
	v_add_f32_e32 v39, 1.0, v39
	v_add_f32_e32 v40, 1.0, v40
	v_add_f32_e32 v41, 1.0, v41
	v_rcp_f32_e32 v32, v32
	v_rcp_f32_e32 v33, v33
	v_rcp_f32_e32 v34, v34
	v_rcp_f32_e32 v35, v35
	v_rcp_f32_e32 v38, v38
	v_rcp_f32_e32 v39, v39
	v_rcp_f32_e32 v40, v40
	v_rcp_f32_e32 v41, v41
	v_mul_f32_e32 v19, v19, v32
	v_mul_f32_e32 v29, v29, v33
	v_mul_f32_e32 v25, v25, v34
	v_mul_f32_e32 v31, v31, v35
	v_mul_f32_e32 v27, v27, v38
	v_mul_f32_e32 v21, v21, v39
	v_mul_f32_e32 v17, v17, v40
	v_mul_f32_e32 v23, v23, v41
	v_mul_f32_e32 v18, v18, v19
	v_mul_f32_e32 v19, v28, v29
	v_mul_f32_e32 v24, v24, v25
	v_mul_f32_e32 v25, v30, v31
	v_mul_f32_e32 v26, v26, v27
	v_mul_f32_e32 v20, v20, v21
	v_mul_f32_e32 v21, v16, v17
	v_mul_f32_e32 v22, v22, v23
	v_cvt_pk_bf16_f32 v16, v18, v19
	v_cvt_pk_bf16_f32 v17, v24, v25
	v_cvt_pk_bf16_f32 v18, v26, v20
	v_cvt_pk_bf16_f32 v19, v21, v22
	global_store_dwordx4 v[36:37], v[16:19], off
	s_nop 1
	v_mov_b32_e32 v16, v246
	s_nop 0
	v_cvt_f32_i32_e32 v19, v12
	v_cvt_f32_i32_e32 v18, v8
	v_cvt_f32_i32_e32 v12, v9
	v_cvt_f32_i32_e32 v9, v14
	v_cvt_f32_i32_e32 v8, v10
	v_cvt_f32_i32_e32 v14, v11
	v_cvt_f32_i32_e32 v11, v4
	v_cvt_f32_i32_e32 v10, v0
	v_cvt_f32_i32_e32 v4, v1
	v_cvt_f32_i32_e32 v1, v6
	v_cvt_f32_i32_e32 v0, v2
	v_cvt_f32_i32_e32 v6, v3
	v_add_u32_e32 v2, 0xb0, v136
	v_mad_i64_i32 v[2:3], s[66:67], v2, s89, v[138:139]
	v_lshl_add_u64 v[20:21], v[2:3], 0, v[120:121]
	v_pk_mul_f32 v[2:3], v[126:127], v[18:19]
	v_pk_mul_f32 v[12:13], v[124:125], v[12:13]
	v_pk_mul_f32 v[8:9], v[140:141], v[8:9]
	v_pk_mul_f32 v[14:15], v[116:117], v[14:15]
	v_pk_mul_f32 v[10:11], v[142:143], v[10:11]
	v_pk_mul_f32 v[4:5], v[122:123], v[4:5]
	v_pk_mul_f32 v[0:1], v[144:145], v[0:1]
	v_pk_mul_f32 v[6:7], v[112:113], v[6:7]
	s_mov_b64 s[66:67], -1
	v_pk_mul_f32 v[2:3], v[2:3], v[16:17] op_sel_hi:[1,0]
	v_pk_mul_f32 v[12:13], v[12:13], v[16:17] op_sel_hi:[1,0]
	v_pk_mul_f32 v[8:9], v[8:9], v[16:17] op_sel_hi:[1,0]
	v_pk_mul_f32 v[14:15], v[14:15], v[16:17] op_sel_hi:[1,0]
	v_pk_mul_f32 v[10:11], v[10:11], v[16:17] op_sel_hi:[1,0]
	v_pk_mul_f32 v[4:5], v[4:5], v[16:17] op_sel_hi:[1,0]
	v_pk_mul_f32 v[0:1], v[0:1], v[16:17] op_sel_hi:[1,0]
	v_pk_mul_f32 v[6:7], v[6:7], v[16:17] op_sel_hi:[1,0]
	v_mul_f32_e32 v16, 0xbfb8aa3b, v3
	v_mul_f32_e32 v17, 0xbfb8aa3b, v13
	v_mul_f32_e32 v18, 0xbfb8aa3b, v9
	v_mul_f32_e32 v19, 0xbfb8aa3b, v15
	v_mul_f32_e32 v22, 0xbfb8aa3b, v11
	v_mul_f32_e32 v23, 0xbfb8aa3b, v5
	v_mul_f32_e32 v24, 0xbfb8aa3b, v1
	v_mul_f32_e32 v25, 0xbfb8aa3b, v7
	v_exp_f32_e32 v16, v16
	v_exp_f32_e32 v17, v17
	v_exp_f32_e32 v18, v18
	v_exp_f32_e32 v19, v19
	v_exp_f32_e32 v22, v22
	v_exp_f32_e32 v23, v23
	v_exp_f32_e32 v24, v24
	v_exp_f32_e32 v25, v25
	v_add_f32_e32 v16, 1.0, v16
	v_add_f32_e32 v17, 1.0, v17
	v_add_f32_e32 v18, 1.0, v18
	v_add_f32_e32 v19, 1.0, v19
	v_add_f32_e32 v22, 1.0, v22
	v_add_f32_e32 v23, 1.0, v23
	v_add_f32_e32 v24, 1.0, v24
	v_add_f32_e32 v25, 1.0, v25
	v_rcp_f32_e32 v16, v16
	v_rcp_f32_e32 v17, v17
	v_rcp_f32_e32 v18, v18
	v_rcp_f32_e32 v19, v19
	v_rcp_f32_e32 v22, v22
	v_rcp_f32_e32 v23, v23
	v_rcp_f32_e32 v24, v24
	v_rcp_f32_e32 v25, v25
	v_mul_f32_e32 v3, v3, v16
	v_mul_f32_e32 v13, v13, v17
	v_mul_f32_e32 v9, v9, v18
	v_mul_f32_e32 v15, v15, v19
	v_mul_f32_e32 v11, v11, v22
	v_mul_f32_e32 v5, v5, v23
	v_mul_f32_e32 v1, v1, v24
	v_mul_f32_e32 v7, v7, v25
	v_mul_f32_e32 v2, v2, v3
	v_mul_f32_e32 v3, v12, v13
	v_mul_f32_e32 v8, v8, v9
	v_mul_f32_e32 v9, v14, v15
	v_mul_f32_e32 v10, v10, v11
	v_mul_f32_e32 v4, v4, v5
	v_mul_f32_e32 v5, v0, v1
	v_mul_f32_e32 v6, v6, v7
	v_cvt_pk_bf16_f32 v0, v2, v3
	v_cvt_pk_bf16_f32 v1, v8, v9
	v_cvt_pk_bf16_f32 v2, v10, v4
	v_cvt_pk_bf16_f32 v3, v5, v6
	global_store_dwordx4 v[20:21], v[0:3], off
	s_cbranch_vccnz .LBB0_270
	s_andn2_b64 vcc, exec, s[6:7]
	s_cbranch_vccnz .LBB0_269
	s_barrier
	s_branch .LBB0_269

; template <int MASK> __device__ __forceinline__ float xor_get(float v) { return __int_as_float(__builtin_amdgcn_ds_swizzle(__float_as_int(v), 0x1F | (MASK << 10))); }
; __device__ __forceinline__ float xor32_sum(float v) { auto rr = __builtin_amdgcn_permlane32_swap(__float_as_uint(v), __float_as_uint(v), false, false); return __uint_as_float(rr[0]) + __uint_as_float(rr[1]); }
; __device__ __forceinline__ void ss_add(u64* p, float v) { atomicAdd(p, (u64)(v * SSFIX)); }
; __device__ __forceinline__ unsigned cvt_pk_bf16(float lo, float hi) { unsigned r; asm volatile("v_cvt_pk_bf16_f32 %0, %1, %2" : "=v"(r) : "v"(lo), "v"(hi)); return r; }
;     __device__ __forceinline__ void operator()(const f32x4 (&acc)[2][2][4][2], const Unit& u, int wr, int wc, int fr, int fq) const {
;     ...
;             for (int m = 0; m < 4; ++m) { const int row = row0 + ai * HALF + m * 16; const size_t off = (size_t)row * ldc + col0; float sq = 0.f;
; #pragma unroll
;                 for (int bj = 0; bj < 2; ++bj) { const size_t p = off + bj * HALF; f32x4 b0, b1;
;                     if constexpr (BASE16) { const u32x4 wb = *(const u32x4*)((const bf16_t*)base + p);
;                         b0 = (f32x4){__uint_as_float(wb.x << 16), __uint_as_float(wb.x & 0xffff0000u), __uint_as_float(wb.y << 16), __uint_as_float(wb.y & 0xffff0000u)};
;                         b1 = (f32x4){__uint_as_float(wb.z << 16), __uint_as_float(wb.z & 0xffff0000u), __uint_as_float(wb.w << 16), __uint_as_float(wb.w & 0xffff0000u)}; }
;                     else { b0 = *(const f32x4*)((const float*)base + p); b1 = *(const f32x4*)((const float*)base + p + 4); }
;                     const f32x4 v0 = b0 + acc[ai][bj][m][0] * csv[bj][0], v1 = b1 + acc[ai][bj][m][1] * csv[bj][1];
;                     if constexpr (HAS_OUT) { *(f32x4*)(out + p) = v0; *(f32x4*)(out + p + 4) = v1; }
;                     if constexpr (HAS_XB) { u32x4 w; w.x = cvt_pk_bf16(v0[0], v0[1]); w.y = cvt_pk_bf16(v0[2], v0[3]); w.z = cvt_pk_bf16(v1[0], v1[1]); w.w = cvt_pk_bf16(v1[2], v1[3]); *(u32x4*)(xb + p) = w; }
;                     sq += ((v0[0] * v0[0] + v0[1] * v0[1]) + (v0[2] * v0[2] + v0[3] * v0[3])) + ((v1[0] * v1[0] + v1[1] * v1[1]) + (v1[2] * v1[2] + v1[3] * v1[3])); }
;                 if constexpr (HAS_SS) { sq += xor_get<16>(sq); sq = xor32_sum(sq); if (fq == 0) ss_add(ss + row, sq); } }
.LBB0_353:
	s_lshl_b32 s36, s69, 8
	s_add_i32 s36, s36, s58
	v_mbcnt_lo_u32_b32 v142, -1, 0
	v_mbcnt_hi_u32_b32 v142, -1, v142
	s_nop 0
	v_bfe_u32 v162, v142, 4, 2
	v_and_or_b32 v144, v142, 15, s36
	s_lshl_b32 s36, s68, 8
	v_lshl_or_b32 v142, v162, 3, s36
	v_or_b32_e32 v142, s59, v142
	v_ashrrev_i32_e32 v145, 31, v144
	v_ashrrev_i32_e32 v143, 31, v142
	v_lshlrev_b64 v[150:151], 11, v[144:145]
	v_lshl_add_u64 v[158:159], v[150:151], 0, v[142:143]
	v_lshl_add_u64 v[160:161], v[158:159], 2, s[52:53]
	s_mov_b32 s101, 0
	global_load_dwordx4 v[164:167], v[160:161], off
	global_load_dwordx4 v[168:171], v[160:161], off offset:16
	global_load_dwordx4 v[172:175], v[160:161], off offset:512
	global_load_dwordx4 v[176:179], v[160:161], off offset:528
	s_mov_b32 s100, 0x20000
	v_lshl_add_u64 v[252:253], v[160:161], 0, s[100:101]
	global_load_dwordx4 v[180:183], v[252:253], off
	global_load_dwordx4 v[184:187], v[252:253], off offset:16
	global_load_dwordx4 v[188:191], v[252:253], off offset:512
	global_load_dwordx4 v[192:195], v[252:253], off offset:528
	s_mov_b32 s100, 0x40000
	v_lshl_add_u64 v[252:253], v[160:161], 0, s[100:101]
	global_load_dwordx4 v[196:199], v[252:253], off
	global_load_dwordx4 v[200:203], v[252:253], off offset:16
	global_load_dwordx4 v[204:207], v[252:253], off offset:512
	global_load_dwordx4 v[208:211], v[252:253], off offset:528
	s_mov_b32 s100, 0x60000
	v_lshl_add_u64 v[252:253], v[160:161], 0, s[100:101]
	global_load_dwordx4 v[212:215], v[252:253], off
	global_load_dwordx4 v[216:219], v[252:253], off offset:16
	global_load_dwordx4 v[220:223], v[252:253], off offset:512
	global_load_dwordx4 v[224:227], v[252:253], off offset:528
	s_mov_b32 s100, 0x100000
	v_lshl_add_u64 v[252:253], v[160:161], 0, s[100:101]
	global_load_dwordx4 v[228:231], v[252:253], off
	global_load_dwordx4 v[232:235], v[252:253], off offset:16
	global_load_dwordx4 v[236:239], v[252:253], off offset:512
	global_load_dwordx4 v[240:243], v[252:253], off offset:528
	v_lshl_add_u64 v[158:159], v[158:159], 1, s[26:27]
	v_cmp_eq_u32_e32 vcc, 0, v162
	s_waitcnt vmcnt(16)
	s_nop 1
	v_mov_b64_e32 v[150:151], v[164:165]
	v_mov_b64_e32 v[152:153], v[166:167]
	v_mov_b64_e32 v[154:155], v[168:169]
	v_mov_b64_e32 v[156:157], v[170:171]
	v_pk_fma_f32 v[152:153], v[126:127], 0.5, v[152:153] op_sel_hi:[1,0,1]
	v_pk_fma_f32 v[150:151], v[124:125], 0.5, v[150:151] op_sel_hi:[1,0,1]
	v_pk_fma_f32 v[156:157], v[122:123], 0.5, v[156:157] op_sel_hi:[1,0,1]
	v_pk_fma_f32 v[154:155], v[120:121], 0.5, v[154:155] op_sel_hi:[1,0,1]
	v_cvt_pk_bf16_f32 v120, v150, v151
	v_cvt_pk_bf16_f32 v121, v152, v153
	v_mul_f32_e32 v151, v151, v151
	v_cvt_pk_bf16_f32 v122, v154, v155
	v_cvt_pk_bf16_f32 v123, v156, v157
	global_store_dwordx4 v[158:159], v[120:123], off
	s_nop 0
	v_mul_f32_e32 v153, v153, v153
	v_mul_f32_e32 v155, v155, v155
	v_mul_f32_e32 v157, v157, v157
	v_fmac_f32_e32 v151, v150, v150
	v_fmac_f32_e32 v153, v152, v152
	v_fmac_f32_e32 v155, v154, v154
	v_fmac_f32_e32 v157, v156, v156
	v_add_f32_e32 v150, v151, v153
	v_add_f32_e32 v151, v155, v157
	v_add_f32_e32 v150, v150, v151
	s_nop 1
	v_mov_b64_e32 v[120:121], v[172:173]
	v_mov_b64_e32 v[122:123], v[174:175]
	v_mov_b64_e32 v[124:125], v[176:177]
	v_mov_b64_e32 v[126:127], v[178:179]
	v_pk_fma_f32 v[118:119], v[118:119], 0.5, v[122:123] op_sel_hi:[1,0,1]
	v_pk_fma_f32 v[116:117], v[116:117], 0.5, v[120:121] op_sel_hi:[1,0,1]
	v_pk_fma_f32 v[120:121], v[114:115], 0.5, v[126:127] op_sel_hi:[1,0,1]
	v_pk_fma_f32 v[114:115], v[112:113], 0.5, v[124:125] op_sel_hi:[1,0,1]
	v_cvt_pk_bf16_f32 v112, v116, v117
	v_mul_f32_e32 v113, v117, v117
	v_mul_f32_e32 v117, v119, v119
	v_mul_f32_e32 v122, v115, v115
	v_mul_f32_e32 v123, v121, v121
	v_fmac_f32_e32 v113, v116, v116
	v_fmac_f32_e32 v117, v118, v118
	v_fmac_f32_e32 v122, v114, v114
	v_fmac_f32_e32 v123, v120, v120
	v_add_f32_e32 v113, v113, v117
	v_add_f32_e32 v116, v122, v123
	v_add_f32_e32 v113, v113, v116
	v_add_f32_e32 v116, v150, v113
	ds_swizzle_b32 v117, v116 offset:swizzle(SWAP,16)
	v_cvt_pk_bf16_f32 v113, v118, v119
	v_cvt_pk_bf16_f32 v114, v114, v115
	v_cvt_pk_bf16_f32 v115, v120, v121
	global_store_dwordx4 v[158:159], v[112:115], off offset:256
	s_waitcnt lgkmcnt(0)
	s_nop 0
	v_add_f32_e32 v112, v116, v117
	v_mov_b32_e32 v113, v112
	s_nop 1
	v_permlane32_swap_b32_e32 v112, v113
	s_and_saveexec_b64 s[36:37], vcc
	s_cbranch_execz .LBB0_355
	v_add_f32_e32 v112, v112, v113
	v_mul_f32_e32 v112, 0x49800000, v112
	v_trunc_f32_e32 v112, v112
	v_mul_f32_e32 v113, 0x2f800000, v112
	v_floor_f32_e32 v113, v113
	v_fmac_f32_e32 v112, 0xcf800000, v113
	v_cvt_u32_f32_e32 v112, v112
	v_cvt_u32_f32_e32 v113, v113
	v_lshl_add_u64 v[114:115], v[144:145], 3, s[38:39]
	global_atomic_add_x2 v[114:115], v[112:113], off
; template <int MASK> __device__ __forceinline__ float xor_get(float v) { return __int_as_float(__builtin_amdgcn_ds_swizzle(__float_as_int(v), 0x1F | (MASK << 10))); }
; __device__ __forceinline__ float xor32_sum(float v) { auto rr = __builtin_amdgcn_permlane32_swap(__float_as_uint(v), __float_as_uint(v), false, false); return __uint_as_float(rr[0]) + __uint_as_float(rr[1]); }
; __device__ __forceinline__ void ss_add(u64* p, float v) { atomicAdd(p, (u64)(v * SSFIX)); }
; __device__ __forceinline__ unsigned cvt_pk_bf16(float lo, float hi) { unsigned r; asm volatile("v_cvt_pk_bf16_f32 %0, %1, %2" : "=v"(r) : "v"(lo), "v"(hi)); return r; }
;     __device__ __forceinline__ void operator()(const f32x4 (&acc)[2][2][4][2], const Unit& u, int wr, int wc, int fr, int fq) const {
;     ...
;             for (int m = 0; m < 4; ++m) { const int row = row0 + ai * HALF + m * 16; const size_t off = (size_t)row * ldc + col0; float sq = 0.f;
; #pragma unroll
;                 for (int bj = 0; bj < 2; ++bj) { const size_t p = off + bj * HALF; f32x4 b0, b1;
;                     if constexpr (BASE16) { const u32x4 wb = *(const u32x4*)((const bf16_t*)base + p);
;                         b0 = (f32x4){__uint_as_float(wb.x << 16), __uint_as_float(wb.x & 0xffff0000u), __uint_as_float(wb.y << 16), __uint_as_float(wb.y & 0xffff0000u)};
;                         b1 = (f32x4){__uint_as_float(wb.z << 16), __uint_as_float(wb.z & 0xffff0000u), __uint_as_float(wb.w << 16), __uint_as_float(wb.w & 0xffff0000u)}; }
;                     else { b0 = *(const f32x4*)((const float*)base + p); b1 = *(const f32x4*)((const float*)base + p + 4); }
;                     const f32x4 v0 = b0 + acc[ai][bj][m][0] * csv[bj][0], v1 = b1 + acc[ai][bj][m][1] * csv[bj][1];
;                     if constexpr (HAS_OUT) { *(f32x4*)(out + p) = v0; *(f32x4*)(out + p + 4) = v1; }
;                     if constexpr (HAS_XB) { u32x4 w; w.x = cvt_pk_bf16(v0[0], v0[1]); w.y = cvt_pk_bf16(v0[2], v0[3]); w.z = cvt_pk_bf16(v1[0], v1[1]); w.w = cvt_pk_bf16(v1[2], v1[3]); *(u32x4*)(xb + p) = w; }
;                     sq += ((v0[0] * v0[0] + v0[1] * v0[1]) + (v0[2] * v0[2] + v0[3] * v0[3])) + ((v1[0] * v1[0] + v1[1] * v1[1]) + (v1[2] * v1[2] + v1[3] * v1[3])); }
;                 if constexpr (HAS_SS) { sq += xor_get<16>(sq); sq = xor32_sum(sq); if (fq == 0) ss_add(ss + row, sq); } }
.LBB0_355:
	s_or_b64 exec, exec, s[36:37]
	v_or_b32_e32 v112, 16, v144
	v_ashrrev_i32_e32 v113, 31, v112
	v_lshlrev_b64 v[114:115], 11, v[112:113]
	v_lshl_add_u64 v[122:123], v[114:115], 0, v[142:143]
	v_lshl_add_u64 v[124:125], v[122:123], 2, s[52:53]
	v_lshl_add_u64 v[122:123], v[122:123], 1, s[26:27]
	s_mov_b32 s100, 0x120000
	v_lshl_add_u64 v[252:253], v[160:161], 0, s[100:101]
	global_load_dwordx4 v[164:167], v[252:253], off
	global_load_dwordx4 v[168:171], v[252:253], off offset:16
	global_load_dwordx4 v[172:175], v[252:253], off offset:512
	global_load_dwordx4 v[176:179], v[252:253], off offset:528
	s_waitcnt vmcnt(19)
	s_nop 1
	v_mov_b64_e32 v[114:115], v[180:181]
	v_mov_b64_e32 v[116:117], v[182:183]
	v_mov_b64_e32 v[118:119], v[184:185]
	v_mov_b64_e32 v[120:121], v[186:187]
	v_pk_fma_f32 v[116:117], v[110:111], 0.5, v[116:117] op_sel_hi:[1,0,1]
	v_pk_fma_f32 v[114:115], v[108:109], 0.5, v[114:115] op_sel_hi:[1,0,1]
	v_pk_fma_f32 v[120:121], v[106:107], 0.5, v[120:121] op_sel_hi:[1,0,1]
	v_pk_fma_f32 v[118:119], v[104:105], 0.5, v[118:119] op_sel_hi:[1,0,1]
	v_cvt_pk_bf16_f32 v104, v114, v115
	v_cvt_pk_bf16_f32 v105, v116, v117
	v_mul_f32_e32 v115, v115, v115
	v_cvt_pk_bf16_f32 v106, v118, v119
	v_cvt_pk_bf16_f32 v107, v120, v121
	global_store_dwordx4 v[122:123], v[104:107], off
	s_nop 0
	v_mul_f32_e32 v117, v117, v117
	v_mul_f32_e32 v119, v119, v119
	v_mul_f32_e32 v121, v121, v121
	v_fmac_f32_e32 v115, v114, v114
	v_fmac_f32_e32 v117, v116, v116
	v_fmac_f32_e32 v119, v118, v118
	v_fmac_f32_e32 v121, v120, v120
	v_add_f32_e32 v114, v115, v117
	v_add_f32_e32 v115, v119, v121
	v_add_f32_e32 v114, v114, v115
	s_nop 1
	v_mov_b64_e32 v[104:105], v[188:189]
	v_mov_b64_e32 v[106:107], v[190:191]
	v_mov_b64_e32 v[108:109], v[192:193]
	v_mov_b64_e32 v[110:111], v[194:195]
	v_pk_fma_f32 v[102:103], v[102:103], 0.5, v[106:107] op_sel_hi:[1,0,1]
	v_pk_fma_f32 v[100:101], v[100:101], 0.5, v[104:105] op_sel_hi:[1,0,1]
	v_pk_fma_f32 v[104:105], v[98:99], 0.5, v[110:111] op_sel_hi:[1,0,1]
	v_pk_fma_f32 v[98:99], v[96:97], 0.5, v[108:109] op_sel_hi:[1,0,1]
	v_cvt_pk_bf16_f32 v96, v100, v101
	v_mul_f32_e32 v97, v101, v101
	v_mul_f32_e32 v101, v103, v103
	v_mul_f32_e32 v106, v99, v99
	v_mul_f32_e32 v107, v105, v105
	v_fmac_f32_e32 v97, v100, v100
	v_fmac_f32_e32 v101, v102, v102
	v_fmac_f32_e32 v106, v98, v98
	v_fmac_f32_e32 v107, v104, v104
	v_add_f32_e32 v97, v97, v101
	v_add_f32_e32 v100, v106, v107
	v_add_f32_e32 v97, v97, v100
	v_add_f32_e32 v100, v114, v97
	ds_swizzle_b32 v101, v100 offset:swizzle(SWAP,16)
	v_cvt_pk_bf16_f32 v97, v102, v103
	v_cvt_pk_bf16_f32 v98, v98, v99
	v_cvt_pk_bf16_f32 v99, v104, v105
	global_store_dwordx4 v[122:123], v[96:99], off offset:256
	s_waitcnt lgkmcnt(0)
	s_nop 0
	v_add_f32_e32 v96, v100, v101
	v_mov_b32_e32 v97, v96
	s_nop 1
	v_permlane32_swap_b32_e32 v96, v97
	s_and_saveexec_b64 s[36:37], vcc
	s_cbranch_execz .LBB0_357
	v_add_f32_e32 v96, v96, v97
	v_mul_f32_e32 v96, 0x49800000, v96
	v_trunc_f32_e32 v96, v96
	v_mul_f32_e32 v97, 0x2f800000, v96
	v_floor_f32_e32 v97, v97
	v_fmac_f32_e32 v96, 0xcf800000, v97
	v_cvt_u32_f32_e32 v96, v96
	v_cvt_u32_f32_e32 v97, v97
	v_lshl_add_u64 v[98:99], v[112:113], 3, s[38:39]
	global_atomic_add_x2 v[98:99], v[96:97], off
.LBB0_357:
	s_or_b64 exec, exec, s[36:37]
	v_or_b32_e32 v96, 32, v144
	v_ashrrev_i32_e32 v97, 31, v96
	v_lshlrev_b64 v[98:99], 11, v[96:97]
	v_lshl_add_u64 v[106:107], v[98:99], 0, v[142:143]
	v_lshl_add_u64 v[108:109], v[106:107], 2, s[52:53]
	v_lshl_add_u64 v[106:107], v[106:107], 1, s[26:27]
	s_mov_b32 s100, 0x140000
	v_lshl_add_u64 v[252:253], v[160:161], 0, s[100:101]
	global_load_dwordx4 v[180:183], v[252:253], off
	global_load_dwordx4 v[184:187], v[252:253], off offset:16
	global_load_dwordx4 v[188:191], v[252:253], off offset:512
	global_load_dwordx4 v[192:195], v[252:253], off offset:528
	s_waitcnt vmcnt(22)
	s_nop 1
	v_mov_b64_e32 v[98:99], v[196:197]
	v_mov_b64_e32 v[100:101], v[198:199]
	v_mov_b64_e32 v[102:103], v[200:201]
	v_mov_b64_e32 v[104:105], v[202:203]
	v_pk_fma_f32 v[100:101], v[94:95], 0.5, v[100:101] op_sel_hi:[1,0,1]
	v_pk_fma_f32 v[98:99], v[92:93], 0.5, v[98:99] op_sel_hi:[1,0,1]
	v_pk_fma_f32 v[104:105], v[90:91], 0.5, v[104:105] op_sel_hi:[1,0,1]
	v_pk_fma_f32 v[102:103], v[88:89], 0.5, v[102:103] op_sel_hi:[1,0,1]
	v_cvt_pk_bf16_f32 v88, v98, v99
	v_cvt_pk_bf16_f32 v89, v100, v101
	v_mul_f32_e32 v99, v99, v99
	v_cvt_pk_bf16_f32 v90, v102, v103
	v_cvt_pk_bf16_f32 v91, v104, v105
	global_store_dwordx4 v[106:107], v[88:91], off
	s_nop 0
	v_mul_f32_e32 v101, v101, v101
	v_mul_f32_e32 v103, v103, v103
	v_mul_f32_e32 v105, v105, v105
	v_fmac_f32_e32 v99, v98, v98
	v_fmac_f32_e32 v101, v100, v100
	v_fmac_f32_e32 v103, v102, v102
	v_fmac_f32_e32 v105, v104, v104
	v_add_f32_e32 v98, v99, v101
	v_add_f32_e32 v99, v103, v105
	v_add_f32_e32 v98, v98, v99
	s_nop 1
	v_mov_b64_e32 v[88:89], v[204:205]
	v_mov_b64_e32 v[90:91], v[206:207]
	v_mov_b64_e32 v[92:93], v[208:209]
	v_mov_b64_e32 v[94:95], v[210:211]
	v_pk_fma_f32 v[86:87], v[86:87], 0.5, v[90:91] op_sel_hi:[1,0,1]
	v_pk_fma_f32 v[84:85], v[84:85], 0.5, v[88:89] op_sel_hi:[1,0,1]
	v_pk_fma_f32 v[88:89], v[82:83], 0.5, v[94:95] op_sel_hi:[1,0,1]
	v_pk_fma_f32 v[82:83], v[80:81], 0.5, v[92:93] op_sel_hi:[1,0,1]
	v_cvt_pk_bf16_f32 v80, v84, v85
	v_mul_f32_e32 v81, v85, v85
	v_mul_f32_e32 v85, v87, v87
	v_mul_f32_e32 v90, v83, v83
	v_mul_f32_e32 v91, v89, v89
	v_fmac_f32_e32 v81, v84, v84
	v_fmac_f32_e32 v85, v86, v86
	v_fmac_f32_e32 v90, v82, v82
	v_fmac_f32_e32 v91, v88, v88
	v_add_f32_e32 v81, v81, v85
	v_add_f32_e32 v84, v90, v91
	v_add_f32_e32 v81, v81, v84
	v_add_f32_e32 v84, v98, v81
	ds_swizzle_b32 v85, v84 offset:swizzle(SWAP,16)
	v_cvt_pk_bf16_f32 v81, v86, v87
	v_cvt_pk_bf16_f32 v82, v82, v83
	v_cvt_pk_bf16_f32 v83, v88, v89
	global_store_dwordx4 v[106:107], v[80:83], off offset:256
	s_waitcnt lgkmcnt(0)
	s_nop 0
	v_add_f32_e32 v80, v84, v85
	v_mov_b32_e32 v81, v80
	s_nop 1
	v_permlane32_swap_b32_e32 v80, v81
	s_and_saveexec_b64 s[36:37], vcc
	s_cbranch_execz .LBB0_359
	v_add_f32_e32 v80, v80, v81
	v_mul_f32_e32 v80, 0x49800000, v80
	v_trunc_f32_e32 v80, v80
	v_mul_f32_e32 v81, 0x2f800000, v80
	v_floor_f32_e32 v81, v81
	v_fmac_f32_e32 v80, 0xcf800000, v81
	v_cvt_u32_f32_e32 v80, v80
	v_cvt_u32_f32_e32 v81, v81
	v_lshl_add_u64 v[82:83], v[96:97], 3, s[38:39]
	global_atomic_add_x2 v[82:83], v[80:81], off
; template <int MASK> __device__ __forceinline__ float xor_get(float v) { return __int_as_float(__builtin_amdgcn_ds_swizzle(__float_as_int(v), 0x1F | (MASK << 10))); }
; __device__ __forceinline__ float xor32_sum(float v) { auto rr = __builtin_amdgcn_permlane32_swap(__float_as_uint(v), __float_as_uint(v), false, false); return __uint_as_float(rr[0]) + __uint_as_float(rr[1]); }
; __device__ __forceinline__ void ss_add(u64* p, float v) { atomicAdd(p, (u64)(v * SSFIX)); }
; __device__ __forceinline__ unsigned cvt_pk_bf16(float lo, float hi) { unsigned r; asm volatile("v_cvt_pk_bf16_f32 %0, %1, %2" : "=v"(r) : "v"(lo), "v"(hi)); return r; }
;     __device__ __forceinline__ void operator()(const f32x4 (&acc)[2][2][4][2], const Unit& u, int wr, int wc, int fr, int fq) const {
;     ...
;             for (int m = 0; m < 4; ++m) { const int row = row0 + ai * HALF + m * 16; const size_t off = (size_t)row * ldc + col0; float sq = 0.f;
; #pragma unroll
;                 for (int bj = 0; bj < 2; ++bj) { const size_t p = off + bj * HALF; f32x4 b0, b1;
;                     if constexpr (BASE16) { const u32x4 wb = *(const u32x4*)((const bf16_t*)base + p);
;                         b0 = (f32x4){__uint_as_float(wb.x << 16), __uint_as_float(wb.x & 0xffff0000u), __uint_as_float(wb.y << 16), __uint_as_float(wb.y & 0xffff0000u)};
;                         b1 = (f32x4){__uint_as_float(wb.z << 16), __uint_as_float(wb.z & 0xffff0000u), __uint_as_float(wb.w << 16), __uint_as_float(wb.w & 0xffff0000u)}; }
;                     else { b0 = *(const f32x4*)((const float*)base + p); b1 = *(const f32x4*)((const float*)base + p + 4); }
;                     const f32x4 v0 = b0 + acc[ai][bj][m][0] * csv[bj][0], v1 = b1 + acc[ai][bj][m][1] * csv[bj][1];
;                     if constexpr (HAS_OUT) { *(f32x4*)(out + p) = v0; *(f32x4*)(out + p + 4) = v1; }
;                     if constexpr (HAS_XB) { u32x4 w; w.x = cvt_pk_bf16(v0[0], v0[1]); w.y = cvt_pk_bf16(v0[2], v0[3]); w.z = cvt_pk_bf16(v1[0], v1[1]); w.w = cvt_pk_bf16(v1[2], v1[3]); *(u32x4*)(xb + p) = w; }
;                     sq += ((v0[0] * v0[0] + v0[1] * v0[1]) + (v0[2] * v0[2] + v0[3] * v0[3])) + ((v1[0] * v1[0] + v1[1] * v1[1]) + (v1[2] * v1[2] + v1[3] * v1[3])); }
;                 if constexpr (HAS_SS) { sq += xor_get<16>(sq); sq = xor32_sum(sq); if (fq == 0) ss_add(ss + row, sq); } }
.LBB0_359:
	s_or_b64 exec, exec, s[36:37]
	v_or_b32_e32 v80, 48, v144
	v_ashrrev_i32_e32 v81, 31, v80
	v_lshlrev_b64 v[82:83], 11, v[80:81]
	v_lshl_add_u64 v[90:91], v[82:83], 0, v[142:143]
	v_lshl_add_u64 v[92:93], v[90:91], 2, s[52:53]
	v_lshl_add_u64 v[90:91], v[90:91], 1, s[26:27]
	s_mov_b32 s100, 0x160000
	v_lshl_add_u64 v[252:253], v[160:161], 0, s[100:101]
	global_load_dwordx4 v[196:199], v[252:253], off
	global_load_dwordx4 v[200:203], v[252:253], off offset:16
	global_load_dwordx4 v[204:207], v[252:253], off offset:512
	global_load_dwordx4 v[208:211], v[252:253], off offset:528
	s_waitcnt vmcnt(25)
	s_nop 1
	v_mov_b64_e32 v[82:83], v[212:213]
	v_mov_b64_e32 v[84:85], v[214:215]
	v_mov_b64_e32 v[86:87], v[216:217]
	v_mov_b64_e32 v[88:89], v[218:219]
	v_pk_fma_f32 v[84:85], v[78:79], 0.5, v[84:85] op_sel_hi:[1,0,1]
	v_pk_fma_f32 v[82:83], v[76:77], 0.5, v[82:83] op_sel_hi:[1,0,1]
	v_pk_fma_f32 v[88:89], v[74:75], 0.5, v[88:89] op_sel_hi:[1,0,1]
	v_pk_fma_f32 v[86:87], v[72:73], 0.5, v[86:87] op_sel_hi:[1,0,1]
	v_cvt_pk_bf16_f32 v72, v82, v83
	v_cvt_pk_bf16_f32 v73, v84, v85
	v_mul_f32_e32 v83, v83, v83
	v_cvt_pk_bf16_f32 v74, v86, v87
	v_cvt_pk_bf16_f32 v75, v88, v89
	global_store_dwordx4 v[90:91], v[72:75], off
	s_nop 0
	v_mul_f32_e32 v85, v85, v85
	v_mul_f32_e32 v87, v87, v87
	v_mul_f32_e32 v89, v89, v89
	v_fmac_f32_e32 v83, v82, v82
	v_fmac_f32_e32 v85, v84, v84
	v_fmac_f32_e32 v87, v86, v86
	v_fmac_f32_e32 v89, v88, v88
	v_add_f32_e32 v82, v83, v85
	v_add_f32_e32 v83, v87, v89
	v_add_f32_e32 v82, v82, v83
	s_nop 1
	v_mov_b64_e32 v[72:73], v[220:221]
	v_mov_b64_e32 v[74:75], v[222:223]
	v_mov_b64_e32 v[76:77], v[224:225]
	v_mov_b64_e32 v[78:79], v[226:227]
	v_pk_fma_f32 v[70:71], v[70:71], 0.5, v[74:75] op_sel_hi:[1,0,1]
	v_pk_fma_f32 v[68:69], v[68:69], 0.5, v[72:73] op_sel_hi:[1,0,1]
	v_pk_fma_f32 v[72:73], v[66:67], 0.5, v[78:79] op_sel_hi:[1,0,1]
	v_pk_fma_f32 v[66:67], v[64:65], 0.5, v[76:77] op_sel_hi:[1,0,1]
	v_cvt_pk_bf16_f32 v64, v68, v69
	v_mul_f32_e32 v65, v69, v69
	v_mul_f32_e32 v69, v71, v71
	v_mul_f32_e32 v74, v67, v67
	v_mul_f32_e32 v75, v73, v73
	v_fmac_f32_e32 v65, v68, v68
	v_fmac_f32_e32 v69, v70, v70
	v_fmac_f32_e32 v74, v66, v66
	v_fmac_f32_e32 v75, v72, v72
	v_add_f32_e32 v65, v65, v69
	v_add_f32_e32 v68, v74, v75
	v_add_f32_e32 v65, v65, v68
	v_add_f32_e32 v68, v82, v65
	ds_swizzle_b32 v69, v68 offset:swizzle(SWAP,16)
	v_cvt_pk_bf16_f32 v65, v70, v71
	v_cvt_pk_bf16_f32 v66, v66, v67
	v_cvt_pk_bf16_f32 v67, v72, v73
	global_store_dwordx4 v[90:91], v[64:67], off offset:256
	s_waitcnt lgkmcnt(0)
	s_nop 0
	v_add_f32_e32 v64, v68, v69
	v_mov_b32_e32 v65, v64
	s_nop 1
	v_permlane32_swap_b32_e32 v64, v65
	s_and_saveexec_b64 s[36:37], vcc
	s_cbranch_execz .LBB0_361
	v_add_f32_e32 v64, v64, v65
	v_mul_f32_e32 v64, 0x49800000, v64
	v_trunc_f32_e32 v64, v64
	v_mul_f32_e32 v65, 0x2f800000, v64
	v_floor_f32_e32 v65, v65
	v_fmac_f32_e32 v64, 0xcf800000, v65
	v_cvt_u32_f32_e32 v64, v64
	v_cvt_u32_f32_e32 v65, v65
	v_lshl_add_u64 v[66:67], v[80:81], 3, s[38:39]
	global_atomic_add_x2 v[66:67], v[64:65], off
.LBB0_361:
	s_or_b64 exec, exec, s[36:37]
	v_add_u32_e32 v64, 0x80, v144
	v_ashrrev_i32_e32 v65, 31, v64
	v_lshlrev_b64 v[66:67], 11, v[64:65]
	v_lshl_add_u64 v[74:75], v[66:67], 0, v[142:143]
	v_lshl_add_u64 v[76:77], v[74:75], 2, s[52:53]
	v_lshl_add_u64 v[74:75], v[74:75], 1, s[26:27]
	s_waitcnt vmcnt(24)
	s_nop 1
	v_mov_b64_e32 v[66:67], v[228:229]
	v_mov_b64_e32 v[68:69], v[230:231]
	v_mov_b64_e32 v[70:71], v[232:233]
	v_mov_b64_e32 v[72:73], v[234:235]
	v_pk_fma_f32 v[68:69], v[62:63], 0.5, v[68:69] op_sel_hi:[1,0,1]
	v_pk_fma_f32 v[66:67], v[60:61], 0.5, v[66:67] op_sel_hi:[1,0,1]
	v_pk_fma_f32 v[72:73], v[58:59], 0.5, v[72:73] op_sel_hi:[1,0,1]
	v_pk_fma_f32 v[70:71], v[56:57], 0.5, v[70:71] op_sel_hi:[1,0,1]
	v_cvt_pk_bf16_f32 v56, v66, v67
	v_cvt_pk_bf16_f32 v57, v68, v69
	v_mul_f32_e32 v67, v67, v67
	v_cvt_pk_bf16_f32 v58, v70, v71
	v_cvt_pk_bf16_f32 v59, v72, v73
	global_store_dwordx4 v[74:75], v[56:59], off
	s_nop 0
	v_mul_f32_e32 v69, v69, v69
	v_mul_f32_e32 v71, v71, v71
	v_mul_f32_e32 v73, v73, v73
	v_fmac_f32_e32 v67, v66, v66
	v_fmac_f32_e32 v69, v68, v68
	v_fmac_f32_e32 v71, v70, v70
	v_fmac_f32_e32 v73, v72, v72
	v_add_f32_e32 v66, v67, v69
	v_add_f32_e32 v67, v71, v73
	v_add_f32_e32 v66, v66, v67
	s_nop 1
	v_mov_b64_e32 v[56:57], v[236:237]
	v_mov_b64_e32 v[58:59], v[238:239]
	v_mov_b64_e32 v[60:61], v[240:241]
	v_mov_b64_e32 v[62:63], v[242:243]
	v_pk_fma_f32 v[54:55], v[54:55], 0.5, v[58:59] op_sel_hi:[1,0,1]
	v_pk_fma_f32 v[52:53], v[52:53], 0.5, v[56:57] op_sel_hi:[1,0,1]
	v_pk_fma_f32 v[56:57], v[50:51], 0.5, v[62:63] op_sel_hi:[1,0,1]
	v_pk_fma_f32 v[50:51], v[48:49], 0.5, v[60:61] op_sel_hi:[1,0,1]
	v_cvt_pk_bf16_f32 v48, v52, v53
	v_mul_f32_e32 v49, v53, v53
	v_mul_f32_e32 v53, v55, v55
	v_mul_f32_e32 v58, v51, v51
	v_mul_f32_e32 v59, v57, v57
	v_fmac_f32_e32 v49, v52, v52
	v_fmac_f32_e32 v53, v54, v54
	v_fmac_f32_e32 v58, v50, v50
	v_fmac_f32_e32 v59, v56, v56
	v_add_f32_e32 v49, v49, v53
	v_add_f32_e32 v52, v58, v59
	v_add_f32_e32 v49, v49, v52
	v_add_f32_e32 v52, v66, v49
	ds_swizzle_b32 v53, v52 offset:swizzle(SWAP,16)
	v_cvt_pk_bf16_f32 v49, v54, v55
	v_cvt_pk_bf16_f32 v50, v50, v51
	v_cvt_pk_bf16_f32 v51, v56, v57
	global_store_dwordx4 v[74:75], v[48:51], off offset:256
	s_waitcnt lgkmcnt(0)
	s_nop 0
	v_add_f32_e32 v48, v52, v53
	v_mov_b32_e32 v49, v48
	s_nop 1
	v_permlane32_swap_b32_e32 v48, v49
	s_and_saveexec_b64 s[36:37], vcc
	s_cbranch_execz .LBB0_363
	v_add_f32_e32 v48, v48, v49
	v_mul_f32_e32 v48, 0x49800000, v48
	v_trunc_f32_e32 v48, v48
	v_mul_f32_e32 v49, 0x2f800000, v48
	v_floor_f32_e32 v49, v49
	v_fmac_f32_e32 v48, 0xcf800000, v49
	v_cvt_u32_f32_e32 v48, v48
	v_cvt_u32_f32_e32 v49, v49
	v_lshl_add_u64 v[50:51], v[64:65], 3, s[38:39]
	global_atomic_add_x2 v[50:51], v[48:49], off
; template <int MASK> __device__ __forceinline__ float xor_get(float v) { return __int_as_float(__builtin_amdgcn_ds_swizzle(__float_as_int(v), 0x1F | (MASK << 10))); }
; __device__ __forceinline__ float xor32_sum(float v) { auto rr = __builtin_amdgcn_permlane32_swap(__float_as_uint(v), __float_as_uint(v), false, false); return __uint_as_float(rr[0]) + __uint_as_float(rr[1]); }
; __device__ __forceinline__ void ss_add(u64* p, float v) { atomicAdd(p, (u64)(v * SSFIX)); }
; __device__ __forceinline__ unsigned cvt_pk_bf16(float lo, float hi) { unsigned r; asm volatile("v_cvt_pk_bf16_f32 %0, %1, %2" : "=v"(r) : "v"(lo), "v"(hi)); return r; }
;     __device__ __forceinline__ void operator()(const f32x4 (&acc)[2][2][4][2], const Unit& u, int wr, int wc, int fr, int fq) const {
;     ...
;             for (int m = 0; m < 4; ++m) { const int row = row0 + ai * HALF + m * 16; const size_t off = (size_t)row * ldc + col0; float sq = 0.f;
; #pragma unroll
;                 for (int bj = 0; bj < 2; ++bj) { const size_t p = off + bj * HALF; f32x4 b0, b1;
;                     if constexpr (BASE16) { const u32x4 wb = *(const u32x4*)((const bf16_t*)base + p);
;                         b0 = (f32x4){__uint_as_float(wb.x << 16), __uint_as_float(wb.x & 0xffff0000u), __uint_as_float(wb.y << 16), __uint_as_float(wb.y & 0xffff0000u)};
;                         b1 = (f32x4){__uint_as_float(wb.z << 16), __uint_as_float(wb.z & 0xffff0000u), __uint_as_float(wb.w << 16), __uint_as_float(wb.w & 0xffff0000u)}; }
;                     else { b0 = *(const f32x4*)((const float*)base + p); b1 = *(const f32x4*)((const float*)base + p + 4); }
;                     const f32x4 v0 = b0 + acc[ai][bj][m][0] * csv[bj][0], v1 = b1 + acc[ai][bj][m][1] * csv[bj][1];
;                     if constexpr (HAS_OUT) { *(f32x4*)(out + p) = v0; *(f32x4*)(out + p + 4) = v1; }
;                     if constexpr (HAS_XB) { u32x4 w; w.x = cvt_pk_bf16(v0[0], v0[1]); w.y = cvt_pk_bf16(v0[2], v0[3]); w.z = cvt_pk_bf16(v1[0], v1[1]); w.w = cvt_pk_bf16(v1[2], v1[3]); *(u32x4*)(xb + p) = w; }
;                     sq += ((v0[0] * v0[0] + v0[1] * v0[1]) + (v0[2] * v0[2] + v0[3] * v0[3])) + ((v1[0] * v1[0] + v1[1] * v1[1]) + (v1[2] * v1[2] + v1[3] * v1[3])); }
;                 if constexpr (HAS_SS) { sq += xor_get<16>(sq); sq = xor32_sum(sq); if (fq == 0) ss_add(ss + row, sq); } }
.LBB0_363:
	s_or_b64 exec, exec, s[36:37]
	v_add_u32_e32 v48, 0x90, v144
	v_ashrrev_i32_e32 v49, 31, v48
	v_lshlrev_b64 v[50:51], 11, v[48:49]
	v_lshl_add_u64 v[58:59], v[50:51], 0, v[142:143]
	v_lshl_add_u64 v[60:61], v[58:59], 2, s[52:53]
	v_lshl_add_u64 v[58:59], v[58:59], 1, s[26:27]
	s_waitcnt vmcnt(20)
	s_nop 1
	v_mov_b64_e32 v[50:51], v[164:165]
	v_mov_b64_e32 v[52:53], v[166:167]
	v_mov_b64_e32 v[54:55], v[168:169]
	v_mov_b64_e32 v[56:57], v[170:171]
	v_pk_fma_f32 v[52:53], v[46:47], 0.5, v[52:53] op_sel_hi:[1,0,1]
	v_pk_fma_f32 v[50:51], v[44:45], 0.5, v[50:51] op_sel_hi:[1,0,1]
	v_pk_fma_f32 v[56:57], v[42:43], 0.5, v[56:57] op_sel_hi:[1,0,1]
	v_pk_fma_f32 v[54:55], v[40:41], 0.5, v[54:55] op_sel_hi:[1,0,1]
	v_cvt_pk_bf16_f32 v40, v50, v51
	v_cvt_pk_bf16_f32 v41, v52, v53
	v_mul_f32_e32 v51, v51, v51
	v_cvt_pk_bf16_f32 v42, v54, v55
	v_cvt_pk_bf16_f32 v43, v56, v57
	global_store_dwordx4 v[58:59], v[40:43], off
	s_nop 0
	v_mul_f32_e32 v53, v53, v53
	v_mul_f32_e32 v55, v55, v55
	v_mul_f32_e32 v57, v57, v57
	v_fmac_f32_e32 v51, v50, v50
	v_fmac_f32_e32 v53, v52, v52
	v_fmac_f32_e32 v55, v54, v54
	v_fmac_f32_e32 v57, v56, v56
	v_add_f32_e32 v50, v51, v53
	v_add_f32_e32 v51, v55, v57
	v_add_f32_e32 v50, v50, v51
	s_nop 1
	v_mov_b64_e32 v[40:41], v[172:173]
	v_mov_b64_e32 v[42:43], v[174:175]
	v_mov_b64_e32 v[44:45], v[176:177]
	v_mov_b64_e32 v[46:47], v[178:179]
	v_pk_fma_f32 v[38:39], v[38:39], 0.5, v[42:43] op_sel_hi:[1,0,1]
	v_pk_fma_f32 v[36:37], v[36:37], 0.5, v[40:41] op_sel_hi:[1,0,1]
	v_pk_fma_f32 v[40:41], v[34:35], 0.5, v[46:47] op_sel_hi:[1,0,1]
	v_pk_fma_f32 v[34:35], v[32:33], 0.5, v[44:45] op_sel_hi:[1,0,1]
	v_cvt_pk_bf16_f32 v32, v36, v37
	v_mul_f32_e32 v33, v37, v37
	v_mul_f32_e32 v37, v39, v39
	v_mul_f32_e32 v42, v35, v35
	v_mul_f32_e32 v43, v41, v41
	v_fmac_f32_e32 v33, v36, v36
	v_fmac_f32_e32 v37, v38, v38
	v_fmac_f32_e32 v42, v34, v34
	v_fmac_f32_e32 v43, v40, v40
	v_add_f32_e32 v33, v33, v37
	v_add_f32_e32 v36, v42, v43
	v_add_f32_e32 v33, v33, v36
	v_add_f32_e32 v36, v50, v33
	ds_swizzle_b32 v37, v36 offset:swizzle(SWAP,16)
	v_cvt_pk_bf16_f32 v33, v38, v39
	v_cvt_pk_bf16_f32 v34, v34, v35
	v_cvt_pk_bf16_f32 v35, v40, v41
	global_store_dwordx4 v[58:59], v[32:35], off offset:256
	s_waitcnt lgkmcnt(0)
	s_nop 0
	v_add_f32_e32 v32, v36, v37
	v_mov_b32_e32 v33, v32
	s_nop 1
	v_permlane32_swap_b32_e32 v32, v33
	s_and_saveexec_b64 s[36:37], vcc
	s_cbranch_execz .LBB0_365
	v_add_f32_e32 v32, v32, v33
	v_mul_f32_e32 v32, 0x49800000, v32
	v_trunc_f32_e32 v32, v32
	v_mul_f32_e32 v33, 0x2f800000, v32
	v_floor_f32_e32 v33, v33
	v_fmac_f32_e32 v32, 0xcf800000, v33
	v_cvt_u32_f32_e32 v32, v32
	v_cvt_u32_f32_e32 v33, v33
	v_lshl_add_u64 v[34:35], v[48:49], 3, s[38:39]
	global_atomic_add_x2 v[34:35], v[32:33], off
; template <int MASK> __device__ __forceinline__ float xor_get(float v) { return __int_as_float(__builtin_amdgcn_ds_swizzle(__float_as_int(v), 0x1F | (MASK << 10))); }
; __device__ __forceinline__ float xor32_sum(float v) { auto rr = __builtin_amdgcn_permlane32_swap(__float_as_uint(v), __float_as_uint(v), false, false); return __uint_as_float(rr[0]) + __uint_as_float(rr[1]); }
; __device__ __forceinline__ void ss_add(u64* p, float v) { atomicAdd(p, (u64)(v * SSFIX)); }
; __device__ __forceinline__ unsigned cvt_pk_bf16(float lo, float hi) { unsigned r; asm volatile("v_cvt_pk_bf16_f32 %0, %1, %2" : "=v"(r) : "v"(lo), "v"(hi)); return r; }
;     __device__ __forceinline__ void operator()(const f32x4 (&acc)[2][2][4][2], const Unit& u, int wr, int wc, int fr, int fq) const {
;     ...
;             for (int m = 0; m < 4; ++m) { const int row = row0 + ai * HALF + m * 16; const size_t off = (size_t)row * ldc + col0; float sq = 0.f;
; #pragma unroll
;                 for (int bj = 0; bj < 2; ++bj) { const size_t p = off + bj * HALF; f32x4 b0, b1;
;                     if constexpr (BASE16) { const u32x4 wb = *(const u32x4*)((const bf16_t*)base + p);
;                         b0 = (f32x4){__uint_as_float(wb.x << 16), __uint_as_float(wb.x & 0xffff0000u), __uint_as_float(wb.y << 16), __uint_as_float(wb.y & 0xffff0000u)};
;                         b1 = (f32x4){__uint_as_float(wb.z << 16), __uint_as_float(wb.z & 0xffff0000u), __uint_as_float(wb.w << 16), __uint_as_float(wb.w & 0xffff0000u)}; }
;                     else { b0 = *(const f32x4*)((const float*)base + p); b1 = *(const f32x4*)((const float*)base + p + 4); }
;                     const f32x4 v0 = b0 + acc[ai][bj][m][0] * csv[bj][0], v1 = b1 + acc[ai][bj][m][1] * csv[bj][1];
;                     if constexpr (HAS_OUT) { *(f32x4*)(out + p) = v0; *(f32x4*)(out + p + 4) = v1; }
;                     if constexpr (HAS_XB) { u32x4 w; w.x = cvt_pk_bf16(v0[0], v0[1]); w.y = cvt_pk_bf16(v0[2], v0[3]); w.z = cvt_pk_bf16(v1[0], v1[1]); w.w = cvt_pk_bf16(v1[2], v1[3]); *(u32x4*)(xb + p) = w; }
;                     sq += ((v0[0] * v0[0] + v0[1] * v0[1]) + (v0[2] * v0[2] + v0[3] * v0[3])) + ((v1[0] * v1[0] + v1[1] * v1[1]) + (v1[2] * v1[2] + v1[3] * v1[3])); }
;                 if constexpr (HAS_SS) { sq += xor_get<16>(sq); sq = xor32_sum(sq); if (fq == 0) ss_add(ss + row, sq); } }
.LBB0_365:
	s_or_b64 exec, exec, s[36:37]
	v_add_u32_e32 v32, 0xa0, v144
	v_ashrrev_i32_e32 v33, 31, v32
	v_lshlrev_b64 v[34:35], 11, v[32:33]
	v_lshl_add_u64 v[42:43], v[34:35], 0, v[142:143]
	v_lshl_add_u64 v[44:45], v[42:43], 2, s[52:53]
	v_lshl_add_u64 v[42:43], v[42:43], 1, s[26:27]
	s_waitcnt vmcnt(16)
	s_nop 1
	v_mov_b64_e32 v[34:35], v[180:181]
	v_mov_b64_e32 v[36:37], v[182:183]
	v_mov_b64_e32 v[38:39], v[184:185]
	v_mov_b64_e32 v[40:41], v[186:187]
	v_pk_fma_f32 v[36:37], v[30:31], 0.5, v[36:37] op_sel_hi:[1,0,1]
	v_pk_fma_f32 v[34:35], v[28:29], 0.5, v[34:35] op_sel_hi:[1,0,1]
	v_pk_fma_f32 v[40:41], v[26:27], 0.5, v[40:41] op_sel_hi:[1,0,1]
	v_pk_fma_f32 v[38:39], v[24:25], 0.5, v[38:39] op_sel_hi:[1,0,1]
	v_cvt_pk_bf16_f32 v24, v34, v35
	v_cvt_pk_bf16_f32 v25, v36, v37
	v_mul_f32_e32 v35, v35, v35
	v_cvt_pk_bf16_f32 v26, v38, v39
	v_cvt_pk_bf16_f32 v27, v40, v41
	global_store_dwordx4 v[42:43], v[24:27], off
	s_nop 0
	v_mul_f32_e32 v37, v37, v37
	v_mul_f32_e32 v39, v39, v39
	v_mul_f32_e32 v41, v41, v41
	v_fmac_f32_e32 v35, v34, v34
	v_fmac_f32_e32 v37, v36, v36
	v_fmac_f32_e32 v39, v38, v38
	v_fmac_f32_e32 v41, v40, v40
	v_add_f32_e32 v34, v35, v37
	v_add_f32_e32 v35, v39, v41
	v_add_f32_e32 v34, v34, v35
	s_nop 1
	v_mov_b64_e32 v[24:25], v[188:189]
	v_mov_b64_e32 v[26:27], v[190:191]
	v_mov_b64_e32 v[28:29], v[192:193]
	v_mov_b64_e32 v[30:31], v[194:195]
	v_pk_fma_f32 v[22:23], v[22:23], 0.5, v[26:27] op_sel_hi:[1,0,1]
	v_pk_fma_f32 v[20:21], v[20:21], 0.5, v[24:25] op_sel_hi:[1,0,1]
	v_pk_fma_f32 v[24:25], v[18:19], 0.5, v[30:31] op_sel_hi:[1,0,1]
	v_pk_fma_f32 v[18:19], v[16:17], 0.5, v[28:29] op_sel_hi:[1,0,1]
	v_cvt_pk_bf16_f32 v16, v20, v21
	v_mul_f32_e32 v17, v21, v21
	v_mul_f32_e32 v21, v23, v23
	v_mul_f32_e32 v26, v19, v19
	v_mul_f32_e32 v27, v25, v25
	v_fmac_f32_e32 v17, v20, v20
	v_fmac_f32_e32 v21, v22, v22
	v_fmac_f32_e32 v26, v18, v18
	v_fmac_f32_e32 v27, v24, v24
	v_add_f32_e32 v17, v17, v21
	v_add_f32_e32 v20, v26, v27
	v_add_f32_e32 v17, v17, v20
	v_add_f32_e32 v20, v34, v17
	ds_swizzle_b32 v21, v20 offset:swizzle(SWAP,16)
	v_cvt_pk_bf16_f32 v17, v22, v23
	v_cvt_pk_bf16_f32 v18, v18, v19
	v_cvt_pk_bf16_f32 v19, v24, v25
	global_store_dwordx4 v[42:43], v[16:19], off offset:256
	s_waitcnt lgkmcnt(0)
	s_nop 0
	v_add_f32_e32 v16, v20, v21
	v_mov_b32_e32 v17, v16
	s_nop 1
	v_permlane32_swap_b32_e32 v16, v17
	s_and_saveexec_b64 s[36:37], vcc
	s_cbranch_execz .LBB0_367
	v_add_f32_e32 v16, v16, v17
	v_mul_f32_e32 v16, 0x49800000, v16
	v_trunc_f32_e32 v16, v16
	v_mul_f32_e32 v17, 0x2f800000, v16
	v_floor_f32_e32 v17, v17
	v_fmac_f32_e32 v16, 0xcf800000, v17
	v_cvt_u32_f32_e32 v16, v16
	v_cvt_u32_f32_e32 v17, v17
	v_lshl_add_u64 v[18:19], v[32:33], 3, s[38:39]
	global_atomic_add_x2 v[18:19], v[16:17], off
.LBB0_367:
	s_or_b64 exec, exec, s[36:37]
	v_add_u32_e32 v16, 0xb0, v144
	v_ashrrev_i32_e32 v17, 31, v16
	v_lshlrev_b64 v[18:19], 11, v[16:17]
	v_lshl_add_u64 v[26:27], v[18:19], 0, v[142:143]
	v_lshl_add_u64 v[28:29], v[26:27], 2, s[52:53]
	v_lshl_add_u64 v[26:27], v[26:27], 1, s[26:27]
	s_waitcnt vmcnt(12)
	s_nop 1
	v_mov_b64_e32 v[18:19], v[196:197]
	v_mov_b64_e32 v[20:21], v[198:199]
	v_mov_b64_e32 v[22:23], v[200:201]
	v_mov_b64_e32 v[24:25], v[202:203]
	v_pk_fma_f32 v[20:21], v[14:15], 0.5, v[20:21] op_sel_hi:[1,0,1]
	v_pk_fma_f32 v[18:19], v[12:13], 0.5, v[18:19] op_sel_hi:[1,0,1]
	v_pk_fma_f32 v[24:25], v[10:11], 0.5, v[24:25] op_sel_hi:[1,0,1]
	v_pk_fma_f32 v[22:23], v[8:9], 0.5, v[22:23] op_sel_hi:[1,0,1]
	v_cvt_pk_bf16_f32 v8, v18, v19
	v_cvt_pk_bf16_f32 v9, v20, v21
	v_mul_f32_e32 v19, v19, v19
	v_cvt_pk_bf16_f32 v10, v22, v23
	v_cvt_pk_bf16_f32 v11, v24, v25
	global_store_dwordx4 v[26:27], v[8:11], off
	s_nop 0
	v_mul_f32_e32 v21, v21, v21
	v_mul_f32_e32 v23, v23, v23
	v_mul_f32_e32 v25, v25, v25
	v_fmac_f32_e32 v19, v18, v18
	v_fmac_f32_e32 v21, v20, v20
	v_fmac_f32_e32 v23, v22, v22
	v_fmac_f32_e32 v25, v24, v24
	v_add_f32_e32 v18, v19, v21
	v_add_f32_e32 v19, v23, v25
	v_add_f32_e32 v18, v18, v19
	s_nop 1
	v_mov_b64_e32 v[8:9], v[204:205]
	v_mov_b64_e32 v[10:11], v[206:207]
	v_mov_b64_e32 v[12:13], v[208:209]
	v_mov_b64_e32 v[14:15], v[210:211]
	v_pk_fma_f32 v[6:7], v[6:7], 0.5, v[10:11] op_sel_hi:[1,0,1]
	v_pk_fma_f32 v[4:5], v[4:5], 0.5, v[8:9] op_sel_hi:[1,0,1]
	v_pk_fma_f32 v[8:9], v[2:3], 0.5, v[14:15] op_sel_hi:[1,0,1]
	v_pk_fma_f32 v[2:3], v[0:1], 0.5, v[12:13] op_sel_hi:[1,0,1]
	v_cvt_pk_bf16_f32 v0, v4, v5
	v_mul_f32_e32 v1, v5, v5
	v_mul_f32_e32 v5, v7, v7
	v_mul_f32_e32 v10, v3, v3
	v_mul_f32_e32 v11, v9, v9
	v_fmac_f32_e32 v1, v4, v4
	v_fmac_f32_e32 v5, v6, v6
	v_fmac_f32_e32 v10, v2, v2
	v_fmac_f32_e32 v11, v8, v8
	v_add_f32_e32 v1, v1, v5
	v_add_f32_e32 v4, v10, v11
	v_add_f32_e32 v1, v1, v4
	v_add_f32_e32 v4, v18, v1
	ds_swizzle_b32 v5, v4 offset:swizzle(SWAP,16)
	v_cvt_pk_bf16_f32 v1, v6, v7
	v_cvt_pk_bf16_f32 v2, v2, v3
	v_cvt_pk_bf16_f32 v3, v8, v9
	global_store_dwordx4 v[26:27], v[0:3], off offset:256
	s_waitcnt lgkmcnt(0)
	s_nop 0
	v_add_f32_e32 v0, v4, v5
	v_mov_b32_e32 v1, v0
	s_nop 1
	v_permlane32_swap_b32_e32 v0, v1
	s_and_saveexec_b64 s[36:37], vcc
	s_cbranch_execz .LBB0_369
	v_add_f32_e32 v0, v0, v1
	v_mul_f32_e32 v0, 0x49800000, v0
	v_trunc_f32_e32 v0, v0
	v_mul_f32_e32 v1, 0x2f800000, v0
	v_floor_f32_e32 v1, v1
	v_fmac_f32_e32 v0, 0xcf800000, v1
	v_cvt_u32_f32_e32 v0, v0
	v_cvt_u32_f32_e32 v1, v1
	v_lshl_add_u64 v[2:3], v[16:17], 3, s[38:39]
	global_atomic_add_x2 v[2:3], v[0:1], off

; template <int MASK> __device__ __forceinline__ float xor_get(float v) { return __int_as_float(__builtin_amdgcn_ds_swizzle(__float_as_int(v), 0x1F | (MASK << 10))); }
; __device__ __forceinline__ float xor32_sum(float v) { auto rr = __builtin_amdgcn_permlane32_swap(__float_as_uint(v), __float_as_uint(v), false, false); return __uint_as_float(rr[0]) + __uint_as_float(rr[1]); }
; __device__ __forceinline__ void ss_add(u64* p, float v) { atomicAdd(p, (u64)(v * SSFIX)); }
; __device__ __forceinline__ unsigned cvt_pk_bf16(float lo, float hi) { unsigned r; asm volatile("v_cvt_pk_bf16_f32 %0, %1, %2" : "=v"(r) : "v"(lo), "v"(hi)); return r; }
;     __device__ __forceinline__ void operator()(const f32x4 (&acc)[2][2][4][2], const Unit& u, int wr, int wc, int fr, int fq) const {
;     ...
;             for (int m = 0; m < 4; ++m) { const int row = row0 + ai * HALF + m * 16; const size_t off = (size_t)row * ldc + col0; float sq = 0.f;
; #pragma unroll
;                 for (int bj = 0; bj < 2; ++bj) { const size_t p = off + bj * HALF; f32x4 b0, b1;
;                     if constexpr (BASE16) { const u32x4 wb = *(const u32x4*)((const bf16_t*)base + p);
;                         b0 = (f32x4){__uint_as_float(wb.x << 16), __uint_as_float(wb.x & 0xffff0000u), __uint_as_float(wb.y << 16), __uint_as_float(wb.y & 0xffff0000u)};
;                         b1 = (f32x4){__uint_as_float(wb.z << 16), __uint_as_float(wb.z & 0xffff0000u), __uint_as_float(wb.w << 16), __uint_as_float(wb.w & 0xffff0000u)}; }
;                     else { b0 = *(const f32x4*)((const float*)base + p); b1 = *(const f32x4*)((const float*)base + p + 4); }
;                     const f32x4 v0 = b0 + acc[ai][bj][m][0] * csv[bj][0], v1 = b1 + acc[ai][bj][m][1] * csv[bj][1];
;                     if constexpr (HAS_OUT) { *(f32x4*)(out + p) = v0; *(f32x4*)(out + p + 4) = v1; }
;                     if constexpr (HAS_XB) { u32x4 w; w.x = cvt_pk_bf16(v0[0], v0[1]); w.y = cvt_pk_bf16(v0[2], v0[3]); w.z = cvt_pk_bf16(v1[0], v1[1]); w.w = cvt_pk_bf16(v1[2], v1[3]); *(u32x4*)(xb + p) = w; }
;                     sq += ((v0[0] * v0[0] + v0[1] * v0[1]) + (v0[2] * v0[2] + v0[3] * v0[3])) + ((v1[0] * v1[0] + v1[1] * v1[1]) + (v1[2] * v1[2] + v1[3] * v1[3])); }
;                 if constexpr (HAS_SS) { sq += xor_get<16>(sq); sq = xor32_sum(sq); if (fq == 0) ss_add(ss + row, sq); } }
.LBB0_392:
	s_lshl_b32 s42, s73, 8
	s_add_i32 s42, s42, s62
	v_mbcnt_lo_u32_b32 v142, -1, 0
	v_mbcnt_hi_u32_b32 v142, -1, v142
	s_nop 0
	v_bfe_u32 v164, v142, 4, 2
	v_and_or_b32 v144, v142, 15, s42
	s_lshl_b32 s42, s72, 8
	v_lshl_or_b32 v142, v164, 3, s42
	v_or_b32_e32 v142, s63, v142
	v_ashrrev_i32_e32 v145, 31, v144
	v_ashrrev_i32_e32 v143, 31, v142
	v_lshlrev_b64 v[150:151], 11, v[144:145]
	v_lshl_add_u64 v[158:159], v[150:151], 0, v[142:143]
	v_lshl_add_u64 v[160:161], v[158:159], 2, s[54:55]
	s_mov_b32 s101, 0
	global_load_dwordx4 v[168:171], v[160:161], off
	global_load_dwordx4 v[172:175], v[160:161], off offset:16
	global_load_dwordx4 v[176:179], v[160:161], off offset:512
	global_load_dwordx4 v[180:183], v[160:161], off offset:528
	s_mov_b32 s100, 0x20000
	v_lshl_add_u64 v[252:253], v[160:161], 0, s[100:101]
	global_load_dwordx4 v[184:187], v[252:253], off
	global_load_dwordx4 v[188:191], v[252:253], off offset:16
	global_load_dwordx4 v[192:195], v[252:253], off offset:512
	global_load_dwordx4 v[196:199], v[252:253], off offset:528
	s_mov_b32 s100, 0x40000
	v_lshl_add_u64 v[252:253], v[160:161], 0, s[100:101]
	global_load_dwordx4 v[200:203], v[252:253], off
	global_load_dwordx4 v[204:207], v[252:253], off offset:16
	global_load_dwordx4 v[208:211], v[252:253], off offset:512
	global_load_dwordx4 v[212:215], v[252:253], off offset:528
	s_mov_b32 s100, 0x60000
	v_lshl_add_u64 v[252:253], v[160:161], 0, s[100:101]
	global_load_dwordx4 v[216:219], v[252:253], off
	global_load_dwordx4 v[220:223], v[252:253], off offset:16
	global_load_dwordx4 v[224:227], v[252:253], off offset:512
	global_load_dwordx4 v[228:231], v[252:253], off offset:528
	s_mov_b32 s100, 0x100000
	v_lshl_add_u64 v[252:253], v[160:161], 0, s[100:101]
	global_load_dwordx4 v[232:235], v[252:253], off
	global_load_dwordx4 v[236:239], v[252:253], off offset:16
	global_load_dwordx4 v[240:243], v[252:253], off offset:512
	global_load_dwordx4 v[244:247], v[252:253], off offset:528
	v_lshlrev_b64 v[158:159], 1, v[158:159]
	v_lshl_add_u64 v[162:163], s[4:5], 0, v[158:159]
	v_or_b32_e32 v158, 0x100, v158
	v_lshl_add_u64 v[158:159], s[4:5], 0, v[158:159]
	v_cmp_eq_u32_e32 vcc, 0, v164
	s_waitcnt vmcnt(16)
	s_nop 1
	v_mov_b64_e32 v[150:151], v[168:169]
	v_mov_b64_e32 v[152:153], v[170:171]
	v_mov_b64_e32 v[154:155], v[172:173]
	v_mov_b64_e32 v[156:157], v[174:175]
	v_pk_fma_f32 v[152:153], v[126:127], 0.5, v[152:153] op_sel_hi:[1,0,1]
	v_pk_fma_f32 v[150:151], v[124:125], 0.5, v[150:151] op_sel_hi:[1,0,1]
	v_pk_fma_f32 v[156:157], v[122:123], 0.5, v[156:157] op_sel_hi:[1,0,1]
	v_pk_fma_f32 v[154:155], v[120:121], 0.5, v[154:155] op_sel_hi:[1,0,1]
	v_cvt_pk_bf16_f32 v120, v150, v151
	v_cvt_pk_bf16_f32 v121, v152, v153
	v_mul_f32_e32 v151, v151, v151
	v_cvt_pk_bf16_f32 v122, v154, v155
	v_cvt_pk_bf16_f32 v123, v156, v157
	global_store_dwordx4 v[162:163], v[120:123], off
	s_nop 0
	v_mul_f32_e32 v153, v153, v153
	v_mul_f32_e32 v155, v155, v155
	v_mul_f32_e32 v157, v157, v157
	v_fmac_f32_e32 v151, v150, v150
	v_fmac_f32_e32 v153, v152, v152
	v_fmac_f32_e32 v155, v154, v154
	v_fmac_f32_e32 v157, v156, v156
	v_add_f32_e32 v150, v151, v153
	v_add_f32_e32 v151, v155, v157
	v_add_f32_e32 v150, v150, v151
	s_nop 1
	v_mov_b64_e32 v[120:121], v[176:177]
	v_mov_b64_e32 v[122:123], v[178:179]
	v_mov_b64_e32 v[124:125], v[180:181]
	v_mov_b64_e32 v[126:127], v[182:183]
	v_pk_fma_f32 v[118:119], v[118:119], 0.5, v[122:123] op_sel_hi:[1,0,1]
	v_pk_fma_f32 v[116:117], v[116:117], 0.5, v[120:121] op_sel_hi:[1,0,1]
	v_pk_fma_f32 v[120:121], v[114:115], 0.5, v[126:127] op_sel_hi:[1,0,1]
	v_pk_fma_f32 v[114:115], v[112:113], 0.5, v[124:125] op_sel_hi:[1,0,1]
	v_cvt_pk_bf16_f32 v112, v116, v117
	v_mul_f32_e32 v113, v117, v117
	v_mul_f32_e32 v117, v119, v119
	v_mul_f32_e32 v122, v115, v115
	v_mul_f32_e32 v123, v121, v121
	v_fmac_f32_e32 v113, v116, v116
	v_fmac_f32_e32 v117, v118, v118
	v_fmac_f32_e32 v122, v114, v114
	v_fmac_f32_e32 v123, v120, v120
	v_add_f32_e32 v113, v113, v117
	v_add_f32_e32 v116, v122, v123
	v_add_f32_e32 v113, v113, v116
	v_add_f32_e32 v116, v150, v113
	ds_swizzle_b32 v117, v116 offset:swizzle(SWAP,16)
	v_cvt_pk_bf16_f32 v113, v118, v119
	v_cvt_pk_bf16_f32 v114, v114, v115
	v_cvt_pk_bf16_f32 v115, v120, v121
	global_store_dwordx4 v[158:159], v[112:115], off
	s_waitcnt lgkmcnt(0)
	s_nop 0
	v_add_f32_e32 v112, v116, v117
	v_mov_b32_e32 v113, v112
	s_nop 1
	v_permlane32_swap_b32_e32 v112, v113
	s_and_saveexec_b64 s[42:43], vcc
	s_cbranch_execz .LBB0_394
	v_add_f32_e32 v112, v112, v113
	v_mul_f32_e32 v112, 0x49800000, v112
	v_trunc_f32_e32 v112, v112
	v_mul_f32_e32 v113, 0x2f800000, v112
	v_floor_f32_e32 v113, v113
	v_fmac_f32_e32 v112, 0xcf800000, v113
	v_cvt_u32_f32_e32 v112, v112
	v_cvt_u32_f32_e32 v113, v113
	v_lshl_add_u64 v[114:115], v[144:145], 3, s[6:7]
	global_atomic_add_x2 v[114:115], v[112:113], off
; template <int MASK> __device__ __forceinline__ float xor_get(float v) { return __int_as_float(__builtin_amdgcn_ds_swizzle(__float_as_int(v), 0x1F | (MASK << 10))); }
; __device__ __forceinline__ float xor32_sum(float v) { auto rr = __builtin_amdgcn_permlane32_swap(__float_as_uint(v), __float_as_uint(v), false, false); return __uint_as_float(rr[0]) + __uint_as_float(rr[1]); }
; __device__ __forceinline__ void ss_add(u64* p, float v) { atomicAdd(p, (u64)(v * SSFIX)); }
; __device__ __forceinline__ unsigned cvt_pk_bf16(float lo, float hi) { unsigned r; asm volatile("v_cvt_pk_bf16_f32 %0, %1, %2" : "=v"(r) : "v"(lo), "v"(hi)); return r; }
;     __device__ __forceinline__ void operator()(const f32x4 (&acc)[2][2][4][2], const Unit& u, int wr, int wc, int fr, int fq) const {
;     ...
;             for (int m = 0; m < 4; ++m) { const int row = row0 + ai * HALF + m * 16; const size_t off = (size_t)row * ldc + col0; float sq = 0.f;
; #pragma unroll
;                 for (int bj = 0; bj < 2; ++bj) { const size_t p = off + bj * HALF; f32x4 b0, b1;
;                     if constexpr (BASE16) { const u32x4 wb = *(const u32x4*)((const bf16_t*)base + p);
;                         b0 = (f32x4){__uint_as_float(wb.x << 16), __uint_as_float(wb.x & 0xffff0000u), __uint_as_float(wb.y << 16), __uint_as_float(wb.y & 0xffff0000u)};
;                         b1 = (f32x4){__uint_as_float(wb.z << 16), __uint_as_float(wb.z & 0xffff0000u), __uint_as_float(wb.w << 16), __uint_as_float(wb.w & 0xffff0000u)}; }
;                     else { b0 = *(const f32x4*)((const float*)base + p); b1 = *(const f32x4*)((const float*)base + p + 4); }
;                     const f32x4 v0 = b0 + acc[ai][bj][m][0] * csv[bj][0], v1 = b1 + acc[ai][bj][m][1] * csv[bj][1];
;                     if constexpr (HAS_OUT) { *(f32x4*)(out + p) = v0; *(f32x4*)(out + p + 4) = v1; }
;                     if constexpr (HAS_XB) { u32x4 w; w.x = cvt_pk_bf16(v0[0], v0[1]); w.y = cvt_pk_bf16(v0[2], v0[3]); w.z = cvt_pk_bf16(v1[0], v1[1]); w.w = cvt_pk_bf16(v1[2], v1[3]); *(u32x4*)(xb + p) = w; }
;                     sq += ((v0[0] * v0[0] + v0[1] * v0[1]) + (v0[2] * v0[2] + v0[3] * v0[3])) + ((v1[0] * v1[0] + v1[1] * v1[1]) + (v1[2] * v1[2] + v1[3] * v1[3])); }
;                 if constexpr (HAS_SS) { sq += xor_get<16>(sq); sq = xor32_sum(sq); if (fq == 0) ss_add(ss + row, sq); } }
.LBB0_394:
	s_or_b64 exec, exec, s[42:43]
	v_or_b32_e32 v112, 16, v144
	v_ashrrev_i32_e32 v113, 31, v112
	v_lshlrev_b64 v[114:115], 11, v[112:113]
	v_lshl_add_u64 v[122:123], v[114:115], 0, v[142:143]
	v_lshl_add_u64 v[124:125], v[122:123], 2, s[54:55]
	v_lshlrev_b64 v[122:123], 1, v[122:123]
	v_lshl_add_u64 v[126:127], s[4:5], 0, v[122:123]
	v_or_b32_e32 v122, 0x100, v122
	v_lshl_add_u64 v[122:123], s[4:5], 0, v[122:123]
	s_mov_b32 s100, 0x120000
	v_lshl_add_u64 v[252:253], v[160:161], 0, s[100:101]
	global_load_dwordx4 v[168:171], v[252:253], off
	global_load_dwordx4 v[172:175], v[252:253], off offset:16
	global_load_dwordx4 v[176:179], v[252:253], off offset:512
	global_load_dwordx4 v[180:183], v[252:253], off offset:528
	s_waitcnt vmcnt(19)
	s_nop 1
	v_mov_b64_e32 v[114:115], v[184:185]
	v_mov_b64_e32 v[116:117], v[186:187]
	v_mov_b64_e32 v[118:119], v[188:189]
	v_mov_b64_e32 v[120:121], v[190:191]
	v_pk_fma_f32 v[116:117], v[110:111], 0.5, v[116:117] op_sel_hi:[1,0,1]
	v_pk_fma_f32 v[114:115], v[108:109], 0.5, v[114:115] op_sel_hi:[1,0,1]
	v_pk_fma_f32 v[120:121], v[106:107], 0.5, v[120:121] op_sel_hi:[1,0,1]
	v_pk_fma_f32 v[118:119], v[104:105], 0.5, v[118:119] op_sel_hi:[1,0,1]
	v_cvt_pk_bf16_f32 v104, v114, v115
	v_cvt_pk_bf16_f32 v105, v116, v117
	v_mul_f32_e32 v115, v115, v115
	v_cvt_pk_bf16_f32 v106, v118, v119
	v_cvt_pk_bf16_f32 v107, v120, v121
	global_store_dwordx4 v[126:127], v[104:107], off
	s_nop 0
	v_mul_f32_e32 v117, v117, v117
	v_mul_f32_e32 v119, v119, v119
	v_mul_f32_e32 v121, v121, v121
	v_fmac_f32_e32 v115, v114, v114
	v_fmac_f32_e32 v117, v116, v116
	v_fmac_f32_e32 v119, v118, v118
	v_fmac_f32_e32 v121, v120, v120
	v_add_f32_e32 v114, v115, v117
	v_add_f32_e32 v115, v119, v121
	v_add_f32_e32 v114, v114, v115
	s_nop 1
	v_mov_b64_e32 v[104:105], v[192:193]
	v_mov_b64_e32 v[106:107], v[194:195]
	v_mov_b64_e32 v[108:109], v[196:197]
	v_mov_b64_e32 v[110:111], v[198:199]
	v_pk_fma_f32 v[102:103], v[102:103], 0.5, v[106:107] op_sel_hi:[1,0,1]
	v_pk_fma_f32 v[100:101], v[100:101], 0.5, v[104:105] op_sel_hi:[1,0,1]
	v_pk_fma_f32 v[104:105], v[98:99], 0.5, v[110:111] op_sel_hi:[1,0,1]
	v_pk_fma_f32 v[98:99], v[96:97], 0.5, v[108:109] op_sel_hi:[1,0,1]
	v_cvt_pk_bf16_f32 v96, v100, v101
	v_mul_f32_e32 v97, v101, v101
	v_mul_f32_e32 v101, v103, v103
	v_mul_f32_e32 v106, v99, v99
	v_mul_f32_e32 v107, v105, v105
	v_fmac_f32_e32 v97, v100, v100
	v_fmac_f32_e32 v101, v102, v102
	v_fmac_f32_e32 v106, v98, v98
	v_fmac_f32_e32 v107, v104, v104
	v_add_f32_e32 v97, v97, v101
	v_add_f32_e32 v100, v106, v107
	v_add_f32_e32 v97, v97, v100
	v_add_f32_e32 v100, v114, v97
	ds_swizzle_b32 v101, v100 offset:swizzle(SWAP,16)
	v_cvt_pk_bf16_f32 v97, v102, v103
	v_cvt_pk_bf16_f32 v98, v98, v99
	v_cvt_pk_bf16_f32 v99, v104, v105
	global_store_dwordx4 v[122:123], v[96:99], off
	s_waitcnt lgkmcnt(0)
	s_nop 0
	v_add_f32_e32 v96, v100, v101
	v_mov_b32_e32 v97, v96
	s_nop 1
	v_permlane32_swap_b32_e32 v96, v97
	s_and_saveexec_b64 s[42:43], vcc
	s_cbranch_execz .LBB0_396
	v_add_f32_e32 v96, v96, v97
	v_mul_f32_e32 v96, 0x49800000, v96
	v_trunc_f32_e32 v96, v96
	v_mul_f32_e32 v97, 0x2f800000, v96
	v_floor_f32_e32 v97, v97
	v_fmac_f32_e32 v96, 0xcf800000, v97
	v_cvt_u32_f32_e32 v96, v96
	v_cvt_u32_f32_e32 v97, v97
	v_lshl_add_u64 v[98:99], v[112:113], 3, s[6:7]
	global_atomic_add_x2 v[98:99], v[96:97], off
.LBB0_396:
	s_or_b64 exec, exec, s[42:43]
	v_or_b32_e32 v96, 32, v144
	v_ashrrev_i32_e32 v97, 31, v96
	v_lshlrev_b64 v[98:99], 11, v[96:97]
	v_lshl_add_u64 v[106:107], v[98:99], 0, v[142:143]
	v_lshl_add_u64 v[108:109], v[106:107], 2, s[54:55]
	v_lshlrev_b64 v[106:107], 1, v[106:107]
	v_lshl_add_u64 v[110:111], s[4:5], 0, v[106:107]
	v_or_b32_e32 v106, 0x100, v106
	v_lshl_add_u64 v[106:107], s[4:5], 0, v[106:107]
	s_mov_b32 s100, 0x140000
	v_lshl_add_u64 v[252:253], v[160:161], 0, s[100:101]
	global_load_dwordx4 v[184:187], v[252:253], off
	global_load_dwordx4 v[188:191], v[252:253], off offset:16
	global_load_dwordx4 v[192:195], v[252:253], off offset:512
	global_load_dwordx4 v[196:199], v[252:253], off offset:528
	s_waitcnt vmcnt(22)
	s_nop 1
	v_mov_b64_e32 v[98:99], v[200:201]
	v_mov_b64_e32 v[100:101], v[202:203]
	v_mov_b64_e32 v[102:103], v[204:205]
	v_mov_b64_e32 v[104:105], v[206:207]
	v_pk_fma_f32 v[100:101], v[94:95], 0.5, v[100:101] op_sel_hi:[1,0,1]
	v_pk_fma_f32 v[98:99], v[92:93], 0.5, v[98:99] op_sel_hi:[1,0,1]
	v_pk_fma_f32 v[104:105], v[90:91], 0.5, v[104:105] op_sel_hi:[1,0,1]
	v_pk_fma_f32 v[102:103], v[88:89], 0.5, v[102:103] op_sel_hi:[1,0,1]
	v_cvt_pk_bf16_f32 v88, v98, v99
	v_cvt_pk_bf16_f32 v89, v100, v101
	v_mul_f32_e32 v99, v99, v99
	v_cvt_pk_bf16_f32 v90, v102, v103
	v_cvt_pk_bf16_f32 v91, v104, v105
	global_store_dwordx4 v[110:111], v[88:91], off
	s_nop 0
	v_mul_f32_e32 v101, v101, v101
	v_mul_f32_e32 v103, v103, v103
	v_mul_f32_e32 v105, v105, v105
	v_fmac_f32_e32 v99, v98, v98
	v_fmac_f32_e32 v101, v100, v100
	v_fmac_f32_e32 v103, v102, v102
	v_fmac_f32_e32 v105, v104, v104
	v_add_f32_e32 v98, v99, v101
	v_add_f32_e32 v99, v103, v105
	v_add_f32_e32 v98, v98, v99
	s_nop 1
	v_mov_b64_e32 v[88:89], v[208:209]
	v_mov_b64_e32 v[90:91], v[210:211]
	v_mov_b64_e32 v[92:93], v[212:213]
	v_mov_b64_e32 v[94:95], v[214:215]
	v_pk_fma_f32 v[86:87], v[86:87], 0.5, v[90:91] op_sel_hi:[1,0,1]
	v_pk_fma_f32 v[84:85], v[84:85], 0.5, v[88:89] op_sel_hi:[1,0,1]
	v_pk_fma_f32 v[88:89], v[82:83], 0.5, v[94:95] op_sel_hi:[1,0,1]
	v_pk_fma_f32 v[82:83], v[80:81], 0.5, v[92:93] op_sel_hi:[1,0,1]
	v_cvt_pk_bf16_f32 v80, v84, v85
	v_mul_f32_e32 v81, v85, v85
	v_mul_f32_e32 v85, v87, v87
	v_mul_f32_e32 v90, v83, v83
	v_mul_f32_e32 v91, v89, v89
	v_fmac_f32_e32 v81, v84, v84
	v_fmac_f32_e32 v85, v86, v86
	v_fmac_f32_e32 v90, v82, v82
	v_fmac_f32_e32 v91, v88, v88
	v_add_f32_e32 v81, v81, v85
	v_add_f32_e32 v84, v90, v91
	v_add_f32_e32 v81, v81, v84
	v_add_f32_e32 v84, v98, v81
	ds_swizzle_b32 v85, v84 offset:swizzle(SWAP,16)
	v_cvt_pk_bf16_f32 v81, v86, v87
	v_cvt_pk_bf16_f32 v82, v82, v83
	v_cvt_pk_bf16_f32 v83, v88, v89
	global_store_dwordx4 v[106:107], v[80:83], off
	s_waitcnt lgkmcnt(0)
	s_nop 0
	v_add_f32_e32 v80, v84, v85
	v_mov_b32_e32 v81, v80
	s_nop 1
	v_permlane32_swap_b32_e32 v80, v81
	s_and_saveexec_b64 s[42:43], vcc
	s_cbranch_execz .LBB0_398
	v_add_f32_e32 v80, v80, v81
	v_mul_f32_e32 v80, 0x49800000, v80
	v_trunc_f32_e32 v80, v80
	v_mul_f32_e32 v81, 0x2f800000, v80
	v_floor_f32_e32 v81, v81
	v_fmac_f32_e32 v80, 0xcf800000, v81
	v_cvt_u32_f32_e32 v80, v80
	v_cvt_u32_f32_e32 v81, v81
	v_lshl_add_u64 v[82:83], v[96:97], 3, s[6:7]
	global_atomic_add_x2 v[82:83], v[80:81], off
; template <int MASK> __device__ __forceinline__ float xor_get(float v) { return __int_as_float(__builtin_amdgcn_ds_swizzle(__float_as_int(v), 0x1F | (MASK << 10))); }
; __device__ __forceinline__ float xor32_sum(float v) { auto rr = __builtin_amdgcn_permlane32_swap(__float_as_uint(v), __float_as_uint(v), false, false); return __uint_as_float(rr[0]) + __uint_as_float(rr[1]); }
; __device__ __forceinline__ void ss_add(u64* p, float v) { atomicAdd(p, (u64)(v * SSFIX)); }
; __device__ __forceinline__ unsigned cvt_pk_bf16(float lo, float hi) { unsigned r; asm volatile("v_cvt_pk_bf16_f32 %0, %1, %2" : "=v"(r) : "v"(lo), "v"(hi)); return r; }
;     __device__ __forceinline__ void operator()(const f32x4 (&acc)[2][2][4][2], const Unit& u, int wr, int wc, int fr, int fq) const {
;     ...
;             for (int m = 0; m < 4; ++m) { const int row = row0 + ai * HALF + m * 16; const size_t off = (size_t)row * ldc + col0; float sq = 0.f;
; #pragma unroll
;                 for (int bj = 0; bj < 2; ++bj) { const size_t p = off + bj * HALF; f32x4 b0, b1;
;                     if constexpr (BASE16) { const u32x4 wb = *(const u32x4*)((const bf16_t*)base + p);
;                         b0 = (f32x4){__uint_as_float(wb.x << 16), __uint_as_float(wb.x & 0xffff0000u), __uint_as_float(wb.y << 16), __uint_as_float(wb.y & 0xffff0000u)};
;                         b1 = (f32x4){__uint_as_float(wb.z << 16), __uint_as_float(wb.z & 0xffff0000u), __uint_as_float(wb.w << 16), __uint_as_float(wb.w & 0xffff0000u)}; }
;                     else { b0 = *(const f32x4*)((const float*)base + p); b1 = *(const f32x4*)((const float*)base + p + 4); }
;                     const f32x4 v0 = b0 + acc[ai][bj][m][0] * csv[bj][0], v1 = b1 + acc[ai][bj][m][1] * csv[bj][1];
;                     if constexpr (HAS_OUT) { *(f32x4*)(out + p) = v0; *(f32x4*)(out + p + 4) = v1; }
;                     if constexpr (HAS_XB) { u32x4 w; w.x = cvt_pk_bf16(v0[0], v0[1]); w.y = cvt_pk_bf16(v0[2], v0[3]); w.z = cvt_pk_bf16(v1[0], v1[1]); w.w = cvt_pk_bf16(v1[2], v1[3]); *(u32x4*)(xb + p) = w; }
;                     sq += ((v0[0] * v0[0] + v0[1] * v0[1]) + (v0[2] * v0[2] + v0[3] * v0[3])) + ((v1[0] * v1[0] + v1[1] * v1[1]) + (v1[2] * v1[2] + v1[3] * v1[3])); }
;                 if constexpr (HAS_SS) { sq += xor_get<16>(sq); sq = xor32_sum(sq); if (fq == 0) ss_add(ss + row, sq); } }
.LBB0_398:
	s_or_b64 exec, exec, s[42:43]
	v_or_b32_e32 v80, 48, v144
	v_ashrrev_i32_e32 v81, 31, v80
	v_lshlrev_b64 v[82:83], 11, v[80:81]
	v_lshl_add_u64 v[90:91], v[82:83], 0, v[142:143]
	v_lshl_add_u64 v[92:93], v[90:91], 2, s[54:55]
	v_lshlrev_b64 v[90:91], 1, v[90:91]
	v_lshl_add_u64 v[94:95], s[4:5], 0, v[90:91]
	v_or_b32_e32 v90, 0x100, v90
	v_lshl_add_u64 v[90:91], s[4:5], 0, v[90:91]
	s_mov_b32 s100, 0x160000
	v_lshl_add_u64 v[252:253], v[160:161], 0, s[100:101]
	global_load_dwordx4 v[200:203], v[252:253], off
	global_load_dwordx4 v[204:207], v[252:253], off offset:16
	global_load_dwordx4 v[208:211], v[252:253], off offset:512
	global_load_dwordx4 v[212:215], v[252:253], off offset:528
	s_waitcnt vmcnt(25)
	s_nop 1
	v_mov_b64_e32 v[82:83], v[216:217]
	v_mov_b64_e32 v[84:85], v[218:219]
	v_mov_b64_e32 v[86:87], v[220:221]
	v_mov_b64_e32 v[88:89], v[222:223]
	v_pk_fma_f32 v[84:85], v[78:79], 0.5, v[84:85] op_sel_hi:[1,0,1]
	v_pk_fma_f32 v[82:83], v[76:77], 0.5, v[82:83] op_sel_hi:[1,0,1]
	v_pk_fma_f32 v[88:89], v[74:75], 0.5, v[88:89] op_sel_hi:[1,0,1]
	v_pk_fma_f32 v[86:87], v[72:73], 0.5, v[86:87] op_sel_hi:[1,0,1]
	v_cvt_pk_bf16_f32 v72, v82, v83
	v_cvt_pk_bf16_f32 v73, v84, v85
	v_mul_f32_e32 v83, v83, v83
	v_cvt_pk_bf16_f32 v74, v86, v87
	v_cvt_pk_bf16_f32 v75, v88, v89
	global_store_dwordx4 v[94:95], v[72:75], off
	s_nop 0
	v_mul_f32_e32 v85, v85, v85
	v_mul_f32_e32 v87, v87, v87
	v_mul_f32_e32 v89, v89, v89
	v_fmac_f32_e32 v83, v82, v82
	v_fmac_f32_e32 v85, v84, v84
	v_fmac_f32_e32 v87, v86, v86
	v_fmac_f32_e32 v89, v88, v88
	v_add_f32_e32 v82, v83, v85
	v_add_f32_e32 v83, v87, v89
	v_add_f32_e32 v82, v82, v83
	s_nop 1
	v_mov_b64_e32 v[72:73], v[224:225]
	v_mov_b64_e32 v[74:75], v[226:227]
	v_mov_b64_e32 v[76:77], v[228:229]
	v_mov_b64_e32 v[78:79], v[230:231]
	v_pk_fma_f32 v[70:71], v[70:71], 0.5, v[74:75] op_sel_hi:[1,0,1]
	v_pk_fma_f32 v[68:69], v[68:69], 0.5, v[72:73] op_sel_hi:[1,0,1]
	v_pk_fma_f32 v[72:73], v[66:67], 0.5, v[78:79] op_sel_hi:[1,0,1]
	v_pk_fma_f32 v[66:67], v[64:65], 0.5, v[76:77] op_sel_hi:[1,0,1]
	v_cvt_pk_bf16_f32 v64, v68, v69
	v_mul_f32_e32 v65, v69, v69
	v_mul_f32_e32 v69, v71, v71
	v_mul_f32_e32 v74, v67, v67
	v_mul_f32_e32 v75, v73, v73
	v_fmac_f32_e32 v65, v68, v68
	v_fmac_f32_e32 v69, v70, v70
	v_fmac_f32_e32 v74, v66, v66
	v_fmac_f32_e32 v75, v72, v72
	v_add_f32_e32 v65, v65, v69
	v_add_f32_e32 v68, v74, v75
	v_add_f32_e32 v65, v65, v68
	v_add_f32_e32 v68, v82, v65
	ds_swizzle_b32 v69, v68 offset:swizzle(SWAP,16)
	v_cvt_pk_bf16_f32 v65, v70, v71
	v_cvt_pk_bf16_f32 v66, v66, v67
	v_cvt_pk_bf16_f32 v67, v72, v73
	global_store_dwordx4 v[90:91], v[64:67], off
	s_waitcnt lgkmcnt(0)
	s_nop 0
	v_add_f32_e32 v64, v68, v69
	v_mov_b32_e32 v65, v64
	s_nop 1
	v_permlane32_swap_b32_e32 v64, v65
	s_and_saveexec_b64 s[42:43], vcc
	s_cbranch_execz .LBB0_400
	v_add_f32_e32 v64, v64, v65
	v_mul_f32_e32 v64, 0x49800000, v64
	v_trunc_f32_e32 v64, v64
	v_mul_f32_e32 v65, 0x2f800000, v64
	v_floor_f32_e32 v65, v65
	v_fmac_f32_e32 v64, 0xcf800000, v65
	v_cvt_u32_f32_e32 v64, v64
	v_cvt_u32_f32_e32 v65, v65
	v_lshl_add_u64 v[66:67], v[80:81], 3, s[6:7]
	global_atomic_add_x2 v[66:67], v[64:65], off
.LBB0_400:
	s_or_b64 exec, exec, s[42:43]
	v_add_u32_e32 v64, 0x80, v144
	v_ashrrev_i32_e32 v65, 31, v64
	v_lshlrev_b64 v[66:67], 11, v[64:65]
	v_lshl_add_u64 v[74:75], v[66:67], 0, v[142:143]
	v_lshl_add_u64 v[76:77], v[74:75], 2, s[54:55]
	v_lshlrev_b64 v[74:75], 1, v[74:75]
	v_lshl_add_u64 v[78:79], s[4:5], 0, v[74:75]
	v_or_b32_e32 v74, 0x100, v74
	v_lshl_add_u64 v[74:75], s[4:5], 0, v[74:75]
	s_waitcnt vmcnt(24)
	s_nop 1
	v_mov_b64_e32 v[66:67], v[232:233]
	v_mov_b64_e32 v[68:69], v[234:235]
	v_mov_b64_e32 v[70:71], v[236:237]
	v_mov_b64_e32 v[72:73], v[238:239]
	v_pk_fma_f32 v[68:69], v[62:63], 0.5, v[68:69] op_sel_hi:[1,0,1]
	v_pk_fma_f32 v[66:67], v[60:61], 0.5, v[66:67] op_sel_hi:[1,0,1]
	v_pk_fma_f32 v[72:73], v[58:59], 0.5, v[72:73] op_sel_hi:[1,0,1]
	v_pk_fma_f32 v[70:71], v[56:57], 0.5, v[70:71] op_sel_hi:[1,0,1]
	v_cvt_pk_bf16_f32 v56, v66, v67
	v_cvt_pk_bf16_f32 v57, v68, v69
	v_mul_f32_e32 v67, v67, v67
	v_cvt_pk_bf16_f32 v58, v70, v71
	v_cvt_pk_bf16_f32 v59, v72, v73
	global_store_dwordx4 v[78:79], v[56:59], off
	s_nop 0
	v_mul_f32_e32 v69, v69, v69
	v_mul_f32_e32 v71, v71, v71
	v_mul_f32_e32 v73, v73, v73
	v_fmac_f32_e32 v67, v66, v66
	v_fmac_f32_e32 v69, v68, v68
	v_fmac_f32_e32 v71, v70, v70
	v_fmac_f32_e32 v73, v72, v72
	v_add_f32_e32 v66, v67, v69
	v_add_f32_e32 v67, v71, v73
	v_add_f32_e32 v66, v66, v67
	s_nop 1
	v_mov_b64_e32 v[56:57], v[240:241]
	v_mov_b64_e32 v[58:59], v[242:243]
	v_mov_b64_e32 v[60:61], v[244:245]
	v_mov_b64_e32 v[62:63], v[246:247]
	v_pk_fma_f32 v[54:55], v[54:55], 0.5, v[58:59] op_sel_hi:[1,0,1]
	v_pk_fma_f32 v[52:53], v[52:53], 0.5, v[56:57] op_sel_hi:[1,0,1]
	v_pk_fma_f32 v[56:57], v[50:51], 0.5, v[62:63] op_sel_hi:[1,0,1]
	v_pk_fma_f32 v[50:51], v[48:49], 0.5, v[60:61] op_sel_hi:[1,0,1]
	v_cvt_pk_bf16_f32 v48, v52, v53
	v_mul_f32_e32 v49, v53, v53
	v_mul_f32_e32 v53, v55, v55
	v_mul_f32_e32 v58, v51, v51
	v_mul_f32_e32 v59, v57, v57
	v_fmac_f32_e32 v49, v52, v52
	v_fmac_f32_e32 v53, v54, v54
	v_fmac_f32_e32 v58, v50, v50
	v_fmac_f32_e32 v59, v56, v56
	v_add_f32_e32 v49, v49, v53
	v_add_f32_e32 v52, v58, v59
	v_add_f32_e32 v49, v49, v52
	v_add_f32_e32 v52, v66, v49
	ds_swizzle_b32 v53, v52 offset:swizzle(SWAP,16)
	v_cvt_pk_bf16_f32 v49, v54, v55
	v_cvt_pk_bf16_f32 v50, v50, v51
	v_cvt_pk_bf16_f32 v51, v56, v57
	global_store_dwordx4 v[74:75], v[48:51], off
	s_waitcnt lgkmcnt(0)
	s_nop 0
	v_add_f32_e32 v48, v52, v53
	v_mov_b32_e32 v49, v48
	s_nop 1
	v_permlane32_swap_b32_e32 v48, v49
	s_and_saveexec_b64 s[42:43], vcc
	s_cbranch_execz .LBB0_402
	v_add_f32_e32 v48, v48, v49
	v_mul_f32_e32 v48, 0x49800000, v48
	v_trunc_f32_e32 v48, v48
	v_mul_f32_e32 v49, 0x2f800000, v48
	v_floor_f32_e32 v49, v49
	v_fmac_f32_e32 v48, 0xcf800000, v49
	v_cvt_u32_f32_e32 v48, v48
	v_cvt_u32_f32_e32 v49, v49
	v_lshl_add_u64 v[50:51], v[64:65], 3, s[6:7]
	global_atomic_add_x2 v[50:51], v[48:49], off
; template <int MASK> __device__ __forceinline__ float xor_get(float v) { return __int_as_float(__builtin_amdgcn_ds_swizzle(__float_as_int(v), 0x1F | (MASK << 10))); }
; __device__ __forceinline__ float xor32_sum(float v) { auto rr = __builtin_amdgcn_permlane32_swap(__float_as_uint(v), __float_as_uint(v), false, false); return __uint_as_float(rr[0]) + __uint_as_float(rr[1]); }
; __device__ __forceinline__ void ss_add(u64* p, float v) { atomicAdd(p, (u64)(v * SSFIX)); }
; __device__ __forceinline__ unsigned cvt_pk_bf16(float lo, float hi) { unsigned r; asm volatile("v_cvt_pk_bf16_f32 %0, %1, %2" : "=v"(r) : "v"(lo), "v"(hi)); return r; }
;     __device__ __forceinline__ void operator()(const f32x4 (&acc)[2][2][4][2], const Unit& u, int wr, int wc, int fr, int fq) const {
;     ...
;             for (int m = 0; m < 4; ++m) { const int row = row0 + ai * HALF + m * 16; const size_t off = (size_t)row * ldc + col0; float sq = 0.f;
; #pragma unroll
;                 for (int bj = 0; bj < 2; ++bj) { const size_t p = off + bj * HALF; f32x4 b0, b1;
;                     if constexpr (BASE16) { const u32x4 wb = *(const u32x4*)((const bf16_t*)base + p);
;                         b0 = (f32x4){__uint_as_float(wb.x << 16), __uint_as_float(wb.x & 0xffff0000u), __uint_as_float(wb.y << 16), __uint_as_float(wb.y & 0xffff0000u)};
;                         b1 = (f32x4){__uint_as_float(wb.z << 16), __uint_as_float(wb.z & 0xffff0000u), __uint_as_float(wb.w << 16), __uint_as_float(wb.w & 0xffff0000u)}; }
;                     else { b0 = *(const f32x4*)((const float*)base + p); b1 = *(const f32x4*)((const float*)base + p + 4); }
;                     const f32x4 v0 = b0 + acc[ai][bj][m][0] * csv[bj][0], v1 = b1 + acc[ai][bj][m][1] * csv[bj][1];
;                     if constexpr (HAS_OUT) { *(f32x4*)(out + p) = v0; *(f32x4*)(out + p + 4) = v1; }
;                     if constexpr (HAS_XB) { u32x4 w; w.x = cvt_pk_bf16(v0[0], v0[1]); w.y = cvt_pk_bf16(v0[2], v0[3]); w.z = cvt_pk_bf16(v1[0], v1[1]); w.w = cvt_pk_bf16(v1[2], v1[3]); *(u32x4*)(xb + p) = w; }
;                     sq += ((v0[0] * v0[0] + v0[1] * v0[1]) + (v0[2] * v0[2] + v0[3] * v0[3])) + ((v1[0] * v1[0] + v1[1] * v1[1]) + (v1[2] * v1[2] + v1[3] * v1[3])); }
;                 if constexpr (HAS_SS) { sq += xor_get<16>(sq); sq = xor32_sum(sq); if (fq == 0) ss_add(ss + row, sq); } }
.LBB0_402:
	s_or_b64 exec, exec, s[42:43]
	v_add_u32_e32 v48, 0x90, v144
	v_ashrrev_i32_e32 v49, 31, v48
	v_lshlrev_b64 v[50:51], 11, v[48:49]
	v_lshl_add_u64 v[58:59], v[50:51], 0, v[142:143]
	v_lshl_add_u64 v[60:61], v[58:59], 2, s[54:55]
	v_lshlrev_b64 v[58:59], 1, v[58:59]
	v_lshl_add_u64 v[62:63], s[4:5], 0, v[58:59]
	v_or_b32_e32 v58, 0x100, v58
	v_lshl_add_u64 v[58:59], s[4:5], 0, v[58:59]
	s_waitcnt vmcnt(20)
	s_nop 1
	v_mov_b64_e32 v[50:51], v[168:169]
	v_mov_b64_e32 v[52:53], v[170:171]
	v_mov_b64_e32 v[54:55], v[172:173]
	v_mov_b64_e32 v[56:57], v[174:175]
	v_pk_fma_f32 v[52:53], v[46:47], 0.5, v[52:53] op_sel_hi:[1,0,1]
	v_pk_fma_f32 v[50:51], v[44:45], 0.5, v[50:51] op_sel_hi:[1,0,1]
	v_pk_fma_f32 v[56:57], v[42:43], 0.5, v[56:57] op_sel_hi:[1,0,1]
	v_pk_fma_f32 v[54:55], v[40:41], 0.5, v[54:55] op_sel_hi:[1,0,1]
	v_cvt_pk_bf16_f32 v40, v50, v51
	v_cvt_pk_bf16_f32 v41, v52, v53
	v_mul_f32_e32 v51, v51, v51
	v_cvt_pk_bf16_f32 v42, v54, v55
	v_cvt_pk_bf16_f32 v43, v56, v57
	global_store_dwordx4 v[62:63], v[40:43], off
	s_nop 0
	v_mul_f32_e32 v53, v53, v53
	v_mul_f32_e32 v55, v55, v55
	v_mul_f32_e32 v57, v57, v57
	v_fmac_f32_e32 v51, v50, v50
	v_fmac_f32_e32 v53, v52, v52
	v_fmac_f32_e32 v55, v54, v54
	v_fmac_f32_e32 v57, v56, v56
	v_add_f32_e32 v50, v51, v53
	v_add_f32_e32 v51, v55, v57
	v_add_f32_e32 v50, v50, v51
	s_nop 1
	v_mov_b64_e32 v[40:41], v[176:177]
	v_mov_b64_e32 v[42:43], v[178:179]
	v_mov_b64_e32 v[44:45], v[180:181]
	v_mov_b64_e32 v[46:47], v[182:183]
	v_pk_fma_f32 v[38:39], v[38:39], 0.5, v[42:43] op_sel_hi:[1,0,1]
	v_pk_fma_f32 v[36:37], v[36:37], 0.5, v[40:41] op_sel_hi:[1,0,1]
	v_pk_fma_f32 v[40:41], v[34:35], 0.5, v[46:47] op_sel_hi:[1,0,1]
	v_pk_fma_f32 v[34:35], v[32:33], 0.5, v[44:45] op_sel_hi:[1,0,1]
	v_cvt_pk_bf16_f32 v32, v36, v37
	v_mul_f32_e32 v33, v37, v37
	v_mul_f32_e32 v37, v39, v39
	v_mul_f32_e32 v42, v35, v35
	v_mul_f32_e32 v43, v41, v41
	v_fmac_f32_e32 v33, v36, v36
	v_fmac_f32_e32 v37, v38, v38
	v_fmac_f32_e32 v42, v34, v34
	v_fmac_f32_e32 v43, v40, v40
	v_add_f32_e32 v33, v33, v37
	v_add_f32_e32 v36, v42, v43
	v_add_f32_e32 v33, v33, v36
	v_add_f32_e32 v36, v50, v33
	ds_swizzle_b32 v37, v36 offset:swizzle(SWAP,16)
	v_cvt_pk_bf16_f32 v33, v38, v39
	v_cvt_pk_bf16_f32 v34, v34, v35
	v_cvt_pk_bf16_f32 v35, v40, v41
	global_store_dwordx4 v[58:59], v[32:35], off
	s_waitcnt lgkmcnt(0)
	s_nop 0
	v_add_f32_e32 v32, v36, v37
	v_mov_b32_e32 v33, v32
	s_nop 1
	v_permlane32_swap_b32_e32 v32, v33
	s_and_saveexec_b64 s[42:43], vcc
	s_cbranch_execz .LBB0_404
	v_add_f32_e32 v32, v32, v33
	v_mul_f32_e32 v32, 0x49800000, v32
	v_trunc_f32_e32 v32, v32
	v_mul_f32_e32 v33, 0x2f800000, v32
	v_floor_f32_e32 v33, v33
	v_fmac_f32_e32 v32, 0xcf800000, v33
	v_cvt_u32_f32_e32 v32, v32
	v_cvt_u32_f32_e32 v33, v33
	v_lshl_add_u64 v[34:35], v[48:49], 3, s[6:7]
	global_atomic_add_x2 v[34:35], v[32:33], off
; template <int MASK> __device__ __forceinline__ float xor_get(float v) { return __int_as_float(__builtin_amdgcn_ds_swizzle(__float_as_int(v), 0x1F | (MASK << 10))); }
; __device__ __forceinline__ float xor32_sum(float v) { auto rr = __builtin_amdgcn_permlane32_swap(__float_as_uint(v), __float_as_uint(v), false, false); return __uint_as_float(rr[0]) + __uint_as_float(rr[1]); }
; __device__ __forceinline__ void ss_add(u64* p, float v) { atomicAdd(p, (u64)(v * SSFIX)); }
; __device__ __forceinline__ unsigned cvt_pk_bf16(float lo, float hi) { unsigned r; asm volatile("v_cvt_pk_bf16_f32 %0, %1, %2" : "=v"(r) : "v"(lo), "v"(hi)); return r; }
;     __device__ __forceinline__ void operator()(const f32x4 (&acc)[2][2][4][2], const Unit& u, int wr, int wc, int fr, int fq) const {
;     ...
;             for (int m = 0; m < 4; ++m) { const int row = row0 + ai * HALF + m * 16; const size_t off = (size_t)row * ldc + col0; float sq = 0.f;
; #pragma unroll
;                 for (int bj = 0; bj < 2; ++bj) { const size_t p = off + bj * HALF; f32x4 b0, b1;
;                     if constexpr (BASE16) { const u32x4 wb = *(const u32x4*)((const bf16_t*)base + p);
;                         b0 = (f32x4){__uint_as_float(wb.x << 16), __uint_as_float(wb.x & 0xffff0000u), __uint_as_float(wb.y << 16), __uint_as_float(wb.y & 0xffff0000u)};
;                         b1 = (f32x4){__uint_as_float(wb.z << 16), __uint_as_float(wb.z & 0xffff0000u), __uint_as_float(wb.w << 16), __uint_as_float(wb.w & 0xffff0000u)}; }
;                     else { b0 = *(const f32x4*)((const float*)base + p); b1 = *(const f32x4*)((const float*)base + p + 4); }
;                     const f32x4 v0 = b0 + acc[ai][bj][m][0] * csv[bj][0], v1 = b1 + acc[ai][bj][m][1] * csv[bj][1];
;                     if constexpr (HAS_OUT) { *(f32x4*)(out + p) = v0; *(f32x4*)(out + p + 4) = v1; }
;                     if constexpr (HAS_XB) { u32x4 w; w.x = cvt_pk_bf16(v0[0], v0[1]); w.y = cvt_pk_bf16(v0[2], v0[3]); w.z = cvt_pk_bf16(v1[0], v1[1]); w.w = cvt_pk_bf16(v1[2], v1[3]); *(u32x4*)(xb + p) = w; }
;                     sq += ((v0[0] * v0[0] + v0[1] * v0[1]) + (v0[2] * v0[2] + v0[3] * v0[3])) + ((v1[0] * v1[0] + v1[1] * v1[1]) + (v1[2] * v1[2] + v1[3] * v1[3])); }
;                 if constexpr (HAS_SS) { sq += xor_get<16>(sq); sq = xor32_sum(sq); if (fq == 0) ss_add(ss + row, sq); } }
.LBB0_404:
	s_or_b64 exec, exec, s[42:43]
	v_add_u32_e32 v32, 0xa0, v144
	v_ashrrev_i32_e32 v33, 31, v32
	v_lshlrev_b64 v[34:35], 11, v[32:33]
	v_lshl_add_u64 v[42:43], v[34:35], 0, v[142:143]
	v_lshl_add_u64 v[44:45], v[42:43], 2, s[54:55]
	v_lshlrev_b64 v[42:43], 1, v[42:43]
	v_lshl_add_u64 v[46:47], s[4:5], 0, v[42:43]
	v_or_b32_e32 v42, 0x100, v42
	v_lshl_add_u64 v[42:43], s[4:5], 0, v[42:43]
	s_waitcnt vmcnt(16)
	s_nop 1
	v_mov_b64_e32 v[34:35], v[184:185]
	v_mov_b64_e32 v[36:37], v[186:187]
	v_mov_b64_e32 v[38:39], v[188:189]
	v_mov_b64_e32 v[40:41], v[190:191]
	v_pk_fma_f32 v[36:37], v[30:31], 0.5, v[36:37] op_sel_hi:[1,0,1]
	v_pk_fma_f32 v[34:35], v[28:29], 0.5, v[34:35] op_sel_hi:[1,0,1]
	v_pk_fma_f32 v[40:41], v[26:27], 0.5, v[40:41] op_sel_hi:[1,0,1]
	v_pk_fma_f32 v[38:39], v[24:25], 0.5, v[38:39] op_sel_hi:[1,0,1]
	v_cvt_pk_bf16_f32 v24, v34, v35
	v_cvt_pk_bf16_f32 v25, v36, v37
	v_mul_f32_e32 v35, v35, v35
	v_cvt_pk_bf16_f32 v26, v38, v39
	v_cvt_pk_bf16_f32 v27, v40, v41
	global_store_dwordx4 v[46:47], v[24:27], off
	s_nop 0
	v_mul_f32_e32 v37, v37, v37
	v_mul_f32_e32 v39, v39, v39
	v_mul_f32_e32 v41, v41, v41
	v_fmac_f32_e32 v35, v34, v34
	v_fmac_f32_e32 v37, v36, v36
	v_fmac_f32_e32 v39, v38, v38
	v_fmac_f32_e32 v41, v40, v40
	v_add_f32_e32 v34, v35, v37
	v_add_f32_e32 v35, v39, v41
	v_add_f32_e32 v34, v34, v35
	s_nop 1
	v_mov_b64_e32 v[24:25], v[192:193]
	v_mov_b64_e32 v[26:27], v[194:195]
	v_mov_b64_e32 v[28:29], v[196:197]
	v_mov_b64_e32 v[30:31], v[198:199]
	v_pk_fma_f32 v[22:23], v[22:23], 0.5, v[26:27] op_sel_hi:[1,0,1]
	v_pk_fma_f32 v[20:21], v[20:21], 0.5, v[24:25] op_sel_hi:[1,0,1]
	v_pk_fma_f32 v[24:25], v[18:19], 0.5, v[30:31] op_sel_hi:[1,0,1]
	v_pk_fma_f32 v[18:19], v[16:17], 0.5, v[28:29] op_sel_hi:[1,0,1]
	v_cvt_pk_bf16_f32 v16, v20, v21
	v_mul_f32_e32 v17, v21, v21
	v_mul_f32_e32 v21, v23, v23
	v_mul_f32_e32 v26, v19, v19
	v_mul_f32_e32 v27, v25, v25
	v_fmac_f32_e32 v17, v20, v20
	v_fmac_f32_e32 v21, v22, v22
	v_fmac_f32_e32 v26, v18, v18
	v_fmac_f32_e32 v27, v24, v24
	v_add_f32_e32 v17, v17, v21
	v_add_f32_e32 v20, v26, v27
	v_add_f32_e32 v17, v17, v20
	v_add_f32_e32 v20, v34, v17
	ds_swizzle_b32 v21, v20 offset:swizzle(SWAP,16)
	v_cvt_pk_bf16_f32 v17, v22, v23
	v_cvt_pk_bf16_f32 v18, v18, v19
	v_cvt_pk_bf16_f32 v19, v24, v25
	global_store_dwordx4 v[42:43], v[16:19], off
	s_waitcnt lgkmcnt(0)
	s_nop 0
	v_add_f32_e32 v16, v20, v21
	v_mov_b32_e32 v17, v16
	s_nop 1
	v_permlane32_swap_b32_e32 v16, v17
	s_and_saveexec_b64 s[42:43], vcc
	s_cbranch_execz .LBB0_406
	v_add_f32_e32 v16, v16, v17
	v_mul_f32_e32 v16, 0x49800000, v16
	v_trunc_f32_e32 v16, v16
	v_mul_f32_e32 v17, 0x2f800000, v16
	v_floor_f32_e32 v17, v17
	v_fmac_f32_e32 v16, 0xcf800000, v17
	v_cvt_u32_f32_e32 v16, v16
	v_cvt_u32_f32_e32 v17, v17
	v_lshl_add_u64 v[18:19], v[32:33], 3, s[6:7]
	global_atomic_add_x2 v[18:19], v[16:17], off
.LBB0_406:
	s_or_b64 exec, exec, s[42:43]
	v_add_u32_e32 v16, 0xb0, v144
	v_ashrrev_i32_e32 v17, 31, v16
	v_lshlrev_b64 v[18:19], 11, v[16:17]
	v_lshl_add_u64 v[26:27], v[18:19], 0, v[142:143]
	v_lshl_add_u64 v[28:29], v[26:27], 2, s[54:55]
	v_lshlrev_b64 v[26:27], 1, v[26:27]
	v_lshl_add_u64 v[30:31], s[4:5], 0, v[26:27]
	v_or_b32_e32 v26, 0x100, v26
	v_lshl_add_u64 v[26:27], s[4:5], 0, v[26:27]
	s_waitcnt vmcnt(12)
	s_nop 1
	v_mov_b64_e32 v[18:19], v[200:201]
	v_mov_b64_e32 v[20:21], v[202:203]
	v_mov_b64_e32 v[22:23], v[204:205]
	v_mov_b64_e32 v[24:25], v[206:207]
	v_pk_fma_f32 v[20:21], v[14:15], 0.5, v[20:21] op_sel_hi:[1,0,1]
	v_pk_fma_f32 v[18:19], v[12:13], 0.5, v[18:19] op_sel_hi:[1,0,1]
	v_pk_fma_f32 v[24:25], v[10:11], 0.5, v[24:25] op_sel_hi:[1,0,1]
	v_pk_fma_f32 v[22:23], v[8:9], 0.5, v[22:23] op_sel_hi:[1,0,1]
	v_cvt_pk_bf16_f32 v8, v18, v19
	v_cvt_pk_bf16_f32 v9, v20, v21
	v_mul_f32_e32 v19, v19, v19
	v_cvt_pk_bf16_f32 v10, v22, v23
	v_cvt_pk_bf16_f32 v11, v24, v25
	global_store_dwordx4 v[30:31], v[8:11], off
	s_nop 0
	v_mul_f32_e32 v21, v21, v21
	v_mul_f32_e32 v23, v23, v23
	v_mul_f32_e32 v25, v25, v25
	v_fmac_f32_e32 v19, v18, v18
	v_fmac_f32_e32 v21, v20, v20
	v_fmac_f32_e32 v23, v22, v22
	v_fmac_f32_e32 v25, v24, v24
	v_add_f32_e32 v18, v19, v21
	v_add_f32_e32 v19, v23, v25
	v_add_f32_e32 v18, v18, v19
	s_nop 1
	v_mov_b64_e32 v[8:9], v[208:209]
	v_mov_b64_e32 v[10:11], v[210:211]
	v_mov_b64_e32 v[12:13], v[212:213]
	v_mov_b64_e32 v[14:15], v[214:215]
	v_pk_fma_f32 v[6:7], v[6:7], 0.5, v[10:11] op_sel_hi:[1,0,1]
	v_pk_fma_f32 v[4:5], v[4:5], 0.5, v[8:9] op_sel_hi:[1,0,1]
	v_pk_fma_f32 v[8:9], v[2:3], 0.5, v[14:15] op_sel_hi:[1,0,1]
	v_pk_fma_f32 v[2:3], v[0:1], 0.5, v[12:13] op_sel_hi:[1,0,1]
	v_cvt_pk_bf16_f32 v0, v4, v5
	v_mul_f32_e32 v1, v5, v5
	v_mul_f32_e32 v5, v7, v7
	v_mul_f32_e32 v10, v3, v3
	v_mul_f32_e32 v11, v9, v9
	v_fmac_f32_e32 v1, v4, v4
	v_fmac_f32_e32 v5, v6, v6
	v_fmac_f32_e32 v10, v2, v2
	v_fmac_f32_e32 v11, v8, v8
	v_add_f32_e32 v1, v1, v5
	v_add_f32_e32 v4, v10, v11
	v_add_f32_e32 v1, v1, v4
	v_add_f32_e32 v4, v18, v1
	ds_swizzle_b32 v5, v4 offset:swizzle(SWAP,16)
	v_cvt_pk_bf16_f32 v1, v6, v7
	v_cvt_pk_bf16_f32 v2, v2, v3
	v_cvt_pk_bf16_f32 v3, v8, v9
	global_store_dwordx4 v[26:27], v[0:3], off
	s_waitcnt lgkmcnt(0)
	s_nop 0
	v_add_f32_e32 v0, v4, v5
	v_mov_b32_e32 v1, v0
	s_nop 1
	v_permlane32_swap_b32_e32 v0, v1
	s_and_saveexec_b64 s[42:43], vcc
	s_cbranch_execz .LBB0_408
	v_add_f32_e32 v0, v0, v1
	v_mul_f32_e32 v0, 0x49800000, v0
	v_trunc_f32_e32 v0, v0
	v_mul_f32_e32 v1, 0x2f800000, v0
	v_floor_f32_e32 v1, v1
	v_fmac_f32_e32 v0, 0xcf800000, v1
	v_cvt_u32_f32_e32 v0, v0
	v_cvt_u32_f32_e32 v1, v1
	v_lshl_add_u64 v[2:3], v[16:17], 3, s[6:7]
	global_atomic_add_x2 v[2:3], v[0:1], off

;     __device__ __forceinline__ void operator()(const f32x4 (&acc)[2][2][4][2], const Unit& u, int wr, int wc, int fr, int fq) const {
;         const int row0 = u.pm * BM + wr * 64 + fr; const int col0 = u.pn * HALF + wc * 32 + 8 * fq;
;         f32x4 sg[2], su[2];
; #pragma unroll
;         for (int n = 0; n < 2; ++n) { sg[n] = cmg ? *(const f32x4*)(cmg + col0 + 4 * n) * cscale : (f32x4){1.f, 1.f, 1.f, 1.f}; su[n] = cmu ? *(const f32x4*)(cmu + col0 + 4 * n) * cscale : (f32x4){1.f, 1.f, 1.f, 1.f}; }
; #pragma unroll
;         for (int ai = 0; ai < 2; ++ai) { unsigned pw[4][2];
; #pragma unroll
;             for (int m = 0; m < 4; ++m) { const int row = row0 + ai * HALF + m * 16; bf16_t* rowp = O + (size_t)row * ldc + col0;
;                 const float rs = rsc ? rsc[row] : 1.f;
;                 f32x4 r[2];
; #pragma unroll
;                 for (int n = 0; n < 2; ++n) { const f32x4 g = acc[ai][0][m][n] * sg[n] * rs, up = acc[ai][1][m][n] * su[n] * rs;
; #pragma unroll
;                     for (int e = 0; e < 4; ++e) { const float sgm = __builtin_amdgcn_rcpf(1.0f + __builtin_amdgcn_exp2f(-1.4426950408889634f * g[e])); r[n][e] = g[e] * sgm * up[e]; } }
.LBB0_1394:
	v_mbcnt_lo_u32_b32 v158, -1, 0
	v_mbcnt_hi_u32_b32 v158, -1, v158
	s_lshl_b32 s53, s85, 7
	v_lshrrev_b32_e32 v128, 1, v158
	v_and_or_b32 v128, v128, 24, s53
	v_or_b32_e32 v176, s79, v128
	v_ashrrev_i32_e32 v177, 31, v176
	v_lshlrev_b64 v[132:133], 2, v[176:177]
	s_lshl_b32 s53, s62, 8
	v_lshl_add_u64 v[134:135], s[36:37], 0, v[132:133]
	s_add_i32 s53, s53, s78
	global_load_dwordx4 v[128:131], v[134:135], off
	v_lshl_add_u64 v[132:133], s[38:39], 0, v[132:133]
	v_and_or_b32 v178, v158, 15, s53
	global_load_dwordx4 v[140:143], v[132:133], off
	global_load_dwordx4 v[136:139], v[134:135], off offset:16
	s_nop 0
	global_load_dwordx4 v[132:135], v[132:133], off offset:16
	v_ashrrev_i32_e32 v179, 31, v178
	v_lshl_add_u64 v[152:153], v[178:179], 2, s[34:35]
	global_load_dword v154, v[152:153], off
	v_cvt_f32_i32_e32 v165, v118
	v_cvt_f32_i32_e32 v164, v114
	v_bfe_u32 v174, v158, 4, 1
	global_load_dword v118, v[152:153], off offset:64
	global_load_dword v158, v[152:153], off offset:128
	global_load_dword v114, v[152:153], off offset:192
	global_load_dword v240, v[152:153], off offset:512
	global_load_dword v241, v[152:153], off offset:576
	global_load_dword v242, v[152:153], off offset:640
	global_load_dword v243, v[152:153], off offset:704
	v_cvt_f32_i32_e32 v161, v125
	v_cvt_f32_i32_e32 v160, v121
	v_cvt_f32_i32_e32 v157, v124
	v_cvt_f32_i32_e32 v156, v120
	v_cvt_f32_i32_e32 v163, v126
	v_cvt_f32_i32_e32 v162, v122
	v_cvt_f32_i32_e32 v127, v127
	v_cvt_f32_i32_e32 v126, v123
	v_cvt_f32_i32_e32 v167, v116
	v_cvt_f32_i32_e32 v169, v117
	v_cvt_f32_i32_e32 v166, v112
	v_cvt_f32_i32_e32 v168, v113
	v_cvt_f32_i32_e32 v109, v109
	v_cvt_f32_i32_e32 v111, v111
	v_cvt_f32_i32_e32 v101, v101
	v_cvt_f32_i32_e32 v103, v103
	v_cvt_f32_i32_e32 v93, v93
	v_cvt_f32_i32_e32 v95, v95
	v_cvt_f32_i32_e32 v85, v85
	v_cvt_f32_i32_e32 v87, v87
	v_cvt_f32_i32_e32 v77, v77
	v_cvt_f32_i32_e32 v79, v79
	v_cvt_f32_i32_e32 v69, v69
	v_cvt_f32_i32_e32 v71, v71
	v_cmp_eq_u32_e32 vcc, 0, v174
	v_lshlrev_b32_e32 v112, 3, v174
	v_lshl_or_b32 v173, v174, 4, v178
	v_sub_u32_e32 v112, v176, v112
	v_ashrrev_i32_e32 v113, 31, v112
	v_cvt_f32_i32_e32 v63, v63
	v_cvt_f32_i32_e32 v61, v61
	v_cvt_f32_i32_e32 v55, v55
	v_cvt_f32_i32_e32 v53, v53
	v_cvt_f32_i32_e32 v47, v47
	v_cvt_f32_i32_e32 v45, v45
	v_cvt_f32_i32_e32 v39, v39
	v_cvt_f32_i32_e32 v37, v37
	v_cvt_f32_i32_e32 v31, v31
	v_cvt_f32_i32_e32 v29, v29
	v_cvt_f32_i32_e32 v23, v23
	v_cvt_f32_i32_e32 v21, v21
	v_cvt_f32_i32_e32 v13, v13
	v_cvt_f32_i32_e32 v15, v15
	v_cvt_f32_i32_e32 v5, v5
	v_cvt_f32_i32_e32 v7, v7
	s_waitcnt vmcnt(0)
	v_pk_mul_f32 v[124:125], v[130:131], s[50:51] op_sel_hi:[1,0]
	v_pk_mul_f32 v[130:131], v[128:129], s[50:51] op_sel_hi:[1,0]
	v_pk_mul_f32 v[128:129], v[140:141], s[50:51] op_sel_hi:[1,0]
	v_pk_mul_f32 v[120:121], v[136:137], s[50:51] op_sel_hi:[1,0]
	v_pk_mul_f32 v[136:137], v[132:133], s[50:51] op_sel_hi:[1,0]
	v_mov_b32_e32 v133, v130
	v_mov_b32_e32 v130, v129
	v_pk_mul_f32 v[116:117], v[138:139], s[50:51] op_sel_hi:[1,0]
	v_pk_mul_f32 v[138:139], v[130:131], v[160:161]
	v_pk_mul_f32 v[122:123], v[142:143], s[50:51] op_sel_hi:[1,0]
	v_pk_mul_f32 v[138:139], v[138:139], v[154:155] op_sel_hi:[1,0]
	v_mov_b32_e32 v132, v128
	v_mov_b32_e32 v128, v122
	v_mov_b32_e32 v129, v124
	v_mov_b32_e32 v124, v123
	v_mul_f32_e32 v161, 0xbfb8aa3b, v139
	v_pk_mul_f32 v[140:141], v[128:129], v[162:163]
	v_pk_mul_f32 v[126:127], v[124:125], v[126:127]
	v_exp_f32_e32 v161, v161
	v_pk_mul_f32 v[140:141], v[140:141], v[154:155] op_sel_hi:[1,0]
	v_pk_mul_f32 v[126:127], v[126:127], v[154:155] op_sel_hi:[1,0]
	v_mov_b32_e32 v122, v136
	v_mov_b32_e32 v123, v120
	v_mov_b32_e32 v120, v137
	v_pk_mul_f32 v[136:137], v[132:133], v[156:157]
	v_mul_f32_e32 v162, 0xbfb8aa3b, v141
	v_mul_f32_e32 v163, 0xbfb8aa3b, v127
	v_pk_mul_f32 v[136:137], v[136:137], v[154:155] op_sel_hi:[1,0]
	v_exp_f32_e32 v162, v162
	v_exp_f32_e32 v163, v163
	v_mul_f32_e32 v160, 0xbfb8aa3b, v137
	v_add_f32_e32 v161, 1.0, v161
	v_exp_f32_e32 v160, v160
	v_rcp_f32_e32 v161, v161
	v_add_f32_e32 v162, 1.0, v162
	v_add_f32_e32 v163, 1.0, v163
	v_rcp_f32_e32 v162, v162
	v_rcp_f32_e32 v163, v163
	v_add_f32_e32 v160, 1.0, v160
	v_mul_f32_e32 v139, v139, v161
	v_rcp_f32_e32 v160, v160
	v_mul_f32_e32 v161, v138, v139
	v_cvt_f32_i32_e32 v139, v119
	v_cvt_f32_i32_e32 v138, v115
	v_pk_mul_f32 v[142:143], v[122:123], v[166:167]
	v_pk_mul_f32 v[134:135], v[134:135], s[50:51] op_sel_hi:[1,0]
	v_pk_mul_f32 v[142:143], v[154:155], v[142:143] op_sel_hi:[0,1]
	v_mul_f32_e32 v141, v141, v162
	v_mul_f32_e32 v127, v127, v163
	v_mul_f32_e32 v166, 0xbfb8aa3b, v143
	v_mul_f32_e32 v140, v140, v141
	v_mul_f32_e32 v141, v126, v127
	v_mov_b32_e32 v127, v116
	v_mov_b32_e32 v116, v135
	v_exp_f32_e32 v166, v166
	v_mul_f32_e32 v137, v137, v160
	v_mov_b32_e32 v126, v134
	v_pk_mul_f32 v[134:135], v[116:117], v[138:139]
	v_mul_f32_e32 v160, v136, v137
	v_pk_mul_f32 v[136:137], v[126:127], v[164:165]
	v_pk_mul_f32 v[134:135], v[154:155], v[134:135] op_sel_hi:[0,1]
	v_pk_mul_f32 v[156:157], v[120:121], v[168:169]
	v_pk_mul_f32 v[136:137], v[154:155], v[136:137] op_sel_hi:[0,1]
	v_mul_f32_e32 v119, 0xbfb8aa3b, v135
	v_pk_mul_f32 v[156:157], v[154:155], v[156:157] op_sel_hi:[0,1]
	v_mul_f32_e32 v115, 0xbfb8aa3b, v137
	v_exp_f32_e32 v119, v119
	v_mul_f32_e32 v167, 0xbfb8aa3b, v157
	v_add_f32_e32 v166, 1.0, v166
	v_exp_f32_e32 v115, v115
	v_exp_f32_e32 v167, v167
	v_rcp_f32_e32 v166, v166
	v_add_f32_e32 v119, 1.0, v119
	v_add_f32_e32 v115, 1.0, v115
	v_rcp_f32_e32 v119, v119
	v_add_f32_e32 v167, 1.0, v167
	v_mul_f32_e32 v143, v143, v166
	v_rcp_f32_e32 v115, v115
	v_mul_f32_e32 v142, v142, v143
;     __device__ __forceinline__ void operator()(const f32x4 (&acc)[2][2][4][2], const Unit& u, int wr, int wc, int fr, int fq) const {
;     ...
;                 for (int n = 0; n < 2; ++n) { const f32x4 g = acc[ai][0][m][n] * sg[n] * rs, up = acc[ai][1][m][n] * su[n] * rs;
; #pragma unroll
;                     for (int e = 0; e < 4; ++e) { const float sgm = __builtin_amdgcn_rcpf(1.0f + __builtin_amdgcn_exp2f(-1.4426950408889634f * g[e])); r[n][e] = g[e] * sgm * up[e]; } }
;                 if constexpr (OUT8) { typedef unsigned u32x2v __attribute__((ext_vector_type(2))); _Pragma("unroll") for (int e = 0; e < 4; ++e) { r[0][e] = __builtin_amdgcn_fmed3f(r[0][e] * ACT8SCALE, -448.f, 448.f); r[1][e] = __builtin_amdgcn_fmed3f(r[1][e] * ACT8SCALE, -448.f, 448.f); }
;                     int w0 = __builtin_amdgcn_cvt_pk_fp8_f32(r[0][0], r[0][1], 0, false); w0 = __builtin_amdgcn_cvt_pk_fp8_f32(r[0][2], r[0][3], w0, true);
;                     int w1 = __builtin_amdgcn_cvt_pk_fp8_f32(r[1][0], r[1][1], 0, false); w1 = __builtin_amdgcn_cvt_pk_fp8_f32(r[1][2], r[1][3], w1, true);
;                     pw[m][0] = (unsigned)w0; pw[m][1] = (unsigned)w1; (void)rowp; }
	v_rcp_f32_e32 v143, v167
	v_mul_f32_e32 v119, v135, v119
	v_mul_f32_e32 v115, v137, v115
	v_mul_f32_e32 v119, v134, v119
	v_mul_f32_e32 v134, 0x41000000, v160
	v_mul_f32_e32 v138, v157, v143
	v_mul_f32_e32 v115, v136, v115
	v_med3_f32 v136, v134, s83, v172
	v_mul_f32_e32 v134, 0x41000000, v142
	v_mul_f32_e32 v138, v156, v138
	v_med3_f32 v137, v134, s83, v172
	v_mul_f32_e32 v134, 0x41000000, v161
	v_med3_f32 v139, v134, s83, v172
	v_mul_f32_e32 v134, 0x41000000, v138
	v_med3_f32 v138, v134, s83, v172
	v_mul_f32_e32 v134, 0x41000000, v140
	v_med3_f32 v140, v134, s83, v172
	v_mul_f32_e32 v134, 0x41000000, v141
	v_med3_f32 v141, v134, s83, v172
	v_cvt_f32_i32_e32 v135, v108
	v_cvt_f32_i32_e32 v134, v104
	v_mul_f32_e32 v104, 0x41000000, v119
	v_mov_b32_e32 v119, 0
	v_mul_f32_e32 v115, 0x41000000, v115
	v_pk_mul_f32 v[134:135], v[132:133], v[134:135]
	v_med3_f32 v115, v115, s83, v172
	v_pk_mul_f32 v[134:135], v[134:135], v[118:119] op_sel_hi:[1,0]
	v_cvt_pk_fp8_f32 v119, v136, v139
	v_mul_f32_e32 v108, 0xbfb8aa3b, v135
	v_exp_f32_e32 v108, v108
	v_mov_b32_e32 v136, 0
	v_cvt_pk_fp8_f32 v136, v137, v138
	v_cvt_pk_fp8_f32 v119, v140, v141 op_sel:[0,0,1]
	v_add_f32_e32 v108, 1.0, v108
	v_rcp_f32_e32 v137, v108
	v_cvt_f32_i32_e32 v108, v105
	v_med3_f32 v104, v104, s83, v172
	v_cvt_pk_fp8_f32 v136, v115, v104 op_sel:[0,0,1]
	v_mul_f32_e32 v115, v135, v137
	v_pk_mul_f32 v[104:105], v[130:131], v[108:109]
	v_cvt_f32_i32_e32 v109, v110
	v_cvt_f32_i32_e32 v108, v106
	v_pk_mul_f32 v[104:105], v[104:105], v[118:119] op_sel_hi:[1,0]
	v_mul_f32_e32 v115, v134, v115
	v_mul_f32_e32 v106, 0xbfb8aa3b, v105
	v_exp_f32_e32 v106, v106
	v_pk_mul_f32 v[108:109], v[128:129], v[108:109]
	v_add_f32_e32 v106, 1.0, v106
	v_pk_mul_f32 v[108:109], v[108:109], v[118:119] op_sel_hi:[1,0]
	v_rcp_f32_e32 v106, v106
	v_mul_f32_e32 v110, 0xbfb8aa3b, v109
	v_exp_f32_e32 v110, v110
	v_mul_f32_e32 v105, v105, v106
	v_cvt_f32_i32_e32 v106, v96
	v_add_f32_e32 v110, 1.0, v110
	v_rcp_f32_e32 v134, v110
	v_cvt_f32_i32_e32 v110, v107
	v_cvt_f32_i32_e32 v107, v100
	v_mul_f32_e32 v135, v104, v105
	v_mul_f32_e32 v109, v109, v134
	v_pk_mul_f32 v[104:105], v[124:125], v[110:111]
	v_pk_mul_f32 v[106:107], v[122:123], v[106:107]
	v_pk_mul_f32 v[104:105], v[104:105], v[118:119] op_sel_hi:[1,0]
	v_pk_mul_f32 v[106:107], v[106:107], v[118:119] op_sel_hi:[1,0]
	v_mul_f32_e32 v96, 0xbfb8aa3b, v105
	v_exp_f32_e32 v96, v96
	v_mul_f32_e32 v100, 0xbfb8aa3b, v107
	v_exp_f32_e32 v100, v100
	v_mul_f32_e32 v108, v108, v109
	v_add_f32_e32 v96, 1.0, v96
	v_rcp_f32_e32 v96, v96
	v_add_f32_e32 v100, 1.0, v100
	v_rcp_f32_e32 v109, v100
	v_cvt_f32_i32_e32 v100, v97
	v_mul_f32_e32 v96, v105, v96
	v_mul_f32_e32 v104, v104, v96
	v_mul_f32_e32 v105, v107, v109
	v_pk_mul_f32 v[96:97], v[120:121], v[100:101]
	v_cvt_f32_i32_e32 v101, v102
	v_pk_mul_f32 v[96:97], v[96:97], v[118:119] op_sel_hi:[1,0]
	v_cvt_f32_i32_e32 v102, v99
	v_mul_f32_e32 v100, 0xbfb8aa3b, v97
	v_exp_f32_e32 v107, v100
	v_cvt_f32_i32_e32 v100, v98
	v_mul_f32_e32 v105, v106, v105
	v_add_f32_e32 v98, 1.0, v107
	v_pk_mul_f32 v[100:101], v[126:127], v[100:101]
	v_rcp_f32_e32 v106, v98
	v_pk_mul_f32 v[98:99], v[100:101], v[118:119] op_sel_hi:[1,0]
	v_mul_f32_e32 v97, v97, v106
	v_mul_f32_e32 v100, 0xbfb8aa3b, v99
	v_exp_f32_e32 v107, v100
	v_pk_mul_f32 v[100:101], v[116:117], v[102:103]
	v_mul_f32_e32 v96, v96, v97
	v_pk_mul_f32 v[100:101], v[100:101], v[118:119] op_sel_hi:[1,0]
	v_add_f32_e32 v103, 1.0, v107
	v_mul_f32_e32 v102, 0xbfb8aa3b, v101
	v_exp_f32_e32 v102, v102
	v_rcp_f32_e32 v103, v103
	v_mul_f32_e32 v96, 0x41000000, v96
	v_add_f32_e32 v102, 1.0, v102
	v_rcp_f32_e32 v102, v102
	v_mul_f32_e32 v97, v99, v103
	v_mul_f32_e32 v97, v98, v97
	v_mul_f32_e32 v99, 0x41000000, v115
	v_mul_f32_e32 v98, v101, v102
	v_med3_f32 v102, v96, s83, v172
	v_mul_f32_e32 v96, 0x41000000, v108
	v_med3_f32 v103, v96, s83, v172
	v_mul_f32_e32 v96, 0x41000000, v97
	v_mul_f32_e32 v98, v100, v98
	v_mul_f32_e32 v100, 0x41000000, v105
	v_med3_f32 v105, v96, s83, v172
	v_mul_f32_e32 v96, 0x41000000, v104
	v_med3_f32 v104, v96, s83, v172
	v_cvt_f32_i32_e32 v97, v92
	v_cvt_f32_i32_e32 v96, v88
	v_mul_f32_e32 v101, 0x41000000, v135
	v_med3_f32 v99, v99, s83, v172
	v_med3_f32 v101, v101, s83, v172
	v_pk_mul_f32 v[96:97], v[132:133], v[96:97]
	v_mul_f32_e32 v88, 0x41000000, v98
	v_pk_mul_f32 v[96:97], v[96:97], v[158:159] op_sel_hi:[1,0]
	v_mov_b32_e32 v98, 0
	v_mul_f32_e32 v92, 0xbfb8aa3b, v97
	v_exp_f32_e32 v92, v92
	v_med3_f32 v100, v100, s83, v172
	v_cvt_pk_fp8_f32 v98, v99, v101
	v_mov_b32_e32 v99, 0
	v_add_f32_e32 v92, 1.0, v92
	v_cvt_pk_fp8_f32 v99, v100, v102
	v_rcp_f32_e32 v100, v92
	v_cvt_f32_i32_e32 v92, v89
	v_med3_f32 v88, v88, s83, v172
	v_cvt_pk_fp8_f32 v99, v105, v88 op_sel:[0,0,1]
	v_mul_f32_e32 v97, v97, v100
	v_pk_mul_f32 v[88:89], v[130:131], v[92:93]
	v_cvt_f32_i32_e32 v93, v94
	v_cvt_f32_i32_e32 v92, v90
	v_pk_mul_f32 v[88:89], v[88:89], v[158:159] op_sel_hi:[1,0]
	v_mul_f32_e32 v96, v96, v97
	v_mul_f32_e32 v90, 0xbfb8aa3b, v89
	v_exp_f32_e32 v90, v90
	v_pk_mul_f32 v[92:93], v[128:129], v[92:93]
	v_cvt_pk_fp8_f32 v98, v103, v104 op_sel:[0,0,1]
	v_pk_mul_f32 v[92:93], v[92:93], v[158:159] op_sel_hi:[1,0]
	v_add_f32_e32 v90, 1.0, v90
	v_mul_f32_e32 v94, 0xbfb8aa3b, v93
	v_exp_f32_e32 v94, v94
	v_rcp_f32_e32 v90, v90
	v_add_f32_e32 v94, 1.0, v94
	v_rcp_f32_e32 v97, v94
	v_cvt_f32_i32_e32 v94, v91
	v_mul_f32_e32 v89, v89, v90
	v_cvt_f32_i32_e32 v91, v84
	v_cvt_f32_i32_e32 v90, v80
	v_mul_f32_e32 v100, v88, v89
	v_pk_mul_f32 v[88:89], v[124:125], v[94:95]
	v_mul_f32_e32 v93, v93, v97
	v_pk_mul_f32 v[88:89], v[88:89], v[158:159] op_sel_hi:[1,0]
; __device__ __forceinline__ unsigned cvt_pk_bf16(float lo, float hi) { unsigned r; asm volatile("v_cvt_pk_bf16_f32 %0, %1, %2" : "=v"(r) : "v"(lo), "v"(hi)); return r; }
;     __device__ __forceinline__ void operator()(const f32x4 (&acc)[2][2][4][2], const Unit& u, int wr, int wc, int fr, int fq) const {
;     ...
;                 if constexpr (OUT8) { typedef unsigned u32x2v __attribute__((ext_vector_type(2))); _Pragma("unroll") for (int e = 0; e < 4; ++e) { r[0][e] = __builtin_amdgcn_fmed3f(r[0][e] * ACT8SCALE, -448.f, 448.f); r[1][e] = __builtin_amdgcn_fmed3f(r[1][e] * ACT8SCALE, -448.f, 448.f); }
;                     int w0 = __builtin_amdgcn_cvt_pk_fp8_f32(r[0][0], r[0][1], 0, false); w0 = __builtin_amdgcn_cvt_pk_fp8_f32(r[0][2], r[0][3], w0, true);
;                     int w1 = __builtin_amdgcn_cvt_pk_fp8_f32(r[1][0], r[1][1], 0, false); w1 = __builtin_amdgcn_cvt_pk_fp8_f32(r[1][2], r[1][3], w1, true);
;                     pw[m][0] = (unsigned)w0; pw[m][1] = (unsigned)w1; (void)rowp; }
;                 else { u32x4 w; w.x = cvt_pk_bf16(r[0][0], r[0][1]); w.y = cvt_pk_bf16(r[0][2], r[0][3]); w.z = cvt_pk_bf16(r[1][0], r[1][1]); w.w = cvt_pk_bf16(r[1][2], r[1][3]);
;                     *(u32x4*)rowp = w; } }
;             if constexpr (OUT8) {
;                 const bool odd = (fq & 1) != 0;
; #pragma unroll
;                 for (int k2 = 0; k2 < 2; ++k2) { const unsigned a0 = pw[2 * k2][0], a1 = pw[2 * k2][1], b0 = pw[2 * k2 + 1][0], b1 = pw[2 * k2 + 1][1];
;                     const unsigned r0 = (unsigned)__builtin_amdgcn_ds_swizzle((int)(odd ? a0 : b0), 0x401F), r1 = (unsigned)__builtin_amdgcn_ds_swizzle((int)(odd ? a1 : b1), 0x401F);
;                     const u32x4 w = odd ? (u32x4){r0, r1, b0, b1} : (u32x4){a0, a1, r0, r1};
	v_pk_mul_f32 v[90:91], v[122:123], v[90:91]
	v_mul_f32_e32 v80, 0xbfb8aa3b, v89
	v_pk_mul_f32 v[90:91], v[90:91], v[158:159] op_sel_hi:[1,0]
	v_exp_f32_e32 v80, v80
	v_mul_f32_e32 v84, 0xbfb8aa3b, v91
	v_exp_f32_e32 v84, v84
	v_mul_f32_e32 v92, v92, v93
	v_add_f32_e32 v80, 1.0, v80
	v_rcp_f32_e32 v80, v80
	v_add_f32_e32 v84, 1.0, v84
	v_rcp_f32_e32 v93, v84
	v_cvt_f32_i32_e32 v84, v81
	v_mul_f32_e32 v80, v89, v80
	v_mul_f32_e32 v88, v88, v80
	v_mul_f32_e32 v89, v91, v93
	v_pk_mul_f32 v[80:81], v[120:121], v[84:85]
	v_cvt_f32_i32_e32 v85, v86
	v_pk_mul_f32 v[80:81], v[80:81], v[158:159] op_sel_hi:[1,0]
	v_cvt_f32_i32_e32 v86, v83
	v_mul_f32_e32 v84, 0xbfb8aa3b, v81
	v_exp_f32_e32 v91, v84
	v_cvt_f32_i32_e32 v84, v82
	v_mul_f32_e32 v89, v90, v89
	v_add_f32_e32 v82, 1.0, v91
	v_pk_mul_f32 v[84:85], v[126:127], v[84:85]
	v_rcp_f32_e32 v90, v82
	v_pk_mul_f32 v[82:83], v[84:85], v[158:159] op_sel_hi:[1,0]
	v_mul_f32_e32 v81, v81, v90
	v_mul_f32_e32 v84, 0xbfb8aa3b, v83
	v_exp_f32_e32 v91, v84
	v_pk_mul_f32 v[84:85], v[116:117], v[86:87]
	v_mul_f32_e32 v80, v80, v81
	v_pk_mul_f32 v[84:85], v[84:85], v[158:159] op_sel_hi:[1,0]
	v_add_f32_e32 v87, 1.0, v91
	v_mul_f32_e32 v86, 0xbfb8aa3b, v85
	v_exp_f32_e32 v86, v86
	v_rcp_f32_e32 v87, v87
	v_mul_f32_e32 v80, 0x41000000, v80
	v_add_f32_e32 v86, 1.0, v86
	v_rcp_f32_e32 v86, v86
	v_mul_f32_e32 v81, v83, v87
	v_mul_f32_e32 v81, v82, v81
	v_mul_f32_e32 v83, 0x41000000, v96
	v_mul_f32_e32 v82, v85, v86
	v_med3_f32 v86, v80, s83, v172
	v_mul_f32_e32 v80, 0x41000000, v92
	v_med3_f32 v87, v80, s83, v172
	v_mul_f32_e32 v80, 0x41000000, v81
	v_mul_f32_e32 v82, v84, v82
	v_mul_f32_e32 v84, 0x41000000, v89
	v_med3_f32 v89, v80, s83, v172
	v_mul_f32_e32 v80, 0x41000000, v88
	v_med3_f32 v88, v80, s83, v172
	v_cvt_f32_i32_e32 v81, v76
	v_cvt_f32_i32_e32 v80, v72
	v_mul_f32_e32 v85, 0x41000000, v100
	v_med3_f32 v83, v83, s83, v172
	v_med3_f32 v85, v85, s83, v172
	v_pk_mul_f32 v[80:81], v[132:133], v[80:81]
	v_mul_f32_e32 v72, 0x41000000, v82
	v_pk_mul_f32 v[80:81], v[80:81], v[114:115] op_sel_hi:[1,0]
	v_mov_b32_e32 v82, 0
	v_mul_f32_e32 v76, 0xbfb8aa3b, v81
	v_exp_f32_e32 v76, v76
	v_med3_f32 v84, v84, s83, v172
	v_cvt_pk_fp8_f32 v82, v83, v85
	v_mov_b32_e32 v83, 0
	v_add_f32_e32 v76, 1.0, v76
	v_cvt_pk_fp8_f32 v83, v84, v86
	v_rcp_f32_e32 v84, v76
	v_cvt_f32_i32_e32 v76, v73
	v_med3_f32 v72, v72, s83, v172
	v_cvt_pk_fp8_f32 v83, v89, v72 op_sel:[0,0,1]
	v_mul_f32_e32 v81, v81, v84
	v_pk_mul_f32 v[72:73], v[130:131], v[76:77]
	v_cvt_f32_i32_e32 v77, v78
	v_cvt_f32_i32_e32 v76, v74
	v_pk_mul_f32 v[72:73], v[72:73], v[114:115] op_sel_hi:[1,0]
	v_mul_f32_e32 v80, v80, v81
	v_mul_f32_e32 v74, 0xbfb8aa3b, v73
	v_exp_f32_e32 v74, v74
	v_pk_mul_f32 v[76:77], v[128:129], v[76:77]
	v_cvt_pk_fp8_f32 v82, v87, v88 op_sel:[0,0,1]
	v_pk_mul_f32 v[76:77], v[76:77], v[114:115] op_sel_hi:[1,0]
	v_add_f32_e32 v74, 1.0, v74
	v_mul_f32_e32 v78, 0xbfb8aa3b, v77
	v_exp_f32_e32 v78, v78
	v_rcp_f32_e32 v74, v74
	v_add_f32_e32 v78, 1.0, v78
	v_rcp_f32_e32 v81, v78
	v_cvt_f32_i32_e32 v78, v75
	v_mul_f32_e32 v73, v73, v74
	v_cvt_f32_i32_e32 v75, v68
	v_cvt_f32_i32_e32 v74, v64
	v_mul_f32_e32 v84, v72, v73
	v_pk_mul_f32 v[72:73], v[124:125], v[78:79]
	v_mul_f32_e32 v77, v77, v81
	v_pk_mul_f32 v[72:73], v[72:73], v[114:115] op_sel_hi:[1,0]
	v_pk_mul_f32 v[74:75], v[122:123], v[74:75]
	v_mul_f32_e32 v64, 0xbfb8aa3b, v73
	v_pk_mul_f32 v[74:75], v[74:75], v[114:115] op_sel_hi:[1,0]
	v_exp_f32_e32 v64, v64
	v_mul_f32_e32 v68, 0xbfb8aa3b, v75
	v_exp_f32_e32 v68, v68
	v_mul_f32_e32 v76, v76, v77
	v_add_f32_e32 v64, 1.0, v64
	v_rcp_f32_e32 v64, v64
	v_add_f32_e32 v68, 1.0, v68
	v_rcp_f32_e32 v77, v68
	v_cvt_f32_i32_e32 v68, v65
	v_mul_f32_e32 v64, v73, v64
	v_mul_f32_e32 v72, v72, v64
	v_mul_f32_e32 v73, v75, v77
	v_pk_mul_f32 v[64:65], v[120:121], v[68:69]
	v_cvt_f32_i32_e32 v69, v70
	v_pk_mul_f32 v[64:65], v[64:65], v[114:115] op_sel_hi:[1,0]
	v_cvt_f32_i32_e32 v70, v67
	v_mul_f32_e32 v68, 0xbfb8aa3b, v65
	v_exp_f32_e32 v75, v68
	v_cvt_f32_i32_e32 v68, v66
	v_mul_f32_e32 v73, v74, v73
	v_add_f32_e32 v66, 1.0, v75
	v_pk_mul_f32 v[68:69], v[126:127], v[68:69]
	v_rcp_f32_e32 v74, v66
	v_pk_mul_f32 v[66:67], v[68:69], v[114:115] op_sel_hi:[1,0]
	v_mul_f32_e32 v65, v65, v74
	v_mul_f32_e32 v68, 0xbfb8aa3b, v67
	v_exp_f32_e32 v75, v68
	v_pk_mul_f32 v[68:69], v[116:117], v[70:71]
	v_mul_f32_e32 v64, v64, v65
	v_pk_mul_f32 v[68:69], v[68:69], v[114:115] op_sel_hi:[1,0]
	v_add_f32_e32 v71, 1.0, v75
	v_mul_f32_e32 v70, 0xbfb8aa3b, v69
	v_exp_f32_e32 v70, v70
	v_rcp_f32_e32 v71, v71
	v_mul_f32_e32 v64, 0x41000000, v64
	v_med3_f32 v64, v64, s83, v172
	v_add_f32_e32 v70, 1.0, v70
	v_rcp_f32_e32 v70, v70
	v_mul_f32_e32 v65, v67, v71
	v_mul_f32_e32 v65, v66, v65
	v_mul_f32_e32 v67, 0x41000000, v80
	v_mul_f32_e32 v66, v69, v70
	v_mul_f32_e32 v69, 0x41000000, v84
	v_mul_f32_e32 v66, v68, v66
	v_med3_f32 v67, v67, s83, v172
	v_mul_f32_e32 v68, 0x41000000, v73
	v_med3_f32 v69, v69, s83, v172
	v_mul_f32_e32 v71, 0x41000000, v72
	v_mov_b32_e32 v72, 0
	v_med3_f32 v68, v68, s83, v172
	v_cvt_pk_fp8_f32 v72, v67, v69
	v_mov_b32_e32 v73, 0
	v_cvt_pk_fp8_f32 v73, v68, v64
	v_mul_f32_e32 v70, 0x41000000, v76
	v_med3_f32 v70, v70, s83, v172
	v_mul_f32_e32 v65, 0x41000000, v65
	v_med3_f32 v71, v71, s83, v172
	v_mul_f32_e32 v66, 0x41000000, v66
	v_med3_f32 v65, v65, s83, v172
	v_cndmask_b32_e32 v64, v119, v98, vcc
	v_med3_f32 v66, v66, s83, v172
	v_cvt_pk_fp8_f32 v72, v70, v71 op_sel:[0,0,1]
	ds_swizzle_b32 v64, v64 offset:swizzle(SWAP,16)
	v_cvt_pk_fp8_f32 v73, v65, v66 op_sel:[0,0,1]
	v_cndmask_b32_e32 v67, v136, v99, vcc
	ds_swizzle_b32 v67, v67 offset:swizzle(SWAP,16)
	v_cndmask_b32_e32 v70, v82, v72, vcc
	ds_swizzle_b32 v74, v70 offset:swizzle(SWAP,16)
	v_cndmask_b32_e32 v70, v83, v73, vcc
	s_waitcnt lgkmcnt(2)
;     __device__ __forceinline__ void operator()(const f32x4 (&acc)[2][2][4][2], const Unit& u, int wr, int wc, int fr, int fq) const {
;     ...
;                 for (int n = 0; n < 2; ++n) { const f32x4 g = acc[ai][0][m][n] * sg[n] * rs, up = acc[ai][1][m][n] * su[n] * rs;
; #pragma unroll
;                     for (int e = 0; e < 4; ++e) { const float sgm = __builtin_amdgcn_rcpf(1.0f + __builtin_amdgcn_exp2f(-1.4426950408889634f * g[e])); r[n][e] = g[e] * sgm * up[e]; } }
;                 if constexpr (OUT8) { typedef unsigned u32x2v __attribute__((ext_vector_type(2))); _Pragma("unroll") for (int e = 0; e < 4; ++e) { r[0][e] = __builtin_amdgcn_fmed3f(r[0][e] * ACT8SCALE, -448.f, 448.f); r[1][e] = __builtin_amdgcn_fmed3f(r[1][e] * ACT8SCALE, -448.f, 448.f); }
;                     int w0 = __builtin_amdgcn_cvt_pk_fp8_f32(r[0][0], r[0][1], 0, false); w0 = __builtin_amdgcn_cvt_pk_fp8_f32(r[0][2], r[0][3], w0, true);
;                     int w1 = __builtin_amdgcn_cvt_pk_fp8_f32(r[1][0], r[1][1], 0, false); w1 = __builtin_amdgcn_cvt_pk_fp8_f32(r[1][2], r[1][3], w1, true);
;                     pw[m][0] = (unsigned)w0; pw[m][1] = (unsigned)w1; (void)rowp; }
;     ...
;                 for (int k2 = 0; k2 < 2; ++k2) { const unsigned a0 = pw[2 * k2][0], a1 = pw[2 * k2][1], b0 = pw[2 * k2 + 1][0], b1 = pw[2 * k2 + 1][1];
;                     const unsigned r0 = (unsigned)__builtin_amdgcn_ds_swizzle((int)(odd ? a0 : b0), 0x401F), r1 = (unsigned)__builtin_amdgcn_ds_swizzle((int)(odd ? a1 : b1), 0x401F);
;                     const u32x4 w = odd ? (u32x4){r0, r1, b0, b1} : (u32x4){a0, a1, r0, r1};
;                     const int row = row0 + ai * HALF + (2 * k2 + (odd ? 1 : 0)) * 16;
;                     *(u32x4*)((unsigned char*)O + (size_t)row * ldc + (col0 - (odd ? 8 : 0))) = w; } } }
	v_cndmask_b32_e32 v68, v98, v64, vcc
	v_cndmask_b32_e32 v66, v64, v119, vcc
	v_mov_b64_e32 v[64:65], s[14:15]
	ds_swizzle_b32 v75, v70 offset:swizzle(SWAP,16)
	v_mad_i64_i32 v[70:71], s[64:65], v173, s84, v[64:65]
	s_waitcnt lgkmcnt(2)
	v_cndmask_b32_e32 v69, v99, v67, vcc
	v_cndmask_b32_e32 v67, v67, v136, vcc
	v_lshl_add_u64 v[70:71], v[70:71], 0, v[112:113]
	global_store_dwordx4 v[70:71], v[66:69], off
	v_or_b32_e32 v70, 32, v173
	v_mad_i64_i32 v[70:71], s[64:65], v70, s84, v[64:65]
	s_waitcnt lgkmcnt(0)
	v_cndmask_b32_e32 v69, v73, v75, vcc
	v_cndmask_b32_e32 v68, v72, v74, vcc
	v_cndmask_b32_e32 v67, v75, v83, vcc
	v_cndmask_b32_e32 v66, v74, v82, vcc
	v_lshl_add_u64 v[70:71], v[70:71], 0, v[112:113]
	global_store_dwordx4 v[70:71], v[66:69], off
	s_nop 1
	v_mov_b32_e32 v68, v242
	s_nop 0
	v_cvt_f32_i32_e32 v67, v62
	v_cvt_f32_i32_e32 v66, v58
	s_nop 1
	v_mov_b32_e32 v58, v243
	v_pk_mul_f32 v[66:67], v[126:127], v[66:67]
	v_pk_mul_f32 v[70:71], v[66:67], v[68:69] op_sel_hi:[1,0]
	s_nop 0
	v_mul_f32_e32 v62, 0xbfb8aa3b, v71
	v_exp_f32_e32 v66, v62
	v_cvt_f32_i32_e32 v62, v59
	v_add_f32_e32 v59, 1.0, v66
	v_pk_mul_f32 v[62:63], v[116:117], v[62:63]
	v_rcp_f32_e32 v59, v59
	v_pk_mul_f32 v[72:73], v[62:63], v[68:69] op_sel_hi:[1,0]
	v_mul_f32_e32 v59, v71, v59
	v_mul_f32_e32 v62, 0xbfb8aa3b, v73
	v_exp_f32_e32 v63, v62
	s_nop 1
	v_mov_b32_e32 v62, v240
	s_nop 1
	v_mov_b32_e32 v66, v241
	v_mul_f32_e32 v59, v70, v59
	v_cvt_f32_i32_e32 v71, v60
	v_cvt_f32_i32_e32 v70, v56
	v_add_f32_e32 v63, 1.0, v63
	v_rcp_f32_e32 v63, v63
	v_mul_f32_e32 v56, 0x41000000, v59
	v_pk_mul_f32 v[70:71], v[122:123], v[70:71]
	v_med3_f32 v59, v56, s83, v172
	v_pk_mul_f32 v[70:71], v[70:71], v[68:69] op_sel_hi:[1,0]
	v_mul_f32_e32 v56, v73, v63
	v_mul_f32_e32 v60, 0xbfb8aa3b, v71
	v_exp_f32_e32 v63, v60
	v_cvt_f32_i32_e32 v60, v57
	v_mul_f32_e32 v67, v72, v56
	v_add_f32_e32 v56, 1.0, v63
	v_rcp_f32_e32 v63, v56
	v_pk_mul_f32 v[56:57], v[120:121], v[60:61]
	v_mul_f32_e32 v61, 0x41000000, v67
	v_pk_mul_f32 v[56:57], v[56:57], v[68:69] op_sel_hi:[1,0]
	v_mul_f32_e32 v63, v71, v63
	v_mul_f32_e32 v60, 0xbfb8aa3b, v57
	v_exp_f32_e32 v60, v60
	v_mul_f32_e32 v63, v70, v63
	v_mul_f32_e32 v63, 0x41000000, v63
	v_med3_f32 v63, v63, s83, v172
	v_add_f32_e32 v60, 1.0, v60
	v_rcp_f32_e32 v60, v60
	v_med3_f32 v61, v61, s83, v172
	v_mul_f32_e32 v57, v57, v60
	v_mul_f32_e32 v60, v56, v57
	v_cvt_f32_i32_e32 v57, v54
	v_cvt_f32_i32_e32 v56, v50
	v_mul_f32_e32 v50, 0x41000000, v60
	v_med3_f32 v60, v50, s83, v172
	v_mov_b32_e32 v50, 0
	v_pk_mul_f32 v[56:57], v[128:129], v[56:57]
	v_cvt_pk_fp8_f32 v50, v63, v60
	v_pk_mul_f32 v[56:57], v[56:57], v[68:69] op_sel_hi:[1,0]
	v_cvt_pk_fp8_f32 v50, v59, v61 op_sel:[0,0,1]
	v_mul_f32_e32 v54, 0xbfb8aa3b, v57
	v_exp_f32_e32 v67, v54
	v_cvt_f32_i32_e32 v54, v51
	v_add_f32_e32 v51, 1.0, v67
	v_pk_mul_f32 v[54:55], v[124:125], v[54:55]
	v_rcp_f32_e32 v51, v51
	v_pk_mul_f32 v[54:55], v[54:55], v[68:69] op_sel_hi:[1,0]
	v_mul_f32_e32 v51, v57, v51
	v_mul_f32_e32 v60, 0xbfb8aa3b, v55
	v_exp_f32_e32 v60, v60
	v_mul_f32_e32 v51, v56, v51
	v_cvt_f32_i32_e32 v57, v52
	v_add_f32_e32 v56, 1.0, v60
	v_rcp_f32_e32 v59, v56
	v_cvt_f32_i32_e32 v56, v48
	v_mul_f32_e32 v48, 0x41000000, v51
	v_med3_f32 v51, v48, s83, v172
	v_mul_f32_e32 v48, v55, v59
	v_pk_mul_f32 v[56:57], v[132:133], v[56:57]
	v_mul_f32_e32 v54, v54, v48
	v_pk_mul_f32 v[56:57], v[56:57], v[68:69] op_sel_hi:[1,0]
	s_nop 0
	v_mul_f32_e32 v52, 0xbfb8aa3b, v57
	v_exp_f32_e32 v55, v52
	v_cvt_f32_i32_e32 v52, v49
	v_add_f32_e32 v48, 1.0, v55
	v_rcp_f32_e32 v55, v48
	v_pk_mul_f32 v[48:49], v[130:131], v[52:53]
	v_mul_f32_e32 v53, 0x41000000, v54
	v_pk_mul_f32 v[48:49], v[48:49], v[68:69] op_sel_hi:[1,0]
	v_mul_f32_e32 v54, v57, v55
	v_mul_f32_e32 v52, 0xbfb8aa3b, v49
	v_exp_f32_e32 v52, v52
	v_mul_f32_e32 v54, v56, v54
	v_mul_f32_e32 v54, 0x41000000, v54
	v_med3_f32 v54, v54, s83, v172
	v_add_f32_e32 v52, 1.0, v52
	v_rcp_f32_e32 v52, v52
	v_med3_f32 v53, v53, s83, v172
	v_mul_f32_e32 v49, v49, v52
	v_mul_f32_e32 v52, v48, v49
	v_cvt_f32_i32_e32 v49, v46
	v_cvt_f32_i32_e32 v48, v42
	v_mul_f32_e32 v42, 0x41000000, v52
	v_med3_f32 v42, v42, s83, v172
	v_mov_b32_e32 v52, 0
	v_pk_mul_f32 v[48:49], v[126:127], v[48:49]
	v_cvt_pk_fp8_f32 v52, v54, v42
	v_pk_mul_f32 v[48:49], v[48:49], v[66:67] op_sel_hi:[1,0]
	v_cvt_pk_fp8_f32 v52, v51, v53 op_sel:[0,0,1]
	v_mul_f32_e32 v46, 0xbfb8aa3b, v49
	v_exp_f32_e32 v55, v46
	v_cvt_f32_i32_e32 v46, v43
	v_add_f32_e32 v42, 1.0, v55
	v_rcp_f32_e32 v54, v42
	v_pk_mul_f32 v[42:43], v[116:117], v[46:47]
	v_mul_f32_e32 v47, v49, v54
	v_pk_mul_f32 v[42:43], v[42:43], v[66:67] op_sel_hi:[1,0]
	v_mul_f32_e32 v48, v48, v47
	v_mul_f32_e32 v46, 0xbfb8aa3b, v43
	v_exp_f32_e32 v46, v46
	v_cvt_f32_i32_e32 v47, v44
	v_cvt_f32_i32_e32 v44, v41
	v_add_f32_e32 v46, 1.0, v46
	v_rcp_f32_e32 v49, v46
	v_cvt_f32_i32_e32 v46, v40
	v_mul_f32_e32 v40, 0x41000000, v48
	v_med3_f32 v48, v40, s83, v172
	v_mul_f32_e32 v40, v43, v49
	v_pk_mul_f32 v[46:47], v[122:123], v[46:47]
	v_mul_f32_e32 v42, v42, v40
	v_pk_mul_f32 v[46:47], v[46:47], v[66:67] op_sel_hi:[1,0]
	v_mul_f32_e32 v42, 0x41000000, v42
	v_mul_f32_e32 v43, 0xbfb8aa3b, v47
	v_exp_f32_e32 v43, v43
	v_med3_f32 v42, v42, s83, v172
	v_add_f32_e32 v40, 1.0, v43
	v_rcp_f32_e32 v43, v40
	v_pk_mul_f32 v[40:41], v[120:121], v[44:45]
	v_mul_f32_e32 v43, v47, v43
	v_pk_mul_f32 v[40:41], v[40:41], v[66:67] op_sel_hi:[1,0]
	v_mul_f32_e32 v43, v46, v43
	v_mul_f32_e32 v44, 0xbfb8aa3b, v41
	v_exp_f32_e32 v44, v44
	v_mul_f32_e32 v43, 0x41000000, v43
	v_med3_f32 v43, v43, s83, v172
	v_add_f32_e32 v44, 1.0, v44
	v_rcp_f32_e32 v44, v44
	s_nop 0
;     __device__ __forceinline__ void operator()(const f32x4 (&acc)[2][2][4][2], const Unit& u, int wr, int wc, int fr, int fq) const {
;     ...
;                 for (int n = 0; n < 2; ++n) { const f32x4 g = acc[ai][0][m][n] * sg[n] * rs, up = acc[ai][1][m][n] * su[n] * rs;
; #pragma unroll
;                     for (int e = 0; e < 4; ++e) { const float sgm = __builtin_amdgcn_rcpf(1.0f + __builtin_amdgcn_exp2f(-1.4426950408889634f * g[e])); r[n][e] = g[e] * sgm * up[e]; } }
;                 if constexpr (OUT8) { typedef unsigned u32x2v __attribute__((ext_vector_type(2))); _Pragma("unroll") for (int e = 0; e < 4; ++e) { r[0][e] = __builtin_amdgcn_fmed3f(r[0][e] * ACT8SCALE, -448.f, 448.f); r[1][e] = __builtin_amdgcn_fmed3f(r[1][e] * ACT8SCALE, -448.f, 448.f); }
;                     int w0 = __builtin_amdgcn_cvt_pk_fp8_f32(r[0][0], r[0][1], 0, false); w0 = __builtin_amdgcn_cvt_pk_fp8_f32(r[0][2], r[0][3], w0, true);
;                     int w1 = __builtin_amdgcn_cvt_pk_fp8_f32(r[1][0], r[1][1], 0, false); w1 = __builtin_amdgcn_cvt_pk_fp8_f32(r[1][2], r[1][3], w1, true);
;                     pw[m][0] = (unsigned)w0; pw[m][1] = (unsigned)w1; (void)rowp; }
	v_mul_f32_e32 v41, v41, v44
	v_mul_f32_e32 v44, v40, v41
	v_cvt_f32_i32_e32 v41, v38
	v_cvt_f32_i32_e32 v40, v34
	v_mul_f32_e32 v34, 0x41000000, v44
	v_med3_f32 v34, v34, s83, v172
	v_mov_b32_e32 v44, 0
	v_pk_mul_f32 v[40:41], v[128:129], v[40:41]
	v_cvt_pk_fp8_f32 v44, v43, v34
	v_pk_mul_f32 v[40:41], v[40:41], v[66:67] op_sel_hi:[1,0]
	v_cvt_pk_fp8_f32 v44, v48, v42 op_sel:[0,0,1]
	v_mul_f32_e32 v38, 0xbfb8aa3b, v41
	v_exp_f32_e32 v45, v38
	v_cvt_f32_i32_e32 v38, v35
	v_add_f32_e32 v34, 1.0, v45
	v_rcp_f32_e32 v43, v34
	v_pk_mul_f32 v[34:35], v[124:125], v[38:39]
	v_mul_f32_e32 v39, v41, v43
	v_pk_mul_f32 v[34:35], v[34:35], v[66:67] op_sel_hi:[1,0]
	v_mul_f32_e32 v40, v40, v39
	v_mul_f32_e32 v38, 0xbfb8aa3b, v35
	v_exp_f32_e32 v38, v38
	v_cvt_f32_i32_e32 v39, v36
	v_cvt_f32_i32_e32 v36, v33
	v_add_f32_e32 v38, 1.0, v38
	v_rcp_f32_e32 v41, v38
	v_cvt_f32_i32_e32 v38, v32
	v_mul_f32_e32 v32, 0x41000000, v40
	v_med3_f32 v40, v32, s83, v172
	v_mul_f32_e32 v32, v35, v41
	v_pk_mul_f32 v[38:39], v[132:133], v[38:39]
	v_mul_f32_e32 v34, v34, v32
	v_pk_mul_f32 v[38:39], v[38:39], v[66:67] op_sel_hi:[1,0]
	v_mul_f32_e32 v34, 0x41000000, v34
	v_mul_f32_e32 v35, 0xbfb8aa3b, v39
	v_exp_f32_e32 v35, v35
	v_med3_f32 v34, v34, s83, v172
	v_add_f32_e32 v32, 1.0, v35
	v_rcp_f32_e32 v35, v32
	v_pk_mul_f32 v[32:33], v[130:131], v[36:37]
	v_mul_f32_e32 v35, v39, v35
	v_pk_mul_f32 v[32:33], v[32:33], v[66:67] op_sel_hi:[1,0]
	v_mul_f32_e32 v35, v38, v35
	v_mul_f32_e32 v36, 0xbfb8aa3b, v33
	v_exp_f32_e32 v36, v36
	v_mul_f32_e32 v35, 0x41000000, v35
	v_med3_f32 v35, v35, s83, v172
	v_add_f32_e32 v36, 1.0, v36
	v_rcp_f32_e32 v36, v36
	s_nop 0
	v_mul_f32_e32 v33, v33, v36
	v_mul_f32_e32 v36, v32, v33
	v_cvt_f32_i32_e32 v33, v30
	v_cvt_f32_i32_e32 v32, v26
	v_mul_f32_e32 v26, 0x41000000, v36
	v_med3_f32 v26, v26, s83, v172
	v_mov_b32_e32 v36, 0
	v_pk_mul_f32 v[32:33], v[126:127], v[32:33]
	v_cvt_pk_fp8_f32 v36, v35, v26
	v_pk_mul_f32 v[32:33], v[32:33], v[62:63] op_sel_hi:[1,0]
	v_cvt_pk_fp8_f32 v36, v40, v34 op_sel:[0,0,1]
	v_mul_f32_e32 v30, 0xbfb8aa3b, v33
	v_exp_f32_e32 v37, v30
	v_cvt_f32_i32_e32 v30, v27
	v_add_f32_e32 v26, 1.0, v37
	v_rcp_f32_e32 v35, v26
	v_pk_mul_f32 v[26:27], v[116:117], v[30:31]
	v_mul_f32_e32 v31, v33, v35
	v_pk_mul_f32 v[26:27], v[26:27], v[62:63] op_sel_hi:[1,0]
	v_mul_f32_e32 v32, v32, v31
	v_mul_f32_e32 v30, 0xbfb8aa3b, v27
	v_exp_f32_e32 v30, v30
	v_cvt_f32_i32_e32 v31, v28
	v_cvt_f32_i32_e32 v28, v25
	v_add_f32_e32 v30, 1.0, v30
	v_rcp_f32_e32 v33, v30
	v_cvt_f32_i32_e32 v30, v24
	v_mul_f32_e32 v24, 0x41000000, v32
	v_med3_f32 v32, v24, s83, v172
	v_mul_f32_e32 v24, v27, v33
	v_pk_mul_f32 v[30:31], v[122:123], v[30:31]
	v_mul_f32_e32 v26, v26, v24
	v_pk_mul_f32 v[30:31], v[30:31], v[62:63] op_sel_hi:[1,0]
	v_mul_f32_e32 v26, 0x41000000, v26
	v_mul_f32_e32 v27, 0xbfb8aa3b, v31
	v_exp_f32_e32 v27, v27
	v_med3_f32 v26, v26, s83, v172
	v_add_f32_e32 v24, 1.0, v27
	v_rcp_f32_e32 v27, v24
	v_pk_mul_f32 v[24:25], v[120:121], v[28:29]
	v_mul_f32_e32 v27, v31, v27
	v_pk_mul_f32 v[24:25], v[24:25], v[62:63] op_sel_hi:[1,0]
	v_mul_f32_e32 v27, v30, v27
	v_mul_f32_e32 v28, 0xbfb8aa3b, v25
	v_exp_f32_e32 v28, v28
	v_mul_f32_e32 v27, 0x41000000, v27
	v_med3_f32 v27, v27, s83, v172
	v_add_f32_e32 v28, 1.0, v28
	v_rcp_f32_e32 v28, v28
	s_nop 0
	v_mul_f32_e32 v25, v25, v28
	v_mul_f32_e32 v24, v24, v25
	v_mul_f32_e32 v28, 0x41000000, v24
	v_cvt_f32_i32_e32 v25, v22
	v_cvt_f32_i32_e32 v24, v18
	v_med3_f32 v18, v28, s83, v172
	v_mov_b32_e32 v28, 0
	v_cvt_pk_fp8_f32 v28, v27, v18
	v_pk_mul_f32 v[24:25], v[128:129], v[24:25]
	v_cvt_f32_i32_e32 v22, v19
	v_pk_mul_f32 v[24:25], v[24:25], v[62:63] op_sel_hi:[1,0]
	v_cvt_pk_fp8_f32 v28, v32, v26 op_sel:[0,0,1]
	v_mul_f32_e32 v18, 0xbfb8aa3b, v25
	v_exp_f32_e32 v18, v18
	s_nop 0
	v_add_f32_e32 v18, 1.0, v18
	v_rcp_f32_e32 v26, v18
	v_pk_mul_f32 v[18:19], v[124:125], v[22:23]
	v_mul_f32_e32 v23, v25, v26
	v_pk_mul_f32 v[18:19], v[18:19], v[62:63] op_sel_hi:[1,0]
	v_mul_f32_e32 v23, v24, v23
	v_mul_f32_e32 v22, 0xbfb8aa3b, v19
	v_exp_f32_e32 v22, v22
	v_mul_f32_e32 v24, 0x41000000, v23
	v_cvt_f32_i32_e32 v23, v20
	v_med3_f32 v24, v24, s83, v172
	v_add_f32_e32 v22, 1.0, v22
	v_rcp_f32_e32 v25, v22
	v_cvt_f32_i32_e32 v22, v16
	v_mul_f32_e32 v16, v19, v25
	v_mul_f32_e32 v16, v18, v16
	v_pk_mul_f32 v[18:19], v[132:133], v[22:23]
	v_mul_f32_e32 v23, 0x41000000, v16
	v_pk_mul_f32 v[18:19], v[18:19], v[62:63] op_sel_hi:[1,0]
	s_nop 0
	v_mul_f32_e32 v20, 0xbfb8aa3b, v19
	v_exp_f32_e32 v22, v20
	v_cvt_f32_i32_e32 v20, v17
	v_add_f32_e32 v16, 1.0, v22
	v_rcp_f32_e32 v22, v16
	v_pk_mul_f32 v[16:17], v[130:131], v[20:21]
	v_mul_f32_e32 v19, v19, v22
	v_pk_mul_f32 v[16:17], v[16:17], v[62:63] op_sel_hi:[1,0]
	v_mul_f32_e32 v18, v18, v19
; __device__ __forceinline__ unsigned cvt_pk_bf16(float lo, float hi) { unsigned r; asm volatile("v_cvt_pk_bf16_f32 %0, %1, %2" : "=v"(r) : "v"(lo), "v"(hi)); return r; }
;     __device__ __forceinline__ void operator()(const f32x4 (&acc)[2][2][4][2], const Unit& u, int wr, int wc, int fr, int fq) const {
;     ...
;                 for (int n = 0; n < 2; ++n) { const f32x4 g = acc[ai][0][m][n] * sg[n] * rs, up = acc[ai][1][m][n] * su[n] * rs;
; #pragma unroll
;                     for (int e = 0; e < 4; ++e) { const float sgm = __builtin_amdgcn_rcpf(1.0f + __builtin_amdgcn_exp2f(-1.4426950408889634f * g[e])); r[n][e] = g[e] * sgm * up[e]; } }
;                 if constexpr (OUT8) { typedef unsigned u32x2v __attribute__((ext_vector_type(2))); _Pragma("unroll") for (int e = 0; e < 4; ++e) { r[0][e] = __builtin_amdgcn_fmed3f(r[0][e] * ACT8SCALE, -448.f, 448.f); r[1][e] = __builtin_amdgcn_fmed3f(r[1][e] * ACT8SCALE, -448.f, 448.f); }
;                     int w0 = __builtin_amdgcn_cvt_pk_fp8_f32(r[0][0], r[0][1], 0, false); w0 = __builtin_amdgcn_cvt_pk_fp8_f32(r[0][2], r[0][3], w0, true);
;                     int w1 = __builtin_amdgcn_cvt_pk_fp8_f32(r[1][0], r[1][1], 0, false); w1 = __builtin_amdgcn_cvt_pk_fp8_f32(r[1][2], r[1][3], w1, true);
;                     pw[m][0] = (unsigned)w0; pw[m][1] = (unsigned)w1; (void)rowp; }
;                 else { u32x4 w; w.x = cvt_pk_bf16(r[0][0], r[0][1]); w.y = cvt_pk_bf16(r[0][2], r[0][3]); w.z = cvt_pk_bf16(r[1][0], r[1][1]); w.w = cvt_pk_bf16(r[1][2], r[1][3]);
;                     *(u32x4*)rowp = w; } }
;             if constexpr (OUT8) {
;                 const bool odd = (fq & 1) != 0;
; #pragma unroll
;                 for (int k2 = 0; k2 < 2; ++k2) { const unsigned a0 = pw[2 * k2][0], a1 = pw[2 * k2][1], b0 = pw[2 * k2 + 1][0], b1 = pw[2 * k2 + 1][1];
;                     const unsigned r0 = (unsigned)__builtin_amdgcn_ds_swizzle((int)(odd ? a0 : b0), 0x401F), r1 = (unsigned)__builtin_amdgcn_ds_swizzle((int)(odd ? a1 : b1), 0x401F);
;                     const u32x4 w = odd ? (u32x4){r0, r1, b0, b1} : (u32x4){a0, a1, r0, r1};
;                     const int row = row0 + ai * HALF + (2 * k2 + (odd ? 1 : 0)) * 16;
;                     *(u32x4*)((unsigned char*)O + (size_t)row * ldc + (col0 - (odd ? 8 : 0))) = w; } } }
	v_mul_f32_e32 v20, 0xbfb8aa3b, v17
	v_exp_f32_e32 v20, v20
	v_mul_f32_e32 v18, 0x41000000, v18
	v_med3_f32 v21, v18, s83, v172
	v_cvt_f32_i32_e32 v18, v8
	v_add_f32_e32 v19, 1.0, v20
	v_rcp_f32_e32 v20, v19
	v_cvt_f32_i32_e32 v19, v12
	v_mul_f32_e32 v8, v17, v20
	v_mul_f32_e32 v8, v16, v8
	v_pk_mul_f32 v[16:17], v[132:133], v[18:19]
	v_mul_f32_e32 v8, 0x41000000, v8
	v_pk_mul_f32 v[16:17], v[16:17], v[58:59] op_sel_hi:[1,0]
	v_med3_f32 v8, v8, s83, v172
	v_mul_f32_e32 v12, 0xbfb8aa3b, v17
	v_exp_f32_e32 v12, v12
	v_mov_b32_e32 v18, 0
	v_cvt_pk_fp8_f32 v18, v21, v8
	v_add_f32_e32 v8, 1.0, v12
	v_rcp_f32_e32 v8, v8
	v_cvt_f32_i32_e32 v12, v9
	v_med3_f32 v9, v23, s83, v172
	v_cvt_pk_fp8_f32 v18, v24, v9 op_sel:[0,0,1]
	v_mul_f32_e32 v17, v17, v8
	v_pk_mul_f32 v[8:9], v[130:131], v[12:13]
	v_cvt_f32_i32_e32 v13, v14
	v_cvt_f32_i32_e32 v12, v10
	v_pk_mul_f32 v[8:9], v[8:9], v[58:59] op_sel_hi:[1,0]
	v_mul_f32_e32 v16, v16, v17
	v_mul_f32_e32 v10, 0xbfb8aa3b, v9
	v_exp_f32_e32 v10, v10
	v_pk_mul_f32 v[12:13], v[128:129], v[12:13]
	v_add_f32_e32 v10, 1.0, v10
	v_pk_mul_f32 v[12:13], v[12:13], v[58:59] op_sel_hi:[1,0]
	v_rcp_f32_e32 v10, v10
	v_mul_f32_e32 v14, 0xbfb8aa3b, v13
	v_exp_f32_e32 v14, v14
	v_mul_f32_e32 v9, v9, v10
	v_cvt_f32_i32_e32 v10, v0
	v_add_f32_e32 v14, 1.0, v14
	v_rcp_f32_e32 v17, v14
	v_cvt_f32_i32_e32 v14, v11
	v_cvt_f32_i32_e32 v11, v4
	v_mul_f32_e32 v19, v8, v9
	v_mul_f32_e32 v13, v13, v17
	v_pk_mul_f32 v[8:9], v[124:125], v[14:15]
	v_pk_mul_f32 v[10:11], v[122:123], v[10:11]
	v_pk_mul_f32 v[8:9], v[8:9], v[58:59] op_sel_hi:[1,0]
	v_pk_mul_f32 v[10:11], v[10:11], v[58:59] op_sel_hi:[1,0]
	v_mul_f32_e32 v0, 0xbfb8aa3b, v9
	v_exp_f32_e32 v0, v0
	v_mul_f32_e32 v4, 0xbfb8aa3b, v11
	v_exp_f32_e32 v4, v4
	v_mul_f32_e32 v12, v12, v13
	v_add_f32_e32 v0, 1.0, v0
	v_rcp_f32_e32 v0, v0
	v_add_f32_e32 v4, 1.0, v4
	v_rcp_f32_e32 v13, v4
	v_cvt_f32_i32_e32 v4, v1
	v_mul_f32_e32 v0, v9, v0
	v_mul_f32_e32 v8, v8, v0
	v_mul_f32_e32 v9, v11, v13
	v_pk_mul_f32 v[0:1], v[120:121], v[4:5]
	v_cvt_f32_i32_e32 v5, v6
	v_pk_mul_f32 v[0:1], v[0:1], v[58:59] op_sel_hi:[1,0]
	v_cvt_f32_i32_e32 v6, v3
	v_mul_f32_e32 v4, 0xbfb8aa3b, v1
	v_exp_f32_e32 v11, v4
	v_cvt_f32_i32_e32 v4, v2
	v_mul_f32_e32 v9, v10, v9
	v_add_f32_e32 v2, 1.0, v11
	v_pk_mul_f32 v[4:5], v[126:127], v[4:5]
	v_rcp_f32_e32 v10, v2
	v_pk_mul_f32 v[2:3], v[4:5], v[58:59] op_sel_hi:[1,0]
	v_mul_f32_e32 v1, v1, v10
	v_mul_f32_e32 v4, 0xbfb8aa3b, v3
	v_exp_f32_e32 v11, v4
	v_pk_mul_f32 v[4:5], v[116:117], v[6:7]
	v_mul_f32_e32 v0, v0, v1
	v_pk_mul_f32 v[4:5], v[4:5], v[58:59] op_sel_hi:[1,0]
	v_add_f32_e32 v7, 1.0, v11
	v_mul_f32_e32 v6, 0xbfb8aa3b, v5
	v_exp_f32_e32 v6, v6
	v_rcp_f32_e32 v7, v7
	v_mul_f32_e32 v0, 0x41000000, v0
	v_med3_f32 v0, v0, s83, v172
	v_add_f32_e32 v6, 1.0, v6
	v_rcp_f32_e32 v6, v6
	v_mul_f32_e32 v1, v3, v7
	v_mul_f32_e32 v1, v2, v1
	v_mul_f32_e32 v3, 0x41000000, v16
	v_mul_f32_e32 v2, v5, v6
	v_mul_f32_e32 v5, 0x41000000, v19
	v_mul_f32_e32 v2, v4, v2
	v_med3_f32 v3, v3, s83, v172
	v_mul_f32_e32 v4, 0x41000000, v9
	v_med3_f32 v5, v5, s83, v172
	v_mul_f32_e32 v7, 0x41000000, v8
	v_mov_b32_e32 v8, 0
	v_med3_f32 v4, v4, s83, v172
	v_cvt_pk_fp8_f32 v8, v3, v5
	v_mov_b32_e32 v9, 0
	v_cvt_pk_fp8_f32 v9, v4, v0
	v_mul_f32_e32 v6, 0x41000000, v12
	v_cndmask_b32_e32 v3, v28, v44, vcc
	v_med3_f32 v6, v6, s83, v172
	v_mul_f32_e32 v1, 0x41000000, v1
	v_med3_f32 v7, v7, s83, v172
	v_mul_f32_e32 v2, 0x41000000, v2
	ds_swizzle_b32 v4, v3 offset:swizzle(SWAP,16)
	v_med3_f32 v1, v1, s83, v172
	v_med3_f32 v2, v2, s83, v172
	v_cvt_pk_fp8_f32 v8, v6, v7 op_sel:[0,0,1]
	v_cvt_pk_fp8_f32 v9, v1, v2 op_sel:[0,0,1]
	v_cndmask_b32_e32 v0, v18, v36, vcc
	ds_swizzle_b32 v0, v0 offset:swizzle(SWAP,16)
	s_waitcnt lgkmcnt(1)
	v_cndmask_b32_e32 v3, v44, v4, vcc
	v_cndmask_b32_e32 v1, v4, v28, vcc
	v_cndmask_b32_e32 v4, v52, v8, vcc
	ds_swizzle_b32 v6, v4 offset:swizzle(SWAP,16)
	v_cndmask_b32_e32 v4, v50, v9, vcc
	v_add_u32_e32 v5, 0x80, v173
	ds_swizzle_b32 v7, v4 offset:swizzle(SWAP,16)
	v_mad_i64_i32 v[4:5], s[64:65], v5, s84, v[64:65]
	s_waitcnt lgkmcnt(2)
	v_cndmask_b32_e32 v2, v36, v0, vcc
	v_cndmask_b32_e32 v0, v0, v18, vcc
	v_lshl_add_u64 v[4:5], v[4:5], 0, v[112:113]
	global_store_dwordx4 v[4:5], v[0:3], off
	v_add_u32_e32 v4, 0xa0, v173
	v_mad_i64_i32 v[4:5], s[64:65], v4, s84, v[64:65]
	s_waitcnt lgkmcnt(0)
	v_cndmask_b32_e32 v3, v9, v7, vcc
	v_cndmask_b32_e32 v2, v8, v6, vcc
	v_cndmask_b32_e32 v1, v7, v50, vcc
	v_cndmask_b32_e32 v0, v6, v52, vcc
	v_lshl_add_u64 v[4:5], v[4:5], 0, v[112:113]
	s_andn2_b64 vcc, exec, s[56:57]
	s_mov_b64 s[56:57], -1
	global_store_dwordx4 v[4:5], v[0:3], off
	s_cbranch_vccnz .LBB0_1386
	s_andn2_b64 vcc, exec, s[22:23]
	s_cbranch_vccnz .LBB0_1385
	s_barrier
	s_branch .LBB0_1385

; #define LAS __attribute__((address_space(3)))
; __global__ void __launch_bounds__(512) mk_fwd(Args args) {
;     extern __shared__ __attribute__((aligned(16))) unsigned char lds_raw[];
;     LAS unsigned char* lds = (LAS unsigned char*)lds_raw;
;     const int G = gridDim.x;
;     const int wv = __builtin_amdgcn_readfirstlane(threadIdx.x >> 6);
;     volatile LAS unsigned* bar_st = (volatile LAS unsigned*)(lds + (LDS_BYTES - 64));
;     if (threadIdx.x < 2) bar_st[threadIdx.x] = 0u;
;     __syncthreads();
	.amdhsa_kernel _Z6mk_fwd4Args
		.amdhsa_group_segment_fixed_size 0
		.amdhsa_private_segment_fixed_size 0
		.amdhsa_kernarg_size 464
		.amdhsa_user_sgpr_count 2
		.amdhsa_user_sgpr_dispatch_ptr 0
		.amdhsa_user_sgpr_queue_ptr 0
		.amdhsa_user_sgpr_kernarg_segment_ptr 1
		.amdhsa_user_sgpr_dispatch_id 0
		.amdhsa_user_sgpr_kernarg_preload_length 0
		.amdhsa_user_sgpr_kernarg_preload_offset 0
		.amdhsa_user_sgpr_private_segment_size 0
		.amdhsa_uses_dynamic_stack 0
		.amdhsa_enable_private_segment 0
		.amdhsa_system_sgpr_workgroup_id_x 1
		.amdhsa_system_sgpr_workgroup_id_y 0
		.amdhsa_system_sgpr_workgroup_id_z 0
		.amdhsa_system_sgpr_workgroup_info 0
		.amdhsa_system_vgpr_workitem_id 2
		.amdhsa_next_free_vgpr 256
		.amdhsa_next_free_sgpr 102
		.amdhsa_accum_offset 256
		.amdhsa_reserve_vcc 1
		.amdhsa_float_round_mode_32 0
		.amdhsa_float_round_mode_16_64 0
		.amdhsa_float_denorm_mode_32 3
		.amdhsa_float_denorm_mode_16_64 3
		.amdhsa_dx10_clamp 1
		.amdhsa_ieee_mode 1
		.amdhsa_fp16_overflow 0
		.amdhsa_tg_split 0
		.amdhsa_exception_fp_ieee_invalid_op 0
		.amdhsa_exception_fp_denorm_src 0
		.amdhsa_exception_fp_ieee_div_zero 0
		.amdhsa_exception_fp_ieee_overflow 0
		.amdhsa_exception_fp_ieee_underflow 0
		.amdhsa_exception_fp_ieee_inexact 0
		.amdhsa_exception_int_div_zero 0
	.end_amdhsa_kernel

;     pg8::Gemm g{A, Bt, M, N, K, lda, ldb}; pg8::StaticOrder S; S.init(M, N, (int)gridDim.x, (int)blockIdx.x);
;     if (base >= 0) { S.base = base; S.stride = stride; } S.cnt = cnt;
;     pg8::gemm_phase<Epi, pg8::StaticOrder, true, true, MODE, MID>(lds, g, S, E, wv);
; }
; __global__ void __launch_bounds__(512) mk_fwd(Args args) {
amdhsa.kernels:
  - .agpr_count:     0
    .args:
      - .offset:         0
        .size:           208
        .value_kind:     by_value
      - .offset:         208
        .size:           4
        .value_kind:     hidden_block_count_x
      - .offset:         212
        .size:           4
        .value_kind:     hidden_block_count_y
      - .offset:         216
        .size:           4
        .value_kind:     hidden_block_count_z
      - .offset:         220
        .size:           2
        .value_kind:     hidden_group_size_x
      - .offset:         222
        .size:           2
        .value_kind:     hidden_group_size_y
      - .offset:         224
        .size:           2
        .value_kind:     hidden_group_size_z
      - .offset:         226
        .size:           2
        .value_kind:     hidden_remainder_x
      - .offset:         228
        .size:           2
        .value_kind:     hidden_remainder_y
      - .offset:         230
        .size:           2
        .value_kind:     hidden_remainder_z
      - .offset:         248
        .size:           8
        .value_kind:     hidden_global_offset_x
      - .offset:         256
        .size:           8
        .value_kind:     hidden_global_offset_y
      - .offset:         264
        .size:           8
        .value_kind:     hidden_global_offset_z
      - .offset:         272
        .size:           2
        .value_kind:     hidden_grid_dims
      - .offset:         296
        .size:           8
        .value_kind:     hidden_multigrid_sync_arg
      - .offset:         328
        .size:           4
        .value_kind:     hidden_dynamic_lds_size
    .group_segment_fixed_size: 0
    .kernarg_segment_align: 8
    .kernarg_segment_size: 464
    .language:       OpenCL C
    .language_version:
      - 2
      - 0
    .max_flat_workgroup_size: 512
    .name:           _Z6mk_fwd4Args
    .private_segment_fixed_size: 0
    .sgpr_count:     108
    .sgpr_spill_count: 0
    .symbol:         _Z6mk_fwd4Args.kd
    .uniform_work_group_size: 1
    .uses_dynamic_stack: false
    .vgpr_count:     256
    .vgpr_spill_count: 0
    .wavefront_size: 64
